# stack1 plus LDS-DMA loads in saddr form (6 of 14 64-bit address VALU ops per K-loop iteration removed)
# speedup vs baseline: 1.0181x; 1.0087x over previous
.LBB0_137:
	ds_read_b128 v[146:149], v178
	ds_read_b128 v[150:153], v178 offset:1024
	ds_read_b128 v[154:157], v178 offset:2048
	ds_read_b128 v[158:161], v178 offset:3072
	ds_read_b128 v[182:185], v179
	ds_read_b128 v[186:189], v179 offset:1024
	ds_read_b128 v[190:193], v179 offset:2048
	ds_read_b128 v[194:197], v179 offset:3072
	s_add_u32 s30, s28, 0xfffc0080
	s_addc_u32 s31, s29, -1
	s_cmp_eq_u32 s72, 12
	s_cselect_b32 s35, s21, s31
	s_cselect_b32 s34, s68, s30
	s_cselect_b32 s31, s19, s71
	s_cselect_b32 s30, s69, s70
	s_add_i32 m0, s27, 0xc000
	ds_read_b128 v[198:201], v180
	ds_read_b128 v[202:205], v180 offset:1024
	ds_read_b128 v[206:209], v180 offset:2048
	ds_read_b128 v[210:213], v180 offset:3072
	ds_read_b128 v[214:217], v180 offset:4096
	ds_read_b128 v[218:221], v180 offset:5120
	ds_read_b128 v[222:225], v180 offset:6144
	ds_read_b128 v[226:229], v180 offset:7168
	global_load_lds_dwordx4 v138, s[28:29]
	s_add_i32 m0, s27, 0xe000
	s_nop 0
	global_load_lds_dwordx4 v140, s[28:29]
	s_waitcnt vmcnt(8)
	s_waitcnt lgkmcnt(0)
	s_barrier
	s_setprio 1
	v_mfma_i32_16x16x64_i8 v[126:129], v[146:149], v[198:201], v[126:129]
	v_mfma_i32_16x16x64_i8 v[118:121], v[154:157], v[198:201], v[118:121]
	v_mfma_i32_16x16x64_i8 v[110:113], v[146:149], v[206:209], v[110:113]
	v_mfma_i32_16x16x64_i8 v[102:105], v[154:157], v[206:209], v[102:105]
	v_mfma_i32_16x16x64_i8 v[94:97], v[146:149], v[214:217], v[94:97]
	v_mfma_i32_16x16x64_i8 v[86:89], v[154:157], v[214:217], v[86:89]
	v_mfma_i32_16x16x64_i8 v[78:81], v[146:149], v[222:225], v[78:81]
	v_mfma_i32_16x16x64_i8 v[70:73], v[154:157], v[222:225], v[70:73]
	v_mfma_i32_16x16x64_i8 v[126:129], v[150:153], v[202:205], v[126:129]
	v_mfma_i32_16x16x64_i8 v[118:121], v[158:161], v[202:205], v[118:121]
	v_mfma_i32_16x16x64_i8 v[110:113], v[150:153], v[210:213], v[110:113]
	v_mfma_i32_16x16x64_i8 v[102:105], v[158:161], v[210:213], v[102:105]
	v_mfma_i32_16x16x64_i8 v[94:97], v[150:153], v[218:221], v[94:97]
	v_mfma_i32_16x16x64_i8 v[86:89], v[158:161], v[218:221], v[86:89]
	v_mfma_i32_16x16x64_i8 v[78:81], v[150:153], v[226:229], v[78:81]
	v_mfma_i32_16x16x64_i8 v[70:73], v[158:161], v[226:229], v[70:73]
	v_mfma_i32_16x16x64_i8 v[122:125], v[182:185], v[198:201], v[122:125]
	v_mfma_i32_16x16x64_i8 v[114:117], v[190:193], v[198:201], v[114:117]
	v_mfma_i32_16x16x64_i8 v[106:109], v[182:185], v[206:209], v[106:109]
	v_mfma_i32_16x16x64_i8 v[98:101], v[190:193], v[206:209], v[98:101]
	v_mfma_i32_16x16x64_i8 v[90:93], v[182:185], v[214:217], v[90:93]
	v_mfma_i32_16x16x64_i8 v[82:85], v[190:193], v[214:217], v[82:85]
	v_mfma_i32_16x16x64_i8 v[74:77], v[182:185], v[222:225], v[74:77]
	v_mfma_i32_16x16x64_i8 v[66:69], v[190:193], v[222:225], v[66:69]
	v_mfma_i32_16x16x64_i8 v[122:125], v[186:189], v[202:205], v[122:125]
	v_mfma_i32_16x16x64_i8 v[114:117], v[194:197], v[202:205], v[114:117]
	v_mfma_i32_16x16x64_i8 v[106:109], v[186:189], v[210:213], v[106:109]
	v_mfma_i32_16x16x64_i8 v[98:101], v[194:197], v[210:213], v[98:101]
	v_mfma_i32_16x16x64_i8 v[90:93], v[186:189], v[218:221], v[90:93]
	v_mfma_i32_16x16x64_i8 v[82:85], v[194:197], v[218:221], v[82:85]
	v_mfma_i32_16x16x64_i8 v[74:77], v[186:189], v[226:229], v[74:77]
	v_mfma_i32_16x16x64_i8 v[66:69], v[194:197], v[226:229], v[66:69]
	s_setprio 0
	s_barrier
	s_add_i32 s73, s46, s38
	v_lshl_add_u64 v[162:163], s[30:31], 0, v[134:135]
	s_mov_b32 m0, s73
	ds_read_b128 v[198:201], v180 offset:16384
	ds_read_b128 v[202:205], v180 offset:17408
	ds_read_b128 v[206:209], v180 offset:18432
	ds_read_b128 v[210:213], v180 offset:19456
	ds_read_b128 v[214:217], v180 offset:20480
	ds_read_b128 v[218:221], v180 offset:21504
	ds_read_b128 v[222:225], v180 offset:22528
	ds_read_b128 v[226:229], v180 offset:23552
	global_load_lds_dwordx4 v134, s[30:31]
	s_add_i32 m0, s73, 0x2000
	s_add_u32 s74, s30, 0x40000
	v_lshl_add_u64 v[230:231], s[30:31], 0, v[130:131]
	s_addc_u32 s75, s31, 0
	s_add_i32 s73, s47, s38
	global_load_lds_dwordx4 v130, s[30:31]
	s_mov_b32 m0, s73
	v_lshl_add_u64 v[234:235], s[34:35], 0, v[132:133]
	global_load_lds_dwordx4 v134, s[74:75]
	s_add_i32 m0, s73, 0x2000
	s_nop 0
	global_load_lds_dwordx4 v130, s[74:75]
	v_lshl_add_u64 v[232:233], s[34:35], 0, v[136:137]
	s_mov_b32 m0, s27
	s_nop 0
	global_load_lds_dwordx4 v136, s[34:35]
	s_mov_b32 m0, s40
	s_nop 0
	global_load_lds_dwordx4 v132, s[34:35]
	s_waitcnt vmcnt(8)
	s_waitcnt lgkmcnt(0)
	s_barrier
	s_setprio 1
	v_mfma_i32_16x16x64_i8 v[62:65], v[146:149], v[198:201], v[62:65]
	v_mfma_i32_16x16x64_i8 v[54:57], v[154:157], v[198:201], v[54:57]
	v_mfma_i32_16x16x64_i8 v[46:49], v[146:149], v[206:209], v[46:49]
	v_mfma_i32_16x16x64_i8 v[38:41], v[154:157], v[206:209], v[38:41]
	v_mfma_i32_16x16x64_i8 v[30:33], v[146:149], v[214:217], v[30:33]
	v_mfma_i32_16x16x64_i8 v[22:25], v[154:157], v[214:217], v[22:25]
	v_mfma_i32_16x16x64_i8 v[14:17], v[146:149], v[222:225], v[14:17]
	v_mfma_i32_16x16x64_i8 v[6:9], v[154:157], v[222:225], v[6:9]
	v_mfma_i32_16x16x64_i8 v[62:65], v[150:153], v[202:205], v[62:65]
	v_mfma_i32_16x16x64_i8 v[54:57], v[158:161], v[202:205], v[54:57]
	v_mfma_i32_16x16x64_i8 v[46:49], v[150:153], v[210:213], v[46:49]
	v_mfma_i32_16x16x64_i8 v[38:41], v[158:161], v[210:213], v[38:41]
	v_mfma_i32_16x16x64_i8 v[30:33], v[150:153], v[218:221], v[30:33]
	v_mfma_i32_16x16x64_i8 v[22:25], v[158:161], v[218:221], v[22:25]
	v_mfma_i32_16x16x64_i8 v[14:17], v[150:153], v[226:229], v[14:17]
	v_mfma_i32_16x16x64_i8 v[6:9], v[158:161], v[226:229], v[6:9]
	v_mfma_i32_16x16x64_i8 v[58:61], v[182:185], v[198:201], v[58:61]
	v_mfma_i32_16x16x64_i8 v[50:53], v[190:193], v[198:201], v[50:53]
	v_mfma_i32_16x16x64_i8 v[42:45], v[182:185], v[206:209], v[42:45]
	v_mfma_i32_16x16x64_i8 v[34:37], v[190:193], v[206:209], v[34:37]
	v_mfma_i32_16x16x64_i8 v[26:29], v[182:185], v[214:217], v[26:29]
	v_mfma_i32_16x16x64_i8 v[18:21], v[190:193], v[214:217], v[18:21]
	v_mfma_i32_16x16x64_i8 v[10:13], v[182:185], v[222:225], v[10:13]
	v_mfma_i32_16x16x64_i8 v[2:5], v[190:193], v[222:225], v[2:5]
	v_mfma_i32_16x16x64_i8 v[58:61], v[186:189], v[202:205], v[58:61]
	v_mfma_i32_16x16x64_i8 v[50:53], v[194:197], v[202:205], v[50:53]
	v_mfma_i32_16x16x64_i8 v[42:45], v[186:189], v[210:213], v[42:45]
	v_mfma_i32_16x16x64_i8 v[34:37], v[194:197], v[210:213], v[34:37]
	v_mfma_i32_16x16x64_i8 v[26:29], v[186:189], v[218:221], v[26:29]
	v_mfma_i32_16x16x64_i8 v[18:21], v[194:197], v[218:221], v[18:21]
	v_mfma_i32_16x16x64_i8 v[10:13], v[186:189], v[226:229], v[10:13]
	v_mfma_i32_16x16x64_i8 v[2:5], v[194:197], v[226:229], v[2:5]
	s_setprio 0
	s_barrier
	s_add_i32 s73, 0, 0x18000
	v_add_u32_e32 v158, s73, v169
	ds_read_b128 v[146:149], v158
	ds_read_b128 v[150:153], v158 offset:1024
	ds_read_b128 v[154:157], v158 offset:2048
	ds_read_b128 v[158:161], v158 offset:3072
	ds_read_b128 v[182:185], v181
	ds_read_b128 v[186:189], v181 offset:1024
	ds_read_b128 v[190:193], v181 offset:2048
	ds_read_b128 v[194:197], v181 offset:3072
	s_add_u32 s34, s34, 0x40000
	s_addc_u32 s35, s35, 0
	s_mov_b32 m0, s41
	ds_read_b128 v[198:201], v180 offset:32768
	ds_read_b128 v[202:205], v180 offset:33792
	ds_read_b128 v[206:209], v180 offset:34816
	ds_read_b128 v[210:213], v180 offset:35840
	ds_read_b128 v[214:217], v180 offset:36864
	ds_read_b128 v[218:221], v180 offset:37888
	ds_read_b128 v[222:225], v180 offset:38912
	ds_read_b128 v[226:229], v180 offset:39936
	global_load_lds_dwordx4 v136, s[34:35]
	s_mov_b32 m0, s42
	s_nop 0
	global_load_lds_dwordx4 v132, s[34:35]
	s_waitcnt vmcnt(8)
	s_waitcnt lgkmcnt(0)
	s_barrier
	s_setprio 1
	v_mfma_i32_16x16x64_i8 v[126:129], v[146:149], v[198:201], v[126:129]
	v_mfma_i32_16x16x64_i8 v[118:121], v[154:157], v[198:201], v[118:121]
	v_mfma_i32_16x16x64_i8 v[110:113], v[146:149], v[206:209], v[110:113]
	v_mfma_i32_16x16x64_i8 v[102:105], v[154:157], v[206:209], v[102:105]
	v_mfma_i32_16x16x64_i8 v[94:97], v[146:149], v[214:217], v[94:97]
	v_mfma_i32_16x16x64_i8 v[86:89], v[154:157], v[214:217], v[86:89]
	v_mfma_i32_16x16x64_i8 v[78:81], v[146:149], v[222:225], v[78:81]
	v_mfma_i32_16x16x64_i8 v[70:73], v[154:157], v[222:225], v[70:73]
	v_mfma_i32_16x16x64_i8 v[126:129], v[150:153], v[202:205], v[126:129]
	v_mfma_i32_16x16x64_i8 v[118:121], v[158:161], v[202:205], v[118:121]
	v_mfma_i32_16x16x64_i8 v[110:113], v[150:153], v[210:213], v[110:113]
	v_mfma_i32_16x16x64_i8 v[102:105], v[158:161], v[210:213], v[102:105]
	v_mfma_i32_16x16x64_i8 v[94:97], v[150:153], v[218:221], v[94:97]
	v_mfma_i32_16x16x64_i8 v[86:89], v[158:161], v[218:221], v[86:89]
	v_mfma_i32_16x16x64_i8 v[78:81], v[150:153], v[226:229], v[78:81]
	v_mfma_i32_16x16x64_i8 v[70:73], v[158:161], v[226:229], v[70:73]
	v_mfma_i32_16x16x64_i8 v[122:125], v[182:185], v[198:201], v[122:125]
	v_mfma_i32_16x16x64_i8 v[114:117], v[190:193], v[198:201], v[114:117]
	v_mfma_i32_16x16x64_i8 v[106:109], v[182:185], v[206:209], v[106:109]
	v_mfma_i32_16x16x64_i8 v[98:101], v[190:193], v[206:209], v[98:101]
	v_mfma_i32_16x16x64_i8 v[90:93], v[182:185], v[214:217], v[90:93]
	v_mfma_i32_16x16x64_i8 v[82:85], v[190:193], v[214:217], v[82:85]
	v_mfma_i32_16x16x64_i8 v[74:77], v[182:185], v[222:225], v[74:77]
	v_mfma_i32_16x16x64_i8 v[66:69], v[190:193], v[222:225], v[66:69]
	v_mfma_i32_16x16x64_i8 v[122:125], v[186:189], v[202:205], v[122:125]
	v_mfma_i32_16x16x64_i8 v[114:117], v[194:197], v[202:205], v[114:117]
	v_mfma_i32_16x16x64_i8 v[106:109], v[186:189], v[210:213], v[106:109]
	v_mfma_i32_16x16x64_i8 v[98:101], v[194:197], v[210:213], v[98:101]
	v_mfma_i32_16x16x64_i8 v[90:93], v[186:189], v[218:221], v[90:93]
	v_mfma_i32_16x16x64_i8 v[82:85], v[194:197], v[218:221], v[82:85]
	v_mfma_i32_16x16x64_i8 v[74:77], v[186:189], v[226:229], v[74:77]
	v_mfma_i32_16x16x64_i8 v[66:69], v[194:197], v[226:229], v[66:69]
	s_setprio 0
	s_barrier
	s_add_i32 s34, s73, s38
	v_lshl_add_u64 v[162:163], v[162:163], 0, s[10:11]
	s_mov_b32 m0, s34
	ds_read_b128 v[198:201], v180 offset:49152
	ds_read_b128 v[202:205], v180 offset:50176
	ds_read_b128 v[206:209], v180 offset:51200
	ds_read_b128 v[210:213], v180 offset:52224
	ds_read_b128 v[214:217], v180 offset:53248
	ds_read_b128 v[218:221], v180 offset:54272
	ds_read_b128 v[222:225], v180 offset:55296
	ds_read_b128 v[226:229], v180 offset:56320
	global_load_lds_dwordx4 v[162:163], off
	s_add_i32 m0, s34, 0x2000
	s_add_u32 s30, s30, 0x40080
	v_lshl_add_u64 v[162:163], v[230:231], 0, s[10:11]
	s_addc_u32 s31, s31, 0
	s_add_i32 s34, s63, s38
	global_load_lds_dwordx4 v[162:163], off
	s_mov_b32 m0, s34
	s_nop 0
	global_load_lds_dwordx4 v134, s[30:31]
	s_add_i32 m0, s34, 0x2000
	s_nop 0
	global_load_lds_dwordx4 v130, s[30:31]
	v_lshl_add_u64 v[162:163], v[232:233], 0, s[10:11]
	s_mov_b32 m0, s43
	s_nop 0
	global_load_lds_dwordx4 v[162:163], off
	v_lshl_add_u64 v[162:163], v[234:235], 0, s[10:11]
	s_mov_b32 m0, s44
	s_nop 0
	global_load_lds_dwordx4 v[162:163], off
	s_waitcnt vmcnt(8)
	s_waitcnt lgkmcnt(0)
	s_barrier
	s_setprio 1
	v_mfma_i32_16x16x64_i8 v[62:65], v[146:149], v[198:201], v[62:65]
	v_mfma_i32_16x16x64_i8 v[54:57], v[154:157], v[198:201], v[54:57]
	v_mfma_i32_16x16x64_i8 v[46:49], v[146:149], v[206:209], v[46:49]
	v_mfma_i32_16x16x64_i8 v[38:41], v[154:157], v[206:209], v[38:41]
	v_mfma_i32_16x16x64_i8 v[30:33], v[146:149], v[214:217], v[30:33]
	v_mfma_i32_16x16x64_i8 v[22:25], v[154:157], v[214:217], v[22:25]
	v_mfma_i32_16x16x64_i8 v[14:17], v[146:149], v[222:225], v[14:17]
	v_mfma_i32_16x16x64_i8 v[6:9], v[154:157], v[222:225], v[6:9]
	v_mfma_i32_16x16x64_i8 v[62:65], v[150:153], v[202:205], v[62:65]
	v_mfma_i32_16x16x64_i8 v[54:57], v[158:161], v[202:205], v[54:57]
	v_mfma_i32_16x16x64_i8 v[46:49], v[150:153], v[210:213], v[46:49]
	v_mfma_i32_16x16x64_i8 v[38:41], v[158:161], v[210:213], v[38:41]
	v_mfma_i32_16x16x64_i8 v[30:33], v[150:153], v[218:221], v[30:33]
	v_mfma_i32_16x16x64_i8 v[22:25], v[158:161], v[218:221], v[22:25]
	v_mfma_i32_16x16x64_i8 v[14:17], v[150:153], v[226:229], v[14:17]
	v_mfma_i32_16x16x64_i8 v[6:9], v[158:161], v[226:229], v[6:9]
	v_mfma_i32_16x16x64_i8 v[58:61], v[182:185], v[198:201], v[58:61]
	v_mfma_i32_16x16x64_i8 v[50:53], v[190:193], v[198:201], v[50:53]
	v_mfma_i32_16x16x64_i8 v[42:45], v[182:185], v[206:209], v[42:45]
	v_mfma_i32_16x16x64_i8 v[34:37], v[190:193], v[206:209], v[34:37]
	v_mfma_i32_16x16x64_i8 v[26:29], v[182:185], v[214:217], v[26:29]
	v_mfma_i32_16x16x64_i8 v[18:21], v[190:193], v[214:217], v[18:21]
	v_mfma_i32_16x16x64_i8 v[10:13], v[182:185], v[222:225], v[10:13]
	v_mfma_i32_16x16x64_i8 v[2:5], v[190:193], v[222:225], v[2:5]
	v_mfma_i32_16x16x64_i8 v[58:61], v[186:189], v[202:205], v[58:61]
	v_mfma_i32_16x16x64_i8 v[50:53], v[194:197], v[202:205], v[50:53]
	v_mfma_i32_16x16x64_i8 v[42:45], v[186:189], v[210:213], v[42:45]
	v_mfma_i32_16x16x64_i8 v[34:37], v[194:197], v[210:213], v[34:37]
	v_mfma_i32_16x16x64_i8 v[26:29], v[186:189], v[218:221], v[26:29]
	v_mfma_i32_16x16x64_i8 v[18:21], v[194:197], v[218:221], v[18:21]
	v_mfma_i32_16x16x64_i8 v[10:13], v[186:189], v[226:229], v[10:13]
	v_mfma_i32_16x16x64_i8 v[2:5], v[194:197], v[226:229], v[2:5]
	s_setprio 0
	s_barrier
	s_add_i32 s72, s72, 2
	s_add_u32 s28, s28, 0x100
	s_addc_u32 s29, s29, 0
	s_add_u32 s70, s70, 0x100
	s_addc_u32 s71, s71, 0
	s_cmp_gt_u32 s72, 13
	s_cbranch_scc0 .LBB0_137
	s_and_b64 vcc, exec, s[14:15]
	s_cbranch_vccz .LBB0_140
	s_barrier

.LBB0_246:
	ds_read_b128 v[154:157], v149
	ds_read_b128 v[158:161], v149 offset:1024
	ds_read_b128 v[162:165], v149 offset:2048
	ds_read_b128 v[170:173], v149 offset:3072
	ds_read_b128 v[174:177], v150
	ds_read_b128 v[178:181], v150 offset:1024
	ds_read_b128 v[182:185], v150 offset:2048
	ds_read_b128 v[186:189], v150 offset:3072
	s_add_u32 s20, s18, 0xffea0080
	s_addc_u32 s21, s19, -1
	s_cmpk_eq_i32 s46, 0x54
	s_cselect_b32 s23, s7, s21
	s_cselect_b32 s22, s6, s20
	s_cselect_b32 s21, s17, s45
	s_cselect_b32 s20, s16, s44
	s_add_i32 m0, s26, 0xc000
	ds_read_b128 v[190:193], v151
	ds_read_b128 v[194:197], v151 offset:1024
	ds_read_b128 v[198:201], v151 offset:2048
	ds_read_b128 v[202:205], v151 offset:3072
	ds_read_b128 v[206:209], v151 offset:4096
	ds_read_b128 v[210:213], v151 offset:5120
	ds_read_b128 v[214:217], v151 offset:6144
	ds_read_b128 v[218:221], v151 offset:7168
	global_load_lds_dwordx4 v138, s[18:19]
	s_add_i32 m0, s26, 0xe000
	s_nop 0
	global_load_lds_dwordx4 v140, s[18:19]
	s_waitcnt vmcnt(8)
	s_waitcnt lgkmcnt(0)
	s_barrier
	s_setprio 1
	v_mfma_f32_16x16x32_bf16 v[126:129], v[154:157], v[190:193], v[126:129]
	v_mfma_f32_16x16x32_bf16 v[122:125], v[162:165], v[190:193], v[122:125]
	v_mfma_f32_16x16x32_bf16 v[118:121], v[154:157], v[198:201], v[118:121]
	v_mfma_f32_16x16x32_bf16 v[110:113], v[162:165], v[198:201], v[110:113]
	v_mfma_f32_16x16x32_bf16 v[102:105], v[154:157], v[206:209], v[102:105]
	v_mfma_f32_16x16x32_bf16 v[94:97], v[162:165], v[206:209], v[94:97]
	v_mfma_f32_16x16x32_bf16 v[86:89], v[154:157], v[214:217], v[86:89]
	v_mfma_f32_16x16x32_bf16 v[78:81], v[162:165], v[214:217], v[78:81]
	v_mfma_f32_16x16x32_bf16 v[126:129], v[158:161], v[194:197], v[126:129]
	v_mfma_f32_16x16x32_bf16 v[122:125], v[170:173], v[194:197], v[122:125]
	v_mfma_f32_16x16x32_bf16 v[118:121], v[158:161], v[202:205], v[118:121]
	v_mfma_f32_16x16x32_bf16 v[110:113], v[170:173], v[202:205], v[110:113]
	v_mfma_f32_16x16x32_bf16 v[102:105], v[158:161], v[210:213], v[102:105]
	v_mfma_f32_16x16x32_bf16 v[94:97], v[170:173], v[210:213], v[94:97]
	v_mfma_f32_16x16x32_bf16 v[86:89], v[158:161], v[218:221], v[86:89]
	v_mfma_f32_16x16x32_bf16 v[78:81], v[170:173], v[218:221], v[78:81]
	v_mfma_f32_16x16x32_bf16 v[114:117], v[174:177], v[190:193], v[114:117]
	v_mfma_f32_16x16x32_bf16 v[106:109], v[182:185], v[190:193], v[106:109]
	v_mfma_f32_16x16x32_bf16 v[98:101], v[174:177], v[198:201], v[98:101]
	v_mfma_f32_16x16x32_bf16 v[90:93], v[182:185], v[198:201], v[90:93]
	v_mfma_f32_16x16x32_bf16 v[82:85], v[174:177], v[206:209], v[82:85]
	v_mfma_f32_16x16x32_bf16 v[74:77], v[182:185], v[206:209], v[74:77]
	v_mfma_f32_16x16x32_bf16 v[70:73], v[174:177], v[214:217], v[70:73]
	v_mfma_f32_16x16x32_bf16 v[66:69], v[182:185], v[214:217], v[66:69]
	v_mfma_f32_16x16x32_bf16 v[114:117], v[178:181], v[194:197], v[114:117]
	v_mfma_f32_16x16x32_bf16 v[106:109], v[186:189], v[194:197], v[106:109]
	v_mfma_f32_16x16x32_bf16 v[98:101], v[178:181], v[202:205], v[98:101]
	v_mfma_f32_16x16x32_bf16 v[90:93], v[186:189], v[202:205], v[90:93]
	v_mfma_f32_16x16x32_bf16 v[82:85], v[178:181], v[210:213], v[82:85]
	v_mfma_f32_16x16x32_bf16 v[74:77], v[186:189], v[210:213], v[74:77]
	v_mfma_f32_16x16x32_bf16 v[70:73], v[178:181], v[218:221], v[70:73]
	v_mfma_f32_16x16x32_bf16 v[66:69], v[186:189], v[218:221], v[66:69]
	s_setprio 0
	s_barrier
	s_add_i32 s47, s36, s25
	v_lshl_add_u64 v[146:147], s[20:21], 0, v[132:133]
	s_mov_b32 m0, s47
	ds_read_b128 v[190:193], v151 offset:16384
	ds_read_b128 v[194:197], v151 offset:17408
	ds_read_b128 v[198:201], v151 offset:18432
	ds_read_b128 v[202:205], v151 offset:19456
	ds_read_b128 v[206:209], v151 offset:20480
	ds_read_b128 v[210:213], v151 offset:21504
	ds_read_b128 v[214:217], v151 offset:22528
	ds_read_b128 v[218:221], v151 offset:23552
	global_load_lds_dwordx4 v132, s[20:21]
	s_add_i32 m0, s47, 0x2000
	s_add_u32 s66, s20, 0x160000
	v_lshl_add_u64 v[222:223], s[20:21], 0, v[136:137]
	s_addc_u32 s67, s21, 0
	s_add_i32 s47, s37, s25
	global_load_lds_dwordx4 v136, s[20:21]
	s_mov_b32 m0, s47
	v_lshl_add_u64 v[226:227], s[22:23], 0, v[134:135]
	global_load_lds_dwordx4 v132, s[66:67]
	s_add_i32 m0, s47, 0x2000
	s_nop 0
	global_load_lds_dwordx4 v136, s[66:67]
	v_lshl_add_u64 v[224:225], s[22:23], 0, v[130:131]
	s_mov_b32 m0, s26
	s_nop 0
	global_load_lds_dwordx4 v130, s[22:23]
	s_mov_b32 m0, s27
	s_nop 0
	global_load_lds_dwordx4 v134, s[22:23]
	s_waitcnt vmcnt(8)
	s_waitcnt lgkmcnt(0)
	s_barrier
	s_setprio 1
	v_mfma_f32_16x16x32_bf16 v[62:65], v[154:157], v[190:193], v[62:65]
	v_mfma_f32_16x16x32_bf16 v[58:61], v[162:165], v[190:193], v[58:61]
	v_mfma_f32_16x16x32_bf16 v[54:57], v[154:157], v[198:201], v[54:57]
	v_mfma_f32_16x16x32_bf16 v[46:49], v[162:165], v[198:201], v[46:49]
	v_mfma_f32_16x16x32_bf16 v[38:41], v[154:157], v[206:209], v[38:41]
	v_mfma_f32_16x16x32_bf16 v[30:33], v[162:165], v[206:209], v[30:33]
	v_mfma_f32_16x16x32_bf16 v[22:25], v[154:157], v[214:217], v[22:25]
	v_mfma_f32_16x16x32_bf16 v[14:17], v[162:165], v[214:217], v[14:17]
	v_mfma_f32_16x16x32_bf16 v[62:65], v[158:161], v[194:197], v[62:65]
	v_mfma_f32_16x16x32_bf16 v[58:61], v[170:173], v[194:197], v[58:61]
	v_mfma_f32_16x16x32_bf16 v[54:57], v[158:161], v[202:205], v[54:57]
	v_mfma_f32_16x16x32_bf16 v[46:49], v[170:173], v[202:205], v[46:49]
	v_mfma_f32_16x16x32_bf16 v[38:41], v[158:161], v[210:213], v[38:41]
	v_mfma_f32_16x16x32_bf16 v[30:33], v[170:173], v[210:213], v[30:33]
	v_mfma_f32_16x16x32_bf16 v[22:25], v[158:161], v[218:221], v[22:25]
	v_mfma_f32_16x16x32_bf16 v[14:17], v[170:173], v[218:221], v[14:17]
	v_mfma_f32_16x16x32_bf16 v[50:53], v[174:177], v[190:193], v[50:53]
	v_mfma_f32_16x16x32_bf16 v[42:45], v[182:185], v[190:193], v[42:45]
	v_mfma_f32_16x16x32_bf16 v[34:37], v[174:177], v[198:201], v[34:37]
	v_mfma_f32_16x16x32_bf16 v[26:29], v[182:185], v[198:201], v[26:29]
	v_mfma_f32_16x16x32_bf16 v[18:21], v[174:177], v[206:209], v[18:21]
	v_mfma_f32_16x16x32_bf16 v[10:13], v[182:185], v[206:209], v[10:13]
	v_mfma_f32_16x16x32_bf16 v[6:9], v[174:177], v[214:217], v[6:9]
	v_mfma_f32_16x16x32_bf16 v[2:5], v[182:185], v[214:217], v[2:5]
	v_mfma_f32_16x16x32_bf16 v[50:53], v[178:181], v[194:197], v[50:53]
	v_mfma_f32_16x16x32_bf16 v[42:45], v[186:189], v[194:197], v[42:45]
	v_mfma_f32_16x16x32_bf16 v[34:37], v[178:181], v[202:205], v[34:37]
	v_mfma_f32_16x16x32_bf16 v[26:29], v[186:189], v[202:205], v[26:29]
	v_mfma_f32_16x16x32_bf16 v[18:21], v[178:181], v[210:213], v[18:21]
	v_mfma_f32_16x16x32_bf16 v[10:13], v[186:189], v[210:213], v[10:13]
	v_mfma_f32_16x16x32_bf16 v[6:9], v[178:181], v[218:221], v[6:9]
	v_mfma_f32_16x16x32_bf16 v[2:5], v[186:189], v[218:221], v[2:5]
	s_setprio 0
	s_barrier
	ds_read_b128 v[154:157], v152
	ds_read_b128 v[158:161], v152 offset:1024
	ds_read_b128 v[162:165], v152 offset:2048
	ds_read_b128 v[170:173], v152 offset:3072
	ds_read_b128 v[174:177], v153
	ds_read_b128 v[178:181], v153 offset:1024
	ds_read_b128 v[182:185], v153 offset:2048
	ds_read_b128 v[186:189], v153 offset:3072
	s_add_u32 s22, s22, 0x160000
	s_addc_u32 s23, s23, 0
	s_mov_b32 m0, s28
	ds_read_b128 v[190:193], v151 offset:32768
	ds_read_b128 v[194:197], v151 offset:33792
	ds_read_b128 v[198:201], v151 offset:34816
	ds_read_b128 v[202:205], v151 offset:35840
	ds_read_b128 v[206:209], v151 offset:36864
	ds_read_b128 v[210:213], v151 offset:37888
	ds_read_b128 v[214:217], v151 offset:38912
	ds_read_b128 v[218:221], v151 offset:39936
	global_load_lds_dwordx4 v130, s[22:23]
	s_mov_b32 m0, s29
	s_nop 0
	global_load_lds_dwordx4 v134, s[22:23]
	s_waitcnt vmcnt(8)
	s_waitcnt lgkmcnt(0)
	s_barrier
	s_setprio 1
	v_mfma_f32_16x16x32_bf16 v[126:129], v[154:157], v[190:193], v[126:129]
	v_mfma_f32_16x16x32_bf16 v[122:125], v[162:165], v[190:193], v[122:125]
	v_mfma_f32_16x16x32_bf16 v[118:121], v[154:157], v[198:201], v[118:121]
	v_mfma_f32_16x16x32_bf16 v[110:113], v[162:165], v[198:201], v[110:113]
	v_mfma_f32_16x16x32_bf16 v[102:105], v[154:157], v[206:209], v[102:105]
	v_mfma_f32_16x16x32_bf16 v[94:97], v[162:165], v[206:209], v[94:97]
	v_mfma_f32_16x16x32_bf16 v[86:89], v[154:157], v[214:217], v[86:89]
	v_mfma_f32_16x16x32_bf16 v[78:81], v[162:165], v[214:217], v[78:81]
	v_mfma_f32_16x16x32_bf16 v[126:129], v[158:161], v[194:197], v[126:129]
	v_mfma_f32_16x16x32_bf16 v[122:125], v[170:173], v[194:197], v[122:125]
	v_mfma_f32_16x16x32_bf16 v[118:121], v[158:161], v[202:205], v[118:121]
	v_mfma_f32_16x16x32_bf16 v[110:113], v[170:173], v[202:205], v[110:113]
	v_mfma_f32_16x16x32_bf16 v[102:105], v[158:161], v[210:213], v[102:105]
	v_mfma_f32_16x16x32_bf16 v[94:97], v[170:173], v[210:213], v[94:97]
	v_mfma_f32_16x16x32_bf16 v[86:89], v[158:161], v[218:221], v[86:89]
	v_mfma_f32_16x16x32_bf16 v[78:81], v[170:173], v[218:221], v[78:81]
	v_mfma_f32_16x16x32_bf16 v[114:117], v[174:177], v[190:193], v[114:117]
	v_mfma_f32_16x16x32_bf16 v[106:109], v[182:185], v[190:193], v[106:109]
	v_mfma_f32_16x16x32_bf16 v[98:101], v[174:177], v[198:201], v[98:101]
	v_mfma_f32_16x16x32_bf16 v[90:93], v[182:185], v[198:201], v[90:93]
	v_mfma_f32_16x16x32_bf16 v[82:85], v[174:177], v[206:209], v[82:85]
	v_mfma_f32_16x16x32_bf16 v[74:77], v[182:185], v[206:209], v[74:77]
	v_mfma_f32_16x16x32_bf16 v[70:73], v[174:177], v[214:217], v[70:73]
	v_mfma_f32_16x16x32_bf16 v[66:69], v[182:185], v[214:217], v[66:69]
	v_mfma_f32_16x16x32_bf16 v[114:117], v[178:181], v[194:197], v[114:117]
	v_mfma_f32_16x16x32_bf16 v[106:109], v[186:189], v[194:197], v[106:109]
	v_mfma_f32_16x16x32_bf16 v[98:101], v[178:181], v[202:205], v[98:101]
	v_mfma_f32_16x16x32_bf16 v[90:93], v[186:189], v[202:205], v[90:93]
	v_mfma_f32_16x16x32_bf16 v[82:85], v[178:181], v[210:213], v[82:85]
	v_mfma_f32_16x16x32_bf16 v[74:77], v[186:189], v[210:213], v[74:77]
	v_mfma_f32_16x16x32_bf16 v[70:73], v[178:181], v[218:221], v[70:73]
	v_mfma_f32_16x16x32_bf16 v[66:69], v[186:189], v[218:221], v[66:69]
	s_setprio 0
	s_barrier
	s_add_i32 s22, s38, s25
	v_lshl_add_u64 v[146:147], v[146:147], 0, s[8:9]
	s_mov_b32 m0, s22
	ds_read_b128 v[190:193], v151 offset:49152
	ds_read_b128 v[194:197], v151 offset:50176
	ds_read_b128 v[198:201], v151 offset:51200
	ds_read_b128 v[202:205], v151 offset:52224
	ds_read_b128 v[206:209], v151 offset:53248
	ds_read_b128 v[210:213], v151 offset:54272
	ds_read_b128 v[214:217], v151 offset:55296
	ds_read_b128 v[218:221], v151 offset:56320
	global_load_lds_dwordx4 v[146:147], off
	s_add_i32 m0, s22, 0x2000
	s_add_u32 s20, s20, 0x160080
	v_lshl_add_u64 v[146:147], v[222:223], 0, s[8:9]
	s_addc_u32 s21, s21, 0
	s_add_i32 s22, s39, s25
	global_load_lds_dwordx4 v[146:147], off
	s_mov_b32 m0, s22
	s_nop 0
	global_load_lds_dwordx4 v132, s[20:21]
	s_add_i32 m0, s22, 0x2000
	s_nop 0
	global_load_lds_dwordx4 v136, s[20:21]
	v_lshl_add_u64 v[146:147], v[224:225], 0, s[8:9]
	s_mov_b32 m0, s30
	s_nop 0
	global_load_lds_dwordx4 v[146:147], off
	v_lshl_add_u64 v[146:147], v[226:227], 0, s[8:9]
	s_mov_b32 m0, s31
	s_nop 0
	global_load_lds_dwordx4 v[146:147], off
	s_waitcnt vmcnt(8)
	s_waitcnt lgkmcnt(0)
	s_barrier
	s_setprio 1
	v_mfma_f32_16x16x32_bf16 v[62:65], v[154:157], v[190:193], v[62:65]
	v_mfma_f32_16x16x32_bf16 v[58:61], v[162:165], v[190:193], v[58:61]
	v_mfma_f32_16x16x32_bf16 v[54:57], v[154:157], v[198:201], v[54:57]
	v_mfma_f32_16x16x32_bf16 v[46:49], v[162:165], v[198:201], v[46:49]
	v_mfma_f32_16x16x32_bf16 v[38:41], v[154:157], v[206:209], v[38:41]
	v_mfma_f32_16x16x32_bf16 v[30:33], v[162:165], v[206:209], v[30:33]
	v_mfma_f32_16x16x32_bf16 v[22:25], v[154:157], v[214:217], v[22:25]
	v_mfma_f32_16x16x32_bf16 v[14:17], v[162:165], v[214:217], v[14:17]
	v_mfma_f32_16x16x32_bf16 v[62:65], v[158:161], v[194:197], v[62:65]
	v_mfma_f32_16x16x32_bf16 v[58:61], v[170:173], v[194:197], v[58:61]
	v_mfma_f32_16x16x32_bf16 v[54:57], v[158:161], v[202:205], v[54:57]
	v_mfma_f32_16x16x32_bf16 v[46:49], v[170:173], v[202:205], v[46:49]
	v_mfma_f32_16x16x32_bf16 v[38:41], v[158:161], v[210:213], v[38:41]
	v_mfma_f32_16x16x32_bf16 v[30:33], v[170:173], v[210:213], v[30:33]
	v_mfma_f32_16x16x32_bf16 v[22:25], v[158:161], v[218:221], v[22:25]
	v_mfma_f32_16x16x32_bf16 v[14:17], v[170:173], v[218:221], v[14:17]
	v_mfma_f32_16x16x32_bf16 v[50:53], v[174:177], v[190:193], v[50:53]
	v_mfma_f32_16x16x32_bf16 v[42:45], v[182:185], v[190:193], v[42:45]
	v_mfma_f32_16x16x32_bf16 v[34:37], v[174:177], v[198:201], v[34:37]
	v_mfma_f32_16x16x32_bf16 v[26:29], v[182:185], v[198:201], v[26:29]
	v_mfma_f32_16x16x32_bf16 v[18:21], v[174:177], v[206:209], v[18:21]
	v_mfma_f32_16x16x32_bf16 v[10:13], v[182:185], v[206:209], v[10:13]
	v_mfma_f32_16x16x32_bf16 v[6:9], v[174:177], v[214:217], v[6:9]
	v_mfma_f32_16x16x32_bf16 v[2:5], v[182:185], v[214:217], v[2:5]
	v_mfma_f32_16x16x32_bf16 v[50:53], v[178:181], v[194:197], v[50:53]
	v_mfma_f32_16x16x32_bf16 v[42:45], v[186:189], v[194:197], v[42:45]
	v_mfma_f32_16x16x32_bf16 v[34:37], v[178:181], v[202:205], v[34:37]
	v_mfma_f32_16x16x32_bf16 v[26:29], v[186:189], v[202:205], v[26:29]
	v_mfma_f32_16x16x32_bf16 v[18:21], v[178:181], v[210:213], v[18:21]
	v_mfma_f32_16x16x32_bf16 v[10:13], v[186:189], v[210:213], v[10:13]
	v_mfma_f32_16x16x32_bf16 v[6:9], v[178:181], v[218:221], v[6:9]
	v_mfma_f32_16x16x32_bf16 v[2:5], v[186:189], v[218:221], v[2:5]
	s_setprio 0
	s_barrier
	s_add_i32 s46, s46, 2
	s_add_u32 s18, s18, 0x100
	s_addc_u32 s19, s19, 0
	s_add_u32 s44, s44, 0x100
	s_addc_u32 s45, s45, 0
	s_cmpk_gt_u32 s46, 0x55
	s_cbranch_scc0 .LBB0_246
	s_and_b64 vcc, exec, s[14:15]
	s_cbranch_vccz .LBB0_249
	s_barrier

.LBB0_388:
	ds_read_b128 v[146:149], v154
	ds_read_b128 v[160:163], v154 offset:1024
	ds_read_b128 v[170:173], v154 offset:2048
	ds_read_b128 v[174:177], v154 offset:3072
	ds_read_b128 v[178:181], v155
	ds_read_b128 v[182:185], v155 offset:1024
	ds_read_b128 v[186:189], v155 offset:2048
	ds_read_b128 v[190:193], v155 offset:3072
	s_add_u32 s24, s22, 0xfff80080
	s_addc_u32 s25, s23, -1
	s_cmp_eq_u32 s71, 28
	s_cselect_b32 s27, s15, s25
	s_cselect_b32 s26, s67, s24
	s_cselect_b32 s25, s13, s70
	s_cselect_b32 s24, s68, s69
	s_add_i32 m0, s21, 0xc000
	ds_read_b128 v[194:197], v156
	ds_read_b128 v[198:201], v156 offset:1024
	ds_read_b128 v[202:205], v156 offset:2048
	ds_read_b128 v[206:209], v156 offset:3072
	ds_read_b128 v[210:213], v156 offset:4096
	ds_read_b128 v[214:217], v156 offset:5120
	ds_read_b128 v[218:221], v156 offset:6144
	ds_read_b128 v[222:225], v156 offset:7168
	global_load_lds_dwordx4 v138, s[22:23]
	s_add_i32 m0, s21, 0xe000
	s_nop 0
	global_load_lds_dwordx4 v140, s[22:23]
	s_waitcnt vmcnt(8)
	s_waitcnt lgkmcnt(0)
	s_barrier
	s_setprio 1
	v_mfma_f32_16x16x32_bf16 v[126:129], v[146:149], v[194:197], v[126:129]
	v_mfma_f32_16x16x32_bf16 v[122:125], v[170:173], v[194:197], v[122:125]
	v_mfma_f32_16x16x32_bf16 v[118:121], v[146:149], v[202:205], v[118:121]
	v_mfma_f32_16x16x32_bf16 v[110:113], v[170:173], v[202:205], v[110:113]
	v_mfma_f32_16x16x32_bf16 v[102:105], v[146:149], v[210:213], v[102:105]
	v_mfma_f32_16x16x32_bf16 v[94:97], v[170:173], v[210:213], v[94:97]
	v_mfma_f32_16x16x32_bf16 v[86:89], v[146:149], v[218:221], v[86:89]
	v_mfma_f32_16x16x32_bf16 v[78:81], v[170:173], v[218:221], v[78:81]
	v_mfma_f32_16x16x32_bf16 v[126:129], v[160:163], v[198:201], v[126:129]
	v_mfma_f32_16x16x32_bf16 v[122:125], v[174:177], v[198:201], v[122:125]
	v_mfma_f32_16x16x32_bf16 v[118:121], v[160:163], v[206:209], v[118:121]
	v_mfma_f32_16x16x32_bf16 v[110:113], v[174:177], v[206:209], v[110:113]
	v_mfma_f32_16x16x32_bf16 v[102:105], v[160:163], v[214:217], v[102:105]
	v_mfma_f32_16x16x32_bf16 v[94:97], v[174:177], v[214:217], v[94:97]
	v_mfma_f32_16x16x32_bf16 v[86:89], v[160:163], v[222:225], v[86:89]
	v_mfma_f32_16x16x32_bf16 v[78:81], v[174:177], v[222:225], v[78:81]
	v_mfma_f32_16x16x32_bf16 v[114:117], v[178:181], v[194:197], v[114:117]
	v_mfma_f32_16x16x32_bf16 v[106:109], v[186:189], v[194:197], v[106:109]
	v_mfma_f32_16x16x32_bf16 v[98:101], v[178:181], v[202:205], v[98:101]
	v_mfma_f32_16x16x32_bf16 v[90:93], v[186:189], v[202:205], v[90:93]
	v_mfma_f32_16x16x32_bf16 v[82:85], v[178:181], v[210:213], v[82:85]
	v_mfma_f32_16x16x32_bf16 v[74:77], v[186:189], v[210:213], v[74:77]
	v_mfma_f32_16x16x32_bf16 v[70:73], v[178:181], v[218:221], v[70:73]
	v_mfma_f32_16x16x32_bf16 v[66:69], v[186:189], v[218:221], v[66:69]
	v_mfma_f32_16x16x32_bf16 v[114:117], v[182:185], v[198:201], v[114:117]
	v_mfma_f32_16x16x32_bf16 v[106:109], v[190:193], v[198:201], v[106:109]
	v_mfma_f32_16x16x32_bf16 v[98:101], v[182:185], v[206:209], v[98:101]
	v_mfma_f32_16x16x32_bf16 v[90:93], v[190:193], v[206:209], v[90:93]
	v_mfma_f32_16x16x32_bf16 v[82:85], v[182:185], v[214:217], v[82:85]
	v_mfma_f32_16x16x32_bf16 v[74:77], v[190:193], v[214:217], v[74:77]
	v_mfma_f32_16x16x32_bf16 v[70:73], v[182:185], v[222:225], v[70:73]
	v_mfma_f32_16x16x32_bf16 v[66:69], v[190:193], v[222:225], v[66:69]
	s_setprio 0
	s_barrier
	s_add_i32 s72, s41, s30
	v_lshl_add_u64 v[164:165], s[24:25], 0, v[134:135]
	s_mov_b32 m0, s72
	ds_read_b128 v[194:197], v156 offset:16384
	ds_read_b128 v[198:201], v156 offset:17408
	ds_read_b128 v[202:205], v156 offset:18432
	ds_read_b128 v[206:209], v156 offset:19456
	ds_read_b128 v[210:213], v156 offset:20480
	ds_read_b128 v[214:217], v156 offset:21504
	ds_read_b128 v[218:221], v156 offset:22528
	ds_read_b128 v[222:225], v156 offset:23552
	global_load_lds_dwordx4 v134, s[24:25]
	s_add_i32 m0, s72, 0x2000
	s_add_u32 s72, s24, 0x80000
	v_lshl_add_u64 v[226:227], s[24:25], 0, v[130:131]
	s_addc_u32 s73, s25, 0
	s_add_i32 s74, s46, s30
	global_load_lds_dwordx4 v130, s[24:25]
	s_mov_b32 m0, s74
	v_lshl_add_u64 v[230:231], s[26:27], 0, v[132:133]
	global_load_lds_dwordx4 v134, s[72:73]
	s_add_i32 m0, s74, 0x2000
	s_nop 0
	global_load_lds_dwordx4 v130, s[72:73]
	v_lshl_add_u64 v[228:229], s[26:27], 0, v[136:137]
	s_mov_b32 m0, s21
	s_nop 0
	global_load_lds_dwordx4 v136, s[26:27]
	s_mov_b32 m0, s34
	s_nop 0
	global_load_lds_dwordx4 v132, s[26:27]
	s_waitcnt vmcnt(8)
	s_waitcnt lgkmcnt(0)
	s_barrier
	s_setprio 1
	v_mfma_f32_16x16x32_bf16 v[62:65], v[146:149], v[194:197], v[62:65]
	v_mfma_f32_16x16x32_bf16 v[58:61], v[170:173], v[194:197], v[58:61]
	v_mfma_f32_16x16x32_bf16 v[54:57], v[146:149], v[202:205], v[54:57]
	v_mfma_f32_16x16x32_bf16 v[46:49], v[170:173], v[202:205], v[46:49]
	v_mfma_f32_16x16x32_bf16 v[38:41], v[146:149], v[210:213], v[38:41]
	v_mfma_f32_16x16x32_bf16 v[30:33], v[170:173], v[210:213], v[30:33]
	v_mfma_f32_16x16x32_bf16 v[22:25], v[146:149], v[218:221], v[22:25]
	v_mfma_f32_16x16x32_bf16 v[14:17], v[170:173], v[218:221], v[14:17]
	v_mfma_f32_16x16x32_bf16 v[62:65], v[160:163], v[198:201], v[62:65]
	v_mfma_f32_16x16x32_bf16 v[58:61], v[174:177], v[198:201], v[58:61]
	v_mfma_f32_16x16x32_bf16 v[54:57], v[160:163], v[206:209], v[54:57]
	v_mfma_f32_16x16x32_bf16 v[46:49], v[174:177], v[206:209], v[46:49]
	v_mfma_f32_16x16x32_bf16 v[38:41], v[160:163], v[214:217], v[38:41]
	v_mfma_f32_16x16x32_bf16 v[30:33], v[174:177], v[214:217], v[30:33]
	v_mfma_f32_16x16x32_bf16 v[22:25], v[160:163], v[222:225], v[22:25]
	v_mfma_f32_16x16x32_bf16 v[14:17], v[174:177], v[222:225], v[14:17]
	v_mfma_f32_16x16x32_bf16 v[50:53], v[178:181], v[194:197], v[50:53]
	v_mfma_f32_16x16x32_bf16 v[42:45], v[186:189], v[194:197], v[42:45]
	v_mfma_f32_16x16x32_bf16 v[34:37], v[178:181], v[202:205], v[34:37]
	v_mfma_f32_16x16x32_bf16 v[26:29], v[186:189], v[202:205], v[26:29]
	v_mfma_f32_16x16x32_bf16 v[18:21], v[178:181], v[210:213], v[18:21]
	v_mfma_f32_16x16x32_bf16 v[10:13], v[186:189], v[210:213], v[10:13]
	v_mfma_f32_16x16x32_bf16 v[6:9], v[178:181], v[218:221], v[6:9]
	v_mfma_f32_16x16x32_bf16 v[2:5], v[186:189], v[218:221], v[2:5]
	v_mfma_f32_16x16x32_bf16 v[50:53], v[182:185], v[198:201], v[50:53]
	v_mfma_f32_16x16x32_bf16 v[42:45], v[190:193], v[198:201], v[42:45]
	v_mfma_f32_16x16x32_bf16 v[34:37], v[182:185], v[206:209], v[34:37]
	v_mfma_f32_16x16x32_bf16 v[26:29], v[190:193], v[206:209], v[26:29]
	v_mfma_f32_16x16x32_bf16 v[18:21], v[182:185], v[214:217], v[18:21]
	v_mfma_f32_16x16x32_bf16 v[10:13], v[190:193], v[214:217], v[10:13]
	v_mfma_f32_16x16x32_bf16 v[6:9], v[182:185], v[222:225], v[6:9]
	v_mfma_f32_16x16x32_bf16 v[2:5], v[190:193], v[222:225], v[2:5]
	s_setprio 0
	s_barrier
	ds_read_b128 v[146:149], v157
	ds_read_b128 v[160:163], v157 offset:1024
	ds_read_b128 v[170:173], v157 offset:2048
	ds_read_b128 v[174:177], v157 offset:3072
	ds_read_b128 v[178:181], v158
	ds_read_b128 v[182:185], v158 offset:1024
	ds_read_b128 v[186:189], v158 offset:2048
	ds_read_b128 v[190:193], v158 offset:3072
	s_add_u32 s26, s26, 0x80000
	s_addc_u32 s27, s27, 0
	s_mov_b32 m0, s35
	ds_read_b128 v[194:197], v156 offset:32768
	ds_read_b128 v[198:201], v156 offset:33792
	ds_read_b128 v[202:205], v156 offset:34816
	ds_read_b128 v[206:209], v156 offset:35840
	ds_read_b128 v[210:213], v156 offset:36864
	ds_read_b128 v[214:217], v156 offset:37888
	ds_read_b128 v[218:221], v156 offset:38912
	ds_read_b128 v[222:225], v156 offset:39936
	global_load_lds_dwordx4 v136, s[26:27]
	s_mov_b32 m0, s36
	s_nop 0
	global_load_lds_dwordx4 v132, s[26:27]
	s_waitcnt vmcnt(8)
	s_waitcnt lgkmcnt(0)
	s_barrier
	s_setprio 1
	v_mfma_f32_16x16x32_bf16 v[126:129], v[146:149], v[194:197], v[126:129]
	v_mfma_f32_16x16x32_bf16 v[122:125], v[170:173], v[194:197], v[122:125]
	v_mfma_f32_16x16x32_bf16 v[118:121], v[146:149], v[202:205], v[118:121]
	v_mfma_f32_16x16x32_bf16 v[110:113], v[170:173], v[202:205], v[110:113]
	v_mfma_f32_16x16x32_bf16 v[102:105], v[146:149], v[210:213], v[102:105]
	v_mfma_f32_16x16x32_bf16 v[94:97], v[170:173], v[210:213], v[94:97]
	v_mfma_f32_16x16x32_bf16 v[86:89], v[146:149], v[218:221], v[86:89]
	v_mfma_f32_16x16x32_bf16 v[78:81], v[170:173], v[218:221], v[78:81]
	v_mfma_f32_16x16x32_bf16 v[126:129], v[160:163], v[198:201], v[126:129]
	v_mfma_f32_16x16x32_bf16 v[122:125], v[174:177], v[198:201], v[122:125]
	v_mfma_f32_16x16x32_bf16 v[118:121], v[160:163], v[206:209], v[118:121]
	v_mfma_f32_16x16x32_bf16 v[110:113], v[174:177], v[206:209], v[110:113]
	v_mfma_f32_16x16x32_bf16 v[102:105], v[160:163], v[214:217], v[102:105]
	v_mfma_f32_16x16x32_bf16 v[94:97], v[174:177], v[214:217], v[94:97]
	v_mfma_f32_16x16x32_bf16 v[86:89], v[160:163], v[222:225], v[86:89]
	v_mfma_f32_16x16x32_bf16 v[78:81], v[174:177], v[222:225], v[78:81]
	v_mfma_f32_16x16x32_bf16 v[114:117], v[178:181], v[194:197], v[114:117]
	v_mfma_f32_16x16x32_bf16 v[106:109], v[186:189], v[194:197], v[106:109]
	v_mfma_f32_16x16x32_bf16 v[98:101], v[178:181], v[202:205], v[98:101]
	v_mfma_f32_16x16x32_bf16 v[90:93], v[186:189], v[202:205], v[90:93]
	v_mfma_f32_16x16x32_bf16 v[82:85], v[178:181], v[210:213], v[82:85]
	v_mfma_f32_16x16x32_bf16 v[74:77], v[186:189], v[210:213], v[74:77]
	v_mfma_f32_16x16x32_bf16 v[70:73], v[178:181], v[218:221], v[70:73]
	v_mfma_f32_16x16x32_bf16 v[66:69], v[186:189], v[218:221], v[66:69]
	v_mfma_f32_16x16x32_bf16 v[114:117], v[182:185], v[198:201], v[114:117]
	v_mfma_f32_16x16x32_bf16 v[106:109], v[190:193], v[198:201], v[106:109]
	v_mfma_f32_16x16x32_bf16 v[98:101], v[182:185], v[206:209], v[98:101]
	v_mfma_f32_16x16x32_bf16 v[90:93], v[190:193], v[206:209], v[90:93]
	v_mfma_f32_16x16x32_bf16 v[82:85], v[182:185], v[214:217], v[82:85]
	v_mfma_f32_16x16x32_bf16 v[74:77], v[190:193], v[214:217], v[74:77]
	v_mfma_f32_16x16x32_bf16 v[70:73], v[182:185], v[222:225], v[70:73]
	v_mfma_f32_16x16x32_bf16 v[66:69], v[190:193], v[222:225], v[66:69]
	s_setprio 0
	s_barrier
	s_add_i32 s26, s47, s30
	v_lshl_add_u64 v[164:165], v[164:165], 0, s[6:7]
	s_mov_b32 m0, s26
	ds_read_b128 v[194:197], v156 offset:49152
	ds_read_b128 v[198:201], v156 offset:50176
	ds_read_b128 v[202:205], v156 offset:51200
	ds_read_b128 v[206:209], v156 offset:52224
	ds_read_b128 v[210:213], v156 offset:53248
	ds_read_b128 v[214:217], v156 offset:54272
	ds_read_b128 v[218:221], v156 offset:55296
	ds_read_b128 v[222:225], v156 offset:56320
	global_load_lds_dwordx4 v[164:165], off
	s_add_i32 m0, s26, 0x2000
	s_add_u32 s24, s24, 0x80080
	v_lshl_add_u64 v[164:165], v[226:227], 0, s[6:7]
	s_addc_u32 s25, s25, 0
	s_add_i32 s26, s63, s30
	global_load_lds_dwordx4 v[164:165], off
	s_mov_b32 m0, s26
	s_nop 0
	global_load_lds_dwordx4 v134, s[24:25]
	s_add_i32 m0, s26, 0x2000
	s_nop 0
	global_load_lds_dwordx4 v130, s[24:25]
	v_lshl_add_u64 v[164:165], v[228:229], 0, s[6:7]
	s_mov_b32 m0, s37
	s_nop 0
	global_load_lds_dwordx4 v[164:165], off
	v_lshl_add_u64 v[164:165], v[230:231], 0, s[6:7]
	s_mov_b32 m0, s38
	s_nop 0
	global_load_lds_dwordx4 v[164:165], off
	s_waitcnt vmcnt(8)
	s_waitcnt lgkmcnt(0)
	s_barrier
	s_setprio 1
	v_mfma_f32_16x16x32_bf16 v[62:65], v[146:149], v[194:197], v[62:65]
	v_mfma_f32_16x16x32_bf16 v[58:61], v[170:173], v[194:197], v[58:61]
	v_mfma_f32_16x16x32_bf16 v[54:57], v[146:149], v[202:205], v[54:57]
	v_mfma_f32_16x16x32_bf16 v[46:49], v[170:173], v[202:205], v[46:49]
	v_mfma_f32_16x16x32_bf16 v[38:41], v[146:149], v[210:213], v[38:41]
	v_mfma_f32_16x16x32_bf16 v[30:33], v[170:173], v[210:213], v[30:33]
	v_mfma_f32_16x16x32_bf16 v[22:25], v[146:149], v[218:221], v[22:25]
	v_mfma_f32_16x16x32_bf16 v[14:17], v[170:173], v[218:221], v[14:17]
	v_mfma_f32_16x16x32_bf16 v[62:65], v[160:163], v[198:201], v[62:65]
	v_mfma_f32_16x16x32_bf16 v[58:61], v[174:177], v[198:201], v[58:61]
	v_mfma_f32_16x16x32_bf16 v[54:57], v[160:163], v[206:209], v[54:57]
	v_mfma_f32_16x16x32_bf16 v[46:49], v[174:177], v[206:209], v[46:49]
	v_mfma_f32_16x16x32_bf16 v[38:41], v[160:163], v[214:217], v[38:41]
	v_mfma_f32_16x16x32_bf16 v[30:33], v[174:177], v[214:217], v[30:33]
	v_mfma_f32_16x16x32_bf16 v[22:25], v[160:163], v[222:225], v[22:25]
	v_mfma_f32_16x16x32_bf16 v[14:17], v[174:177], v[222:225], v[14:17]
	v_mfma_f32_16x16x32_bf16 v[50:53], v[178:181], v[194:197], v[50:53]
	v_mfma_f32_16x16x32_bf16 v[42:45], v[186:189], v[194:197], v[42:45]
	v_mfma_f32_16x16x32_bf16 v[34:37], v[178:181], v[202:205], v[34:37]
	v_mfma_f32_16x16x32_bf16 v[26:29], v[186:189], v[202:205], v[26:29]
	v_mfma_f32_16x16x32_bf16 v[18:21], v[178:181], v[210:213], v[18:21]
	v_mfma_f32_16x16x32_bf16 v[10:13], v[186:189], v[210:213], v[10:13]
	v_mfma_f32_16x16x32_bf16 v[6:9], v[178:181], v[218:221], v[6:9]
	v_mfma_f32_16x16x32_bf16 v[2:5], v[186:189], v[218:221], v[2:5]
	v_mfma_f32_16x16x32_bf16 v[50:53], v[182:185], v[198:201], v[50:53]
	v_mfma_f32_16x16x32_bf16 v[42:45], v[190:193], v[198:201], v[42:45]
	v_mfma_f32_16x16x32_bf16 v[34:37], v[182:185], v[206:209], v[34:37]
	v_mfma_f32_16x16x32_bf16 v[26:29], v[190:193], v[206:209], v[26:29]
	v_mfma_f32_16x16x32_bf16 v[18:21], v[182:185], v[214:217], v[18:21]
	v_mfma_f32_16x16x32_bf16 v[10:13], v[190:193], v[214:217], v[10:13]
	v_mfma_f32_16x16x32_bf16 v[6:9], v[182:185], v[222:225], v[6:9]
	v_mfma_f32_16x16x32_bf16 v[2:5], v[190:193], v[222:225], v[2:5]
	s_setprio 0
	s_barrier
	s_add_i32 s71, s71, 2
	s_add_u32 s22, s22, 0x100
	s_addc_u32 s23, s23, 0
	s_add_u32 s69, s69, 0x100
	s_addc_u32 s70, s70, 0
	s_cmp_gt_u32 s71, 29
	s_cbranch_scc0 .LBB0_388
	s_and_b64 vcc, exec, s[10:11]
	s_cbranch_vccz .LBB0_391
	s_barrier

.LBB0_575:
	ds_read_b128 v[154:157], v149
	ds_read_b128 v[158:161], v149 offset:1024
	ds_read_b128 v[162:165], v149 offset:2048
	ds_read_b128 v[170:173], v149 offset:3072
	ds_read_b128 v[174:177], v150
	ds_read_b128 v[178:181], v150 offset:1024
	ds_read_b128 v[182:185], v150 offset:2048
	ds_read_b128 v[186:189], v150 offset:3072
	s_add_u32 s26, s24, 0xfff80080
	s_addc_u32 s27, s25, -1
	s_cmp_eq_u32 s50, 28
	s_cselect_b32 s29, s17, s27
	s_cselect_b32 s28, s46, s26
	s_cselect_b32 s27, s15, s49
	s_cselect_b32 s26, s47, s48
	s_add_i32 m0, s23, 0xc000
	ds_read_b128 v[190:193], v151
	ds_read_b128 v[194:197], v151 offset:1024
	ds_read_b128 v[198:201], v151 offset:2048
	ds_read_b128 v[202:205], v151 offset:3072
	ds_read_b128 v[206:209], v151 offset:4096
	ds_read_b128 v[210:213], v151 offset:5120
	ds_read_b128 v[214:217], v151 offset:6144
	ds_read_b128 v[218:221], v151 offset:7168
	global_load_lds_dwordx4 v138, s[24:25]
	s_add_i32 m0, s23, 0xe000
	s_nop 0
	global_load_lds_dwordx4 v140, s[24:25]
	s_waitcnt vmcnt(8)
	s_waitcnt lgkmcnt(0)
	s_barrier
	s_setprio 1
	v_mfma_f32_16x16x32_bf16 v[126:129], v[154:157], v[190:193], v[126:129]
	v_mfma_f32_16x16x32_bf16 v[122:125], v[162:165], v[190:193], v[122:125]
	v_mfma_f32_16x16x32_bf16 v[118:121], v[154:157], v[198:201], v[118:121]
	v_mfma_f32_16x16x32_bf16 v[110:113], v[162:165], v[198:201], v[110:113]
	v_mfma_f32_16x16x32_bf16 v[102:105], v[154:157], v[206:209], v[102:105]
	v_mfma_f32_16x16x32_bf16 v[94:97], v[162:165], v[206:209], v[94:97]
	v_mfma_f32_16x16x32_bf16 v[86:89], v[154:157], v[214:217], v[86:89]
	v_mfma_f32_16x16x32_bf16 v[78:81], v[162:165], v[214:217], v[78:81]
	v_mfma_f32_16x16x32_bf16 v[126:129], v[158:161], v[194:197], v[126:129]
	v_mfma_f32_16x16x32_bf16 v[122:125], v[170:173], v[194:197], v[122:125]
	v_mfma_f32_16x16x32_bf16 v[118:121], v[158:161], v[202:205], v[118:121]
	v_mfma_f32_16x16x32_bf16 v[110:113], v[170:173], v[202:205], v[110:113]
	v_mfma_f32_16x16x32_bf16 v[102:105], v[158:161], v[210:213], v[102:105]
	v_mfma_f32_16x16x32_bf16 v[94:97], v[170:173], v[210:213], v[94:97]
	v_mfma_f32_16x16x32_bf16 v[86:89], v[158:161], v[218:221], v[86:89]
	v_mfma_f32_16x16x32_bf16 v[78:81], v[170:173], v[218:221], v[78:81]
	v_mfma_f32_16x16x32_bf16 v[114:117], v[174:177], v[190:193], v[114:117]
	v_mfma_f32_16x16x32_bf16 v[106:109], v[182:185], v[190:193], v[106:109]
	v_mfma_f32_16x16x32_bf16 v[98:101], v[174:177], v[198:201], v[98:101]
	v_mfma_f32_16x16x32_bf16 v[90:93], v[182:185], v[198:201], v[90:93]
	v_mfma_f32_16x16x32_bf16 v[82:85], v[174:177], v[206:209], v[82:85]
	v_mfma_f32_16x16x32_bf16 v[74:77], v[182:185], v[206:209], v[74:77]
	v_mfma_f32_16x16x32_bf16 v[70:73], v[174:177], v[214:217], v[70:73]
	v_mfma_f32_16x16x32_bf16 v[66:69], v[182:185], v[214:217], v[66:69]
	v_mfma_f32_16x16x32_bf16 v[114:117], v[178:181], v[194:197], v[114:117]
	v_mfma_f32_16x16x32_bf16 v[106:109], v[186:189], v[194:197], v[106:109]
	v_mfma_f32_16x16x32_bf16 v[98:101], v[178:181], v[202:205], v[98:101]
	v_mfma_f32_16x16x32_bf16 v[90:93], v[186:189], v[202:205], v[90:93]
	v_mfma_f32_16x16x32_bf16 v[82:85], v[178:181], v[210:213], v[82:85]
	v_mfma_f32_16x16x32_bf16 v[74:77], v[186:189], v[210:213], v[74:77]
	v_mfma_f32_16x16x32_bf16 v[70:73], v[178:181], v[218:221], v[70:73]
	v_mfma_f32_16x16x32_bf16 v[66:69], v[186:189], v[218:221], v[66:69]
	s_setprio 0
	s_barrier
	s_add_i32 s51, s41, s31
	v_lshl_add_u64 v[146:147], s[26:27], 0, v[132:133]
	s_mov_b32 m0, s51
	ds_read_b128 v[190:193], v151 offset:16384
	ds_read_b128 v[194:197], v151 offset:17408
	ds_read_b128 v[198:201], v151 offset:18432
	ds_read_b128 v[202:205], v151 offset:19456
	ds_read_b128 v[206:209], v151 offset:20480
	ds_read_b128 v[210:213], v151 offset:21504
	ds_read_b128 v[214:217], v151 offset:22528
	ds_read_b128 v[218:221], v151 offset:23552
	global_load_lds_dwordx4 v132, s[26:27]
	s_add_i32 m0, s51, 0x2000
	s_add_u32 s68, s26, 0x80000
	v_lshl_add_u64 v[222:223], s[26:27], 0, v[136:137]
	s_addc_u32 s69, s27, 0
	s_add_i32 s51, s42, s31
	global_load_lds_dwordx4 v136, s[26:27]
	s_mov_b32 m0, s51
	v_lshl_add_u64 v[226:227], s[28:29], 0, v[134:135]
	global_load_lds_dwordx4 v132, s[68:69]
	s_add_i32 m0, s51, 0x2000
	s_nop 0
	global_load_lds_dwordx4 v136, s[68:69]
	v_lshl_add_u64 v[224:225], s[28:29], 0, v[130:131]
	s_mov_b32 m0, s23
	s_nop 0
	global_load_lds_dwordx4 v130, s[28:29]
	s_mov_b32 m0, s34
	s_nop 0
	global_load_lds_dwordx4 v134, s[28:29]
	s_waitcnt vmcnt(8)
	s_waitcnt lgkmcnt(0)
	s_barrier
	s_setprio 1
	v_mfma_f32_16x16x32_bf16 v[62:65], v[154:157], v[190:193], v[62:65]
	v_mfma_f32_16x16x32_bf16 v[58:61], v[162:165], v[190:193], v[58:61]
	v_mfma_f32_16x16x32_bf16 v[54:57], v[154:157], v[198:201], v[54:57]
	v_mfma_f32_16x16x32_bf16 v[46:49], v[162:165], v[198:201], v[46:49]
	v_mfma_f32_16x16x32_bf16 v[38:41], v[154:157], v[206:209], v[38:41]
	v_mfma_f32_16x16x32_bf16 v[30:33], v[162:165], v[206:209], v[30:33]
	v_mfma_f32_16x16x32_bf16 v[22:25], v[154:157], v[214:217], v[22:25]
	v_mfma_f32_16x16x32_bf16 v[14:17], v[162:165], v[214:217], v[14:17]
	v_mfma_f32_16x16x32_bf16 v[62:65], v[158:161], v[194:197], v[62:65]
	v_mfma_f32_16x16x32_bf16 v[58:61], v[170:173], v[194:197], v[58:61]
	v_mfma_f32_16x16x32_bf16 v[54:57], v[158:161], v[202:205], v[54:57]
	v_mfma_f32_16x16x32_bf16 v[46:49], v[170:173], v[202:205], v[46:49]
	v_mfma_f32_16x16x32_bf16 v[38:41], v[158:161], v[210:213], v[38:41]
	v_mfma_f32_16x16x32_bf16 v[30:33], v[170:173], v[210:213], v[30:33]
	v_mfma_f32_16x16x32_bf16 v[22:25], v[158:161], v[218:221], v[22:25]
	v_mfma_f32_16x16x32_bf16 v[14:17], v[170:173], v[218:221], v[14:17]
	v_mfma_f32_16x16x32_bf16 v[50:53], v[174:177], v[190:193], v[50:53]
	v_mfma_f32_16x16x32_bf16 v[42:45], v[182:185], v[190:193], v[42:45]
	v_mfma_f32_16x16x32_bf16 v[34:37], v[174:177], v[198:201], v[34:37]
	v_mfma_f32_16x16x32_bf16 v[26:29], v[182:185], v[198:201], v[26:29]
	v_mfma_f32_16x16x32_bf16 v[18:21], v[174:177], v[206:209], v[18:21]
	v_mfma_f32_16x16x32_bf16 v[10:13], v[182:185], v[206:209], v[10:13]
	v_mfma_f32_16x16x32_bf16 v[6:9], v[174:177], v[214:217], v[6:9]
	v_mfma_f32_16x16x32_bf16 v[2:5], v[182:185], v[214:217], v[2:5]
	v_mfma_f32_16x16x32_bf16 v[50:53], v[178:181], v[194:197], v[50:53]
	v_mfma_f32_16x16x32_bf16 v[42:45], v[186:189], v[194:197], v[42:45]
	v_mfma_f32_16x16x32_bf16 v[34:37], v[178:181], v[202:205], v[34:37]
	v_mfma_f32_16x16x32_bf16 v[26:29], v[186:189], v[202:205], v[26:29]
	v_mfma_f32_16x16x32_bf16 v[18:21], v[178:181], v[210:213], v[18:21]
	v_mfma_f32_16x16x32_bf16 v[10:13], v[186:189], v[210:213], v[10:13]
	v_mfma_f32_16x16x32_bf16 v[6:9], v[178:181], v[218:221], v[6:9]
	v_mfma_f32_16x16x32_bf16 v[2:5], v[186:189], v[218:221], v[2:5]
	s_setprio 0
	s_barrier
	ds_read_b128 v[154:157], v152
	ds_read_b128 v[158:161], v152 offset:1024
	ds_read_b128 v[162:165], v152 offset:2048
	ds_read_b128 v[170:173], v152 offset:3072
	ds_read_b128 v[174:177], v153
	ds_read_b128 v[178:181], v153 offset:1024
	ds_read_b128 v[182:185], v153 offset:2048
	ds_read_b128 v[186:189], v153 offset:3072
	s_add_u32 s28, s28, 0x80000
	s_addc_u32 s29, s29, 0
	s_mov_b32 m0, s35
	ds_read_b128 v[190:193], v151 offset:32768
	ds_read_b128 v[194:197], v151 offset:33792
	ds_read_b128 v[198:201], v151 offset:34816
	ds_read_b128 v[202:205], v151 offset:35840
	ds_read_b128 v[206:209], v151 offset:36864
	ds_read_b128 v[210:213], v151 offset:37888
	ds_read_b128 v[214:217], v151 offset:38912
	ds_read_b128 v[218:221], v151 offset:39936
	global_load_lds_dwordx4 v130, s[28:29]
	s_mov_b32 m0, s36
	s_nop 0
	global_load_lds_dwordx4 v134, s[28:29]
	s_waitcnt vmcnt(8)
	s_waitcnt lgkmcnt(0)
	s_barrier
	s_setprio 1
	v_mfma_f32_16x16x32_bf16 v[126:129], v[154:157], v[190:193], v[126:129]
	v_mfma_f32_16x16x32_bf16 v[122:125], v[162:165], v[190:193], v[122:125]
	v_mfma_f32_16x16x32_bf16 v[118:121], v[154:157], v[198:201], v[118:121]
	v_mfma_f32_16x16x32_bf16 v[110:113], v[162:165], v[198:201], v[110:113]
	v_mfma_f32_16x16x32_bf16 v[102:105], v[154:157], v[206:209], v[102:105]
	v_mfma_f32_16x16x32_bf16 v[94:97], v[162:165], v[206:209], v[94:97]
	v_mfma_f32_16x16x32_bf16 v[86:89], v[154:157], v[214:217], v[86:89]
	v_mfma_f32_16x16x32_bf16 v[78:81], v[162:165], v[214:217], v[78:81]
	v_mfma_f32_16x16x32_bf16 v[126:129], v[158:161], v[194:197], v[126:129]
	v_mfma_f32_16x16x32_bf16 v[122:125], v[170:173], v[194:197], v[122:125]
	v_mfma_f32_16x16x32_bf16 v[118:121], v[158:161], v[202:205], v[118:121]
	v_mfma_f32_16x16x32_bf16 v[110:113], v[170:173], v[202:205], v[110:113]
	v_mfma_f32_16x16x32_bf16 v[102:105], v[158:161], v[210:213], v[102:105]
	v_mfma_f32_16x16x32_bf16 v[94:97], v[170:173], v[210:213], v[94:97]
	v_mfma_f32_16x16x32_bf16 v[86:89], v[158:161], v[218:221], v[86:89]
	v_mfma_f32_16x16x32_bf16 v[78:81], v[170:173], v[218:221], v[78:81]
	v_mfma_f32_16x16x32_bf16 v[114:117], v[174:177], v[190:193], v[114:117]
	v_mfma_f32_16x16x32_bf16 v[106:109], v[182:185], v[190:193], v[106:109]
	v_mfma_f32_16x16x32_bf16 v[98:101], v[174:177], v[198:201], v[98:101]
	v_mfma_f32_16x16x32_bf16 v[90:93], v[182:185], v[198:201], v[90:93]
	v_mfma_f32_16x16x32_bf16 v[82:85], v[174:177], v[206:209], v[82:85]
	v_mfma_f32_16x16x32_bf16 v[74:77], v[182:185], v[206:209], v[74:77]
	v_mfma_f32_16x16x32_bf16 v[70:73], v[174:177], v[214:217], v[70:73]
	v_mfma_f32_16x16x32_bf16 v[66:69], v[182:185], v[214:217], v[66:69]
	v_mfma_f32_16x16x32_bf16 v[114:117], v[178:181], v[194:197], v[114:117]
	v_mfma_f32_16x16x32_bf16 v[106:109], v[186:189], v[194:197], v[106:109]
	v_mfma_f32_16x16x32_bf16 v[98:101], v[178:181], v[202:205], v[98:101]
	v_mfma_f32_16x16x32_bf16 v[90:93], v[186:189], v[202:205], v[90:93]
	v_mfma_f32_16x16x32_bf16 v[82:85], v[178:181], v[210:213], v[82:85]
	v_mfma_f32_16x16x32_bf16 v[74:77], v[186:189], v[210:213], v[74:77]
	v_mfma_f32_16x16x32_bf16 v[70:73], v[178:181], v[218:221], v[70:73]
	v_mfma_f32_16x16x32_bf16 v[66:69], v[186:189], v[218:221], v[66:69]
	s_setprio 0
	s_barrier
	s_add_i32 s28, s43, s31
	v_lshl_add_u64 v[146:147], v[146:147], 0, s[8:9]
	s_mov_b32 m0, s28
	ds_read_b128 v[190:193], v151 offset:49152
	ds_read_b128 v[194:197], v151 offset:50176
	ds_read_b128 v[198:201], v151 offset:51200
	ds_read_b128 v[202:205], v151 offset:52224
	ds_read_b128 v[206:209], v151 offset:53248
	ds_read_b128 v[210:213], v151 offset:54272
	ds_read_b128 v[214:217], v151 offset:55296
	ds_read_b128 v[218:221], v151 offset:56320
	global_load_lds_dwordx4 v[146:147], off
	s_add_i32 m0, s28, 0x2000
	s_add_u32 s26, s26, 0x80080
	v_lshl_add_u64 v[146:147], v[222:223], 0, s[8:9]
	s_addc_u32 s27, s27, 0
	s_add_i32 s28, s44, s31
	global_load_lds_dwordx4 v[146:147], off
	s_mov_b32 m0, s28
	s_nop 0
	global_load_lds_dwordx4 v132, s[26:27]
	s_add_i32 m0, s28, 0x2000
	s_nop 0
	global_load_lds_dwordx4 v136, s[26:27]
	v_lshl_add_u64 v[146:147], v[224:225], 0, s[8:9]
	s_mov_b32 m0, s37
	s_nop 0
	global_load_lds_dwordx4 v[146:147], off
	v_lshl_add_u64 v[146:147], v[226:227], 0, s[8:9]
	s_mov_b32 m0, s38
	s_nop 0
	global_load_lds_dwordx4 v[146:147], off
	s_waitcnt vmcnt(8)
	s_waitcnt lgkmcnt(0)
	s_barrier
	s_setprio 1
	v_mfma_f32_16x16x32_bf16 v[62:65], v[154:157], v[190:193], v[62:65]
	v_mfma_f32_16x16x32_bf16 v[58:61], v[162:165], v[190:193], v[58:61]
	v_mfma_f32_16x16x32_bf16 v[54:57], v[154:157], v[198:201], v[54:57]
	v_mfma_f32_16x16x32_bf16 v[46:49], v[162:165], v[198:201], v[46:49]
	v_mfma_f32_16x16x32_bf16 v[38:41], v[154:157], v[206:209], v[38:41]
	v_mfma_f32_16x16x32_bf16 v[30:33], v[162:165], v[206:209], v[30:33]
	v_mfma_f32_16x16x32_bf16 v[22:25], v[154:157], v[214:217], v[22:25]
	v_mfma_f32_16x16x32_bf16 v[14:17], v[162:165], v[214:217], v[14:17]
	v_mfma_f32_16x16x32_bf16 v[62:65], v[158:161], v[194:197], v[62:65]
	v_mfma_f32_16x16x32_bf16 v[58:61], v[170:173], v[194:197], v[58:61]
	v_mfma_f32_16x16x32_bf16 v[54:57], v[158:161], v[202:205], v[54:57]
	v_mfma_f32_16x16x32_bf16 v[46:49], v[170:173], v[202:205], v[46:49]
	v_mfma_f32_16x16x32_bf16 v[38:41], v[158:161], v[210:213], v[38:41]
	v_mfma_f32_16x16x32_bf16 v[30:33], v[170:173], v[210:213], v[30:33]
	v_mfma_f32_16x16x32_bf16 v[22:25], v[158:161], v[218:221], v[22:25]
	v_mfma_f32_16x16x32_bf16 v[14:17], v[170:173], v[218:221], v[14:17]
	v_mfma_f32_16x16x32_bf16 v[50:53], v[174:177], v[190:193], v[50:53]
	v_mfma_f32_16x16x32_bf16 v[42:45], v[182:185], v[190:193], v[42:45]
	v_mfma_f32_16x16x32_bf16 v[34:37], v[174:177], v[198:201], v[34:37]
	v_mfma_f32_16x16x32_bf16 v[26:29], v[182:185], v[198:201], v[26:29]
	v_mfma_f32_16x16x32_bf16 v[18:21], v[174:177], v[206:209], v[18:21]
	v_mfma_f32_16x16x32_bf16 v[10:13], v[182:185], v[206:209], v[10:13]
	v_mfma_f32_16x16x32_bf16 v[6:9], v[174:177], v[214:217], v[6:9]
	v_mfma_f32_16x16x32_bf16 v[2:5], v[182:185], v[214:217], v[2:5]
	v_mfma_f32_16x16x32_bf16 v[50:53], v[178:181], v[194:197], v[50:53]
	v_mfma_f32_16x16x32_bf16 v[42:45], v[186:189], v[194:197], v[42:45]
	v_mfma_f32_16x16x32_bf16 v[34:37], v[178:181], v[202:205], v[34:37]
	v_mfma_f32_16x16x32_bf16 v[26:29], v[186:189], v[202:205], v[26:29]
	v_mfma_f32_16x16x32_bf16 v[18:21], v[178:181], v[210:213], v[18:21]
	v_mfma_f32_16x16x32_bf16 v[10:13], v[186:189], v[210:213], v[10:13]
	v_mfma_f32_16x16x32_bf16 v[6:9], v[178:181], v[218:221], v[6:9]
	v_mfma_f32_16x16x32_bf16 v[2:5], v[186:189], v[218:221], v[2:5]
	s_setprio 0
	s_barrier
	s_add_i32 s50, s50, 2
	s_add_u32 s24, s24, 0x100
	s_addc_u32 s25, s25, 0
	s_add_u32 s48, s48, 0x100
	s_addc_u32 s49, s49, 0
	s_cmp_gt_u32 s50, 29
	s_cbranch_scc0 .LBB0_575
	s_and_b64 vcc, exec, s[12:13]
	s_cbranch_vccz .LBB0_578
	s_barrier

.LBB0_737:
	ds_read_b128 v[146:149], v178
	ds_read_b128 v[150:153], v178 offset:1024
	ds_read_b128 v[154:157], v178 offset:2048
	ds_read_b128 v[158:161], v178 offset:3072
	ds_read_b128 v[182:185], v179
	ds_read_b128 v[186:189], v179 offset:1024
	ds_read_b128 v[190:193], v179 offset:2048
	ds_read_b128 v[194:197], v179 offset:3072
	s_add_u32 s30, s28, 0xfffc0080
	s_addc_u32 s31, s29, -1
	s_cmp_eq_u32 s72, 12
	s_cselect_b32 s35, s21, s31
	s_cselect_b32 s34, s68, s30
	s_cselect_b32 s31, s19, s71
	s_cselect_b32 s30, s69, s70
	s_add_i32 m0, s27, 0xc000
	ds_read_b128 v[198:201], v180
	ds_read_b128 v[202:205], v180 offset:1024
	ds_read_b128 v[206:209], v180 offset:2048
	ds_read_b128 v[210:213], v180 offset:3072
	ds_read_b128 v[214:217], v180 offset:4096
	ds_read_b128 v[218:221], v180 offset:5120
	ds_read_b128 v[222:225], v180 offset:6144
	ds_read_b128 v[226:229], v180 offset:7168
	global_load_lds_dwordx4 v138, s[28:29]
	s_add_i32 m0, s27, 0xe000
	s_nop 0
	global_load_lds_dwordx4 v140, s[28:29]
	s_waitcnt vmcnt(8)
	s_waitcnt lgkmcnt(0)
	s_barrier
	s_setprio 1
	v_mfma_i32_16x16x64_i8 v[126:129], v[146:149], v[198:201], v[126:129]
	v_mfma_i32_16x16x64_i8 v[118:121], v[154:157], v[198:201], v[118:121]
	v_mfma_i32_16x16x64_i8 v[110:113], v[146:149], v[206:209], v[110:113]
	v_mfma_i32_16x16x64_i8 v[102:105], v[154:157], v[206:209], v[102:105]
	v_mfma_i32_16x16x64_i8 v[94:97], v[146:149], v[214:217], v[94:97]
	v_mfma_i32_16x16x64_i8 v[86:89], v[154:157], v[214:217], v[86:89]
	v_mfma_i32_16x16x64_i8 v[78:81], v[146:149], v[222:225], v[78:81]
	v_mfma_i32_16x16x64_i8 v[70:73], v[154:157], v[222:225], v[70:73]
	v_mfma_i32_16x16x64_i8 v[126:129], v[150:153], v[202:205], v[126:129]
	v_mfma_i32_16x16x64_i8 v[118:121], v[158:161], v[202:205], v[118:121]
	v_mfma_i32_16x16x64_i8 v[110:113], v[150:153], v[210:213], v[110:113]
	v_mfma_i32_16x16x64_i8 v[102:105], v[158:161], v[210:213], v[102:105]
	v_mfma_i32_16x16x64_i8 v[94:97], v[150:153], v[218:221], v[94:97]
	v_mfma_i32_16x16x64_i8 v[86:89], v[158:161], v[218:221], v[86:89]
	v_mfma_i32_16x16x64_i8 v[78:81], v[150:153], v[226:229], v[78:81]
	v_mfma_i32_16x16x64_i8 v[70:73], v[158:161], v[226:229], v[70:73]
	v_mfma_i32_16x16x64_i8 v[122:125], v[182:185], v[198:201], v[122:125]
	v_mfma_i32_16x16x64_i8 v[114:117], v[190:193], v[198:201], v[114:117]
	v_mfma_i32_16x16x64_i8 v[106:109], v[182:185], v[206:209], v[106:109]
	v_mfma_i32_16x16x64_i8 v[98:101], v[190:193], v[206:209], v[98:101]
	v_mfma_i32_16x16x64_i8 v[90:93], v[182:185], v[214:217], v[90:93]
	v_mfma_i32_16x16x64_i8 v[82:85], v[190:193], v[214:217], v[82:85]
	v_mfma_i32_16x16x64_i8 v[74:77], v[182:185], v[222:225], v[74:77]
	v_mfma_i32_16x16x64_i8 v[66:69], v[190:193], v[222:225], v[66:69]
	v_mfma_i32_16x16x64_i8 v[122:125], v[186:189], v[202:205], v[122:125]
	v_mfma_i32_16x16x64_i8 v[114:117], v[194:197], v[202:205], v[114:117]
	v_mfma_i32_16x16x64_i8 v[106:109], v[186:189], v[210:213], v[106:109]
	v_mfma_i32_16x16x64_i8 v[98:101], v[194:197], v[210:213], v[98:101]
	v_mfma_i32_16x16x64_i8 v[90:93], v[186:189], v[218:221], v[90:93]
	v_mfma_i32_16x16x64_i8 v[82:85], v[194:197], v[218:221], v[82:85]
	v_mfma_i32_16x16x64_i8 v[74:77], v[186:189], v[226:229], v[74:77]
	v_mfma_i32_16x16x64_i8 v[66:69], v[194:197], v[226:229], v[66:69]
	s_setprio 0
	s_barrier
	s_add_i32 s73, s46, s38
	v_lshl_add_u64 v[162:163], s[30:31], 0, v[134:135]
	s_mov_b32 m0, s73
	ds_read_b128 v[198:201], v180 offset:16384
	ds_read_b128 v[202:205], v180 offset:17408
	ds_read_b128 v[206:209], v180 offset:18432
	ds_read_b128 v[210:213], v180 offset:19456
	ds_read_b128 v[214:217], v180 offset:20480
	ds_read_b128 v[218:221], v180 offset:21504
	ds_read_b128 v[222:225], v180 offset:22528
	ds_read_b128 v[226:229], v180 offset:23552
	global_load_lds_dwordx4 v134, s[30:31]
	s_add_i32 m0, s73, 0x2000
	s_add_u32 s74, s30, 0x40000
	v_lshl_add_u64 v[230:231], s[30:31], 0, v[130:131]
	s_addc_u32 s75, s31, 0
	s_add_i32 s73, s47, s38
	global_load_lds_dwordx4 v130, s[30:31]
	s_mov_b32 m0, s73
	v_lshl_add_u64 v[234:235], s[34:35], 0, v[132:133]
	global_load_lds_dwordx4 v134, s[74:75]
	s_add_i32 m0, s73, 0x2000
	s_nop 0
	global_load_lds_dwordx4 v130, s[74:75]
	v_lshl_add_u64 v[232:233], s[34:35], 0, v[136:137]
	s_mov_b32 m0, s27
	s_nop 0
	global_load_lds_dwordx4 v136, s[34:35]
	s_mov_b32 m0, s40
	s_nop 0
	global_load_lds_dwordx4 v132, s[34:35]
	s_waitcnt vmcnt(8)
	s_waitcnt lgkmcnt(0)
	s_barrier
	s_setprio 1
	v_mfma_i32_16x16x64_i8 v[62:65], v[146:149], v[198:201], v[62:65]
	v_mfma_i32_16x16x64_i8 v[54:57], v[154:157], v[198:201], v[54:57]
	v_mfma_i32_16x16x64_i8 v[46:49], v[146:149], v[206:209], v[46:49]
	v_mfma_i32_16x16x64_i8 v[38:41], v[154:157], v[206:209], v[38:41]
	v_mfma_i32_16x16x64_i8 v[30:33], v[146:149], v[214:217], v[30:33]
	v_mfma_i32_16x16x64_i8 v[22:25], v[154:157], v[214:217], v[22:25]
	v_mfma_i32_16x16x64_i8 v[14:17], v[146:149], v[222:225], v[14:17]
	v_mfma_i32_16x16x64_i8 v[6:9], v[154:157], v[222:225], v[6:9]
	v_mfma_i32_16x16x64_i8 v[62:65], v[150:153], v[202:205], v[62:65]
	v_mfma_i32_16x16x64_i8 v[54:57], v[158:161], v[202:205], v[54:57]
	v_mfma_i32_16x16x64_i8 v[46:49], v[150:153], v[210:213], v[46:49]
	v_mfma_i32_16x16x64_i8 v[38:41], v[158:161], v[210:213], v[38:41]
	v_mfma_i32_16x16x64_i8 v[30:33], v[150:153], v[218:221], v[30:33]
	v_mfma_i32_16x16x64_i8 v[22:25], v[158:161], v[218:221], v[22:25]
	v_mfma_i32_16x16x64_i8 v[14:17], v[150:153], v[226:229], v[14:17]
	v_mfma_i32_16x16x64_i8 v[6:9], v[158:161], v[226:229], v[6:9]
	v_mfma_i32_16x16x64_i8 v[58:61], v[182:185], v[198:201], v[58:61]
	v_mfma_i32_16x16x64_i8 v[50:53], v[190:193], v[198:201], v[50:53]
	v_mfma_i32_16x16x64_i8 v[42:45], v[182:185], v[206:209], v[42:45]
	v_mfma_i32_16x16x64_i8 v[34:37], v[190:193], v[206:209], v[34:37]
	v_mfma_i32_16x16x64_i8 v[26:29], v[182:185], v[214:217], v[26:29]
	v_mfma_i32_16x16x64_i8 v[18:21], v[190:193], v[214:217], v[18:21]
	v_mfma_i32_16x16x64_i8 v[10:13], v[182:185], v[222:225], v[10:13]
	v_mfma_i32_16x16x64_i8 v[2:5], v[190:193], v[222:225], v[2:5]
	v_mfma_i32_16x16x64_i8 v[58:61], v[186:189], v[202:205], v[58:61]
	v_mfma_i32_16x16x64_i8 v[50:53], v[194:197], v[202:205], v[50:53]
	v_mfma_i32_16x16x64_i8 v[42:45], v[186:189], v[210:213], v[42:45]
	v_mfma_i32_16x16x64_i8 v[34:37], v[194:197], v[210:213], v[34:37]
	v_mfma_i32_16x16x64_i8 v[26:29], v[186:189], v[218:221], v[26:29]
	v_mfma_i32_16x16x64_i8 v[18:21], v[194:197], v[218:221], v[18:21]
	v_mfma_i32_16x16x64_i8 v[10:13], v[186:189], v[226:229], v[10:13]
	v_mfma_i32_16x16x64_i8 v[2:5], v[194:197], v[226:229], v[2:5]
	s_setprio 0
	s_barrier
	s_add_i32 s73, 0, 0x18000
	v_add_u32_e32 v158, s73, v169
	ds_read_b128 v[146:149], v158
	ds_read_b128 v[150:153], v158 offset:1024
	ds_read_b128 v[154:157], v158 offset:2048
	ds_read_b128 v[158:161], v158 offset:3072
	ds_read_b128 v[182:185], v181
	ds_read_b128 v[186:189], v181 offset:1024
	ds_read_b128 v[190:193], v181 offset:2048
	ds_read_b128 v[194:197], v181 offset:3072
	s_add_u32 s34, s34, 0x40000
	s_addc_u32 s35, s35, 0
	s_mov_b32 m0, s41
	ds_read_b128 v[198:201], v180 offset:32768
	ds_read_b128 v[202:205], v180 offset:33792
	ds_read_b128 v[206:209], v180 offset:34816
	ds_read_b128 v[210:213], v180 offset:35840
	ds_read_b128 v[214:217], v180 offset:36864
	ds_read_b128 v[218:221], v180 offset:37888
	ds_read_b128 v[222:225], v180 offset:38912
	ds_read_b128 v[226:229], v180 offset:39936
	global_load_lds_dwordx4 v136, s[34:35]
	s_mov_b32 m0, s42
	s_nop 0
	global_load_lds_dwordx4 v132, s[34:35]
	s_waitcnt vmcnt(8)
	s_waitcnt lgkmcnt(0)
	s_barrier
	s_setprio 1
	v_mfma_i32_16x16x64_i8 v[126:129], v[146:149], v[198:201], v[126:129]
	v_mfma_i32_16x16x64_i8 v[118:121], v[154:157], v[198:201], v[118:121]
	v_mfma_i32_16x16x64_i8 v[110:113], v[146:149], v[206:209], v[110:113]
	v_mfma_i32_16x16x64_i8 v[102:105], v[154:157], v[206:209], v[102:105]
	v_mfma_i32_16x16x64_i8 v[94:97], v[146:149], v[214:217], v[94:97]
	v_mfma_i32_16x16x64_i8 v[86:89], v[154:157], v[214:217], v[86:89]
	v_mfma_i32_16x16x64_i8 v[78:81], v[146:149], v[222:225], v[78:81]
	v_mfma_i32_16x16x64_i8 v[70:73], v[154:157], v[222:225], v[70:73]
	v_mfma_i32_16x16x64_i8 v[126:129], v[150:153], v[202:205], v[126:129]
	v_mfma_i32_16x16x64_i8 v[118:121], v[158:161], v[202:205], v[118:121]
	v_mfma_i32_16x16x64_i8 v[110:113], v[150:153], v[210:213], v[110:113]
	v_mfma_i32_16x16x64_i8 v[102:105], v[158:161], v[210:213], v[102:105]
	v_mfma_i32_16x16x64_i8 v[94:97], v[150:153], v[218:221], v[94:97]
	v_mfma_i32_16x16x64_i8 v[86:89], v[158:161], v[218:221], v[86:89]
	v_mfma_i32_16x16x64_i8 v[78:81], v[150:153], v[226:229], v[78:81]
	v_mfma_i32_16x16x64_i8 v[70:73], v[158:161], v[226:229], v[70:73]
	v_mfma_i32_16x16x64_i8 v[122:125], v[182:185], v[198:201], v[122:125]
	v_mfma_i32_16x16x64_i8 v[114:117], v[190:193], v[198:201], v[114:117]
	v_mfma_i32_16x16x64_i8 v[106:109], v[182:185], v[206:209], v[106:109]
	v_mfma_i32_16x16x64_i8 v[98:101], v[190:193], v[206:209], v[98:101]
	v_mfma_i32_16x16x64_i8 v[90:93], v[182:185], v[214:217], v[90:93]
	v_mfma_i32_16x16x64_i8 v[82:85], v[190:193], v[214:217], v[82:85]
	v_mfma_i32_16x16x64_i8 v[74:77], v[182:185], v[222:225], v[74:77]
	v_mfma_i32_16x16x64_i8 v[66:69], v[190:193], v[222:225], v[66:69]
	v_mfma_i32_16x16x64_i8 v[122:125], v[186:189], v[202:205], v[122:125]
	v_mfma_i32_16x16x64_i8 v[114:117], v[194:197], v[202:205], v[114:117]
	v_mfma_i32_16x16x64_i8 v[106:109], v[186:189], v[210:213], v[106:109]
	v_mfma_i32_16x16x64_i8 v[98:101], v[194:197], v[210:213], v[98:101]
	v_mfma_i32_16x16x64_i8 v[90:93], v[186:189], v[218:221], v[90:93]
	v_mfma_i32_16x16x64_i8 v[82:85], v[194:197], v[218:221], v[82:85]
	v_mfma_i32_16x16x64_i8 v[74:77], v[186:189], v[226:229], v[74:77]
	v_mfma_i32_16x16x64_i8 v[66:69], v[194:197], v[226:229], v[66:69]
	s_setprio 0
	s_barrier
	s_add_i32 s34, s73, s38
	v_lshl_add_u64 v[162:163], v[162:163], 0, s[10:11]
	s_mov_b32 m0, s34
	ds_read_b128 v[198:201], v180 offset:49152
	ds_read_b128 v[202:205], v180 offset:50176
	ds_read_b128 v[206:209], v180 offset:51200
	ds_read_b128 v[210:213], v180 offset:52224
	ds_read_b128 v[214:217], v180 offset:53248
	ds_read_b128 v[218:221], v180 offset:54272
	ds_read_b128 v[222:225], v180 offset:55296
	ds_read_b128 v[226:229], v180 offset:56320
	global_load_lds_dwordx4 v[162:163], off
	s_add_i32 m0, s34, 0x2000
	s_add_u32 s30, s30, 0x40080
	v_lshl_add_u64 v[162:163], v[230:231], 0, s[10:11]
	s_addc_u32 s31, s31, 0
	s_add_i32 s34, s48, s38
	global_load_lds_dwordx4 v[162:163], off
	s_mov_b32 m0, s34
	s_nop 0
	global_load_lds_dwordx4 v134, s[30:31]
	s_add_i32 m0, s34, 0x2000
	s_nop 0
	global_load_lds_dwordx4 v130, s[30:31]
	v_lshl_add_u64 v[162:163], v[232:233], 0, s[10:11]
	s_mov_b32 m0, s43
	s_nop 0
	global_load_lds_dwordx4 v[162:163], off
	v_lshl_add_u64 v[162:163], v[234:235], 0, s[10:11]
	s_mov_b32 m0, s44
	s_nop 0
	global_load_lds_dwordx4 v[162:163], off
	s_waitcnt vmcnt(8)
	s_waitcnt lgkmcnt(0)
	s_barrier
	s_setprio 1
	v_mfma_i32_16x16x64_i8 v[62:65], v[146:149], v[198:201], v[62:65]
	v_mfma_i32_16x16x64_i8 v[54:57], v[154:157], v[198:201], v[54:57]
	v_mfma_i32_16x16x64_i8 v[46:49], v[146:149], v[206:209], v[46:49]
	v_mfma_i32_16x16x64_i8 v[38:41], v[154:157], v[206:209], v[38:41]
	v_mfma_i32_16x16x64_i8 v[30:33], v[146:149], v[214:217], v[30:33]
	v_mfma_i32_16x16x64_i8 v[22:25], v[154:157], v[214:217], v[22:25]
	v_mfma_i32_16x16x64_i8 v[14:17], v[146:149], v[222:225], v[14:17]
	v_mfma_i32_16x16x64_i8 v[6:9], v[154:157], v[222:225], v[6:9]
	v_mfma_i32_16x16x64_i8 v[62:65], v[150:153], v[202:205], v[62:65]
	v_mfma_i32_16x16x64_i8 v[54:57], v[158:161], v[202:205], v[54:57]
	v_mfma_i32_16x16x64_i8 v[46:49], v[150:153], v[210:213], v[46:49]
	v_mfma_i32_16x16x64_i8 v[38:41], v[158:161], v[210:213], v[38:41]
	v_mfma_i32_16x16x64_i8 v[30:33], v[150:153], v[218:221], v[30:33]
	v_mfma_i32_16x16x64_i8 v[22:25], v[158:161], v[218:221], v[22:25]
	v_mfma_i32_16x16x64_i8 v[14:17], v[150:153], v[226:229], v[14:17]
	v_mfma_i32_16x16x64_i8 v[6:9], v[158:161], v[226:229], v[6:9]
	v_mfma_i32_16x16x64_i8 v[58:61], v[182:185], v[198:201], v[58:61]
	v_mfma_i32_16x16x64_i8 v[50:53], v[190:193], v[198:201], v[50:53]
	v_mfma_i32_16x16x64_i8 v[42:45], v[182:185], v[206:209], v[42:45]
	v_mfma_i32_16x16x64_i8 v[34:37], v[190:193], v[206:209], v[34:37]
	v_mfma_i32_16x16x64_i8 v[26:29], v[182:185], v[214:217], v[26:29]
	v_mfma_i32_16x16x64_i8 v[18:21], v[190:193], v[214:217], v[18:21]
	v_mfma_i32_16x16x64_i8 v[10:13], v[182:185], v[222:225], v[10:13]
	v_mfma_i32_16x16x64_i8 v[2:5], v[190:193], v[222:225], v[2:5]
	v_mfma_i32_16x16x64_i8 v[58:61], v[186:189], v[202:205], v[58:61]
	v_mfma_i32_16x16x64_i8 v[50:53], v[194:197], v[202:205], v[50:53]
	v_mfma_i32_16x16x64_i8 v[42:45], v[186:189], v[210:213], v[42:45]
	v_mfma_i32_16x16x64_i8 v[34:37], v[194:197], v[210:213], v[34:37]
	v_mfma_i32_16x16x64_i8 v[26:29], v[186:189], v[218:221], v[26:29]
	v_mfma_i32_16x16x64_i8 v[18:21], v[194:197], v[218:221], v[18:21]
	v_mfma_i32_16x16x64_i8 v[10:13], v[186:189], v[226:229], v[10:13]
	v_mfma_i32_16x16x64_i8 v[2:5], v[194:197], v[226:229], v[2:5]
	s_setprio 0
	s_barrier
	s_add_i32 s72, s72, 2
	s_add_u32 s28, s28, 0x100
	s_addc_u32 s29, s29, 0
	s_add_u32 s70, s70, 0x100
	s_addc_u32 s71, s71, 0
	s_cmp_gt_u32 s72, 13
	s_cbranch_scc0 .LBB0_737
	s_and_b64 vcc, exec, s[14:15]
	s_cbranch_vccz .LBB0_740
	s_barrier

.LBB0_846:
	ds_read_b128 v[154:157], v149
	ds_read_b128 v[158:161], v149 offset:1024
	ds_read_b128 v[162:165], v149 offset:2048
	ds_read_b128 v[170:173], v149 offset:3072
	ds_read_b128 v[174:177], v150
	ds_read_b128 v[178:181], v150 offset:1024
	ds_read_b128 v[182:185], v150 offset:2048
	ds_read_b128 v[186:189], v150 offset:3072
	s_add_u32 s20, s18, 0xffea0080
	s_addc_u32 s21, s19, -1
	s_cmpk_eq_i32 s46, 0x54
	s_cselect_b32 s23, s7, s21
	s_cselect_b32 s22, s6, s20
	s_cselect_b32 s21, s17, s45
	s_cselect_b32 s20, s16, s44
	s_add_i32 m0, s26, 0xc000
	ds_read_b128 v[190:193], v151
	ds_read_b128 v[194:197], v151 offset:1024
	ds_read_b128 v[198:201], v151 offset:2048
	ds_read_b128 v[202:205], v151 offset:3072
	ds_read_b128 v[206:209], v151 offset:4096
	ds_read_b128 v[210:213], v151 offset:5120
	ds_read_b128 v[214:217], v151 offset:6144
	ds_read_b128 v[218:221], v151 offset:7168
	global_load_lds_dwordx4 v138, s[18:19]
	s_add_i32 m0, s26, 0xe000
	s_nop 0
	global_load_lds_dwordx4 v140, s[18:19]
	s_waitcnt vmcnt(8)
	s_waitcnt lgkmcnt(0)
	s_barrier
	s_setprio 1
	v_mfma_f32_16x16x32_bf16 v[126:129], v[154:157], v[190:193], v[126:129]
	v_mfma_f32_16x16x32_bf16 v[122:125], v[162:165], v[190:193], v[122:125]
	v_mfma_f32_16x16x32_bf16 v[118:121], v[154:157], v[198:201], v[118:121]
	v_mfma_f32_16x16x32_bf16 v[110:113], v[162:165], v[198:201], v[110:113]
	v_mfma_f32_16x16x32_bf16 v[102:105], v[154:157], v[206:209], v[102:105]
	v_mfma_f32_16x16x32_bf16 v[94:97], v[162:165], v[206:209], v[94:97]
	v_mfma_f32_16x16x32_bf16 v[86:89], v[154:157], v[214:217], v[86:89]
	v_mfma_f32_16x16x32_bf16 v[78:81], v[162:165], v[214:217], v[78:81]
	v_mfma_f32_16x16x32_bf16 v[126:129], v[158:161], v[194:197], v[126:129]
	v_mfma_f32_16x16x32_bf16 v[122:125], v[170:173], v[194:197], v[122:125]
	v_mfma_f32_16x16x32_bf16 v[118:121], v[158:161], v[202:205], v[118:121]
	v_mfma_f32_16x16x32_bf16 v[110:113], v[170:173], v[202:205], v[110:113]
	v_mfma_f32_16x16x32_bf16 v[102:105], v[158:161], v[210:213], v[102:105]
	v_mfma_f32_16x16x32_bf16 v[94:97], v[170:173], v[210:213], v[94:97]
	v_mfma_f32_16x16x32_bf16 v[86:89], v[158:161], v[218:221], v[86:89]
	v_mfma_f32_16x16x32_bf16 v[78:81], v[170:173], v[218:221], v[78:81]
	v_mfma_f32_16x16x32_bf16 v[114:117], v[174:177], v[190:193], v[114:117]
	v_mfma_f32_16x16x32_bf16 v[106:109], v[182:185], v[190:193], v[106:109]
	v_mfma_f32_16x16x32_bf16 v[98:101], v[174:177], v[198:201], v[98:101]
	v_mfma_f32_16x16x32_bf16 v[90:93], v[182:185], v[198:201], v[90:93]
	v_mfma_f32_16x16x32_bf16 v[82:85], v[174:177], v[206:209], v[82:85]
	v_mfma_f32_16x16x32_bf16 v[74:77], v[182:185], v[206:209], v[74:77]
	v_mfma_f32_16x16x32_bf16 v[70:73], v[174:177], v[214:217], v[70:73]
	v_mfma_f32_16x16x32_bf16 v[66:69], v[182:185], v[214:217], v[66:69]
	v_mfma_f32_16x16x32_bf16 v[114:117], v[178:181], v[194:197], v[114:117]
	v_mfma_f32_16x16x32_bf16 v[106:109], v[186:189], v[194:197], v[106:109]
	v_mfma_f32_16x16x32_bf16 v[98:101], v[178:181], v[202:205], v[98:101]
	v_mfma_f32_16x16x32_bf16 v[90:93], v[186:189], v[202:205], v[90:93]
	v_mfma_f32_16x16x32_bf16 v[82:85], v[178:181], v[210:213], v[82:85]
	v_mfma_f32_16x16x32_bf16 v[74:77], v[186:189], v[210:213], v[74:77]
	v_mfma_f32_16x16x32_bf16 v[70:73], v[178:181], v[218:221], v[70:73]
	v_mfma_f32_16x16x32_bf16 v[66:69], v[186:189], v[218:221], v[66:69]
	s_setprio 0
	s_barrier
	s_add_i32 s47, s36, s25
	v_lshl_add_u64 v[146:147], s[20:21], 0, v[132:133]
	s_mov_b32 m0, s47
	ds_read_b128 v[190:193], v151 offset:16384
	ds_read_b128 v[194:197], v151 offset:17408
	ds_read_b128 v[198:201], v151 offset:18432
	ds_read_b128 v[202:205], v151 offset:19456
	ds_read_b128 v[206:209], v151 offset:20480
	ds_read_b128 v[210:213], v151 offset:21504
	ds_read_b128 v[214:217], v151 offset:22528
	ds_read_b128 v[218:221], v151 offset:23552
	global_load_lds_dwordx4 v132, s[20:21]
	s_add_i32 m0, s47, 0x2000
	s_add_u32 s48, s20, 0x160000
	v_lshl_add_u64 v[222:223], s[20:21], 0, v[136:137]
	s_addc_u32 s49, s21, 0
	s_add_i32 s47, s37, s25
	global_load_lds_dwordx4 v136, s[20:21]
	s_mov_b32 m0, s47
	v_lshl_add_u64 v[226:227], s[22:23], 0, v[134:135]
	global_load_lds_dwordx4 v132, s[48:49]
	s_add_i32 m0, s47, 0x2000
	s_nop 0
	global_load_lds_dwordx4 v136, s[48:49]
	v_lshl_add_u64 v[224:225], s[22:23], 0, v[130:131]
	s_mov_b32 m0, s26
	s_nop 0
	global_load_lds_dwordx4 v130, s[22:23]
	s_mov_b32 m0, s27
	s_nop 0
	global_load_lds_dwordx4 v134, s[22:23]
	s_waitcnt vmcnt(8)
	s_waitcnt lgkmcnt(0)
	s_barrier
	s_setprio 1
	v_mfma_f32_16x16x32_bf16 v[62:65], v[154:157], v[190:193], v[62:65]
	v_mfma_f32_16x16x32_bf16 v[58:61], v[162:165], v[190:193], v[58:61]
	v_mfma_f32_16x16x32_bf16 v[54:57], v[154:157], v[198:201], v[54:57]
	v_mfma_f32_16x16x32_bf16 v[46:49], v[162:165], v[198:201], v[46:49]
	v_mfma_f32_16x16x32_bf16 v[38:41], v[154:157], v[206:209], v[38:41]
	v_mfma_f32_16x16x32_bf16 v[30:33], v[162:165], v[206:209], v[30:33]
	v_mfma_f32_16x16x32_bf16 v[22:25], v[154:157], v[214:217], v[22:25]
	v_mfma_f32_16x16x32_bf16 v[14:17], v[162:165], v[214:217], v[14:17]
	v_mfma_f32_16x16x32_bf16 v[62:65], v[158:161], v[194:197], v[62:65]
	v_mfma_f32_16x16x32_bf16 v[58:61], v[170:173], v[194:197], v[58:61]
	v_mfma_f32_16x16x32_bf16 v[54:57], v[158:161], v[202:205], v[54:57]
	v_mfma_f32_16x16x32_bf16 v[46:49], v[170:173], v[202:205], v[46:49]
	v_mfma_f32_16x16x32_bf16 v[38:41], v[158:161], v[210:213], v[38:41]
	v_mfma_f32_16x16x32_bf16 v[30:33], v[170:173], v[210:213], v[30:33]
	v_mfma_f32_16x16x32_bf16 v[22:25], v[158:161], v[218:221], v[22:25]
	v_mfma_f32_16x16x32_bf16 v[14:17], v[170:173], v[218:221], v[14:17]
	v_mfma_f32_16x16x32_bf16 v[50:53], v[174:177], v[190:193], v[50:53]
	v_mfma_f32_16x16x32_bf16 v[42:45], v[182:185], v[190:193], v[42:45]
	v_mfma_f32_16x16x32_bf16 v[34:37], v[174:177], v[198:201], v[34:37]
	v_mfma_f32_16x16x32_bf16 v[26:29], v[182:185], v[198:201], v[26:29]
	v_mfma_f32_16x16x32_bf16 v[18:21], v[174:177], v[206:209], v[18:21]
	v_mfma_f32_16x16x32_bf16 v[10:13], v[182:185], v[206:209], v[10:13]
	v_mfma_f32_16x16x32_bf16 v[6:9], v[174:177], v[214:217], v[6:9]
	v_mfma_f32_16x16x32_bf16 v[2:5], v[182:185], v[214:217], v[2:5]
	v_mfma_f32_16x16x32_bf16 v[50:53], v[178:181], v[194:197], v[50:53]
	v_mfma_f32_16x16x32_bf16 v[42:45], v[186:189], v[194:197], v[42:45]
	v_mfma_f32_16x16x32_bf16 v[34:37], v[178:181], v[202:205], v[34:37]
	v_mfma_f32_16x16x32_bf16 v[26:29], v[186:189], v[202:205], v[26:29]
	v_mfma_f32_16x16x32_bf16 v[18:21], v[178:181], v[210:213], v[18:21]
	v_mfma_f32_16x16x32_bf16 v[10:13], v[186:189], v[210:213], v[10:13]
	v_mfma_f32_16x16x32_bf16 v[6:9], v[178:181], v[218:221], v[6:9]
	v_mfma_f32_16x16x32_bf16 v[2:5], v[186:189], v[218:221], v[2:5]
	s_setprio 0
	s_barrier
	ds_read_b128 v[154:157], v152
	ds_read_b128 v[158:161], v152 offset:1024
	ds_read_b128 v[162:165], v152 offset:2048
	ds_read_b128 v[170:173], v152 offset:3072
	ds_read_b128 v[174:177], v153
	ds_read_b128 v[178:181], v153 offset:1024
	ds_read_b128 v[182:185], v153 offset:2048
	ds_read_b128 v[186:189], v153 offset:3072
	s_add_u32 s22, s22, 0x160000
	s_addc_u32 s23, s23, 0
	s_mov_b32 m0, s28
	ds_read_b128 v[190:193], v151 offset:32768
	ds_read_b128 v[194:197], v151 offset:33792
	ds_read_b128 v[198:201], v151 offset:34816
	ds_read_b128 v[202:205], v151 offset:35840
	ds_read_b128 v[206:209], v151 offset:36864
	ds_read_b128 v[210:213], v151 offset:37888
	ds_read_b128 v[214:217], v151 offset:38912
	ds_read_b128 v[218:221], v151 offset:39936
	global_load_lds_dwordx4 v130, s[22:23]
	s_mov_b32 m0, s29
	s_nop 0
	global_load_lds_dwordx4 v134, s[22:23]
	s_waitcnt vmcnt(8)
	s_waitcnt lgkmcnt(0)
	s_barrier
	s_setprio 1
	v_mfma_f32_16x16x32_bf16 v[126:129], v[154:157], v[190:193], v[126:129]
	v_mfma_f32_16x16x32_bf16 v[122:125], v[162:165], v[190:193], v[122:125]
	v_mfma_f32_16x16x32_bf16 v[118:121], v[154:157], v[198:201], v[118:121]
	v_mfma_f32_16x16x32_bf16 v[110:113], v[162:165], v[198:201], v[110:113]
	v_mfma_f32_16x16x32_bf16 v[102:105], v[154:157], v[206:209], v[102:105]
	v_mfma_f32_16x16x32_bf16 v[94:97], v[162:165], v[206:209], v[94:97]
	v_mfma_f32_16x16x32_bf16 v[86:89], v[154:157], v[214:217], v[86:89]
	v_mfma_f32_16x16x32_bf16 v[78:81], v[162:165], v[214:217], v[78:81]
	v_mfma_f32_16x16x32_bf16 v[126:129], v[158:161], v[194:197], v[126:129]
	v_mfma_f32_16x16x32_bf16 v[122:125], v[170:173], v[194:197], v[122:125]
	v_mfma_f32_16x16x32_bf16 v[118:121], v[158:161], v[202:205], v[118:121]
	v_mfma_f32_16x16x32_bf16 v[110:113], v[170:173], v[202:205], v[110:113]
	v_mfma_f32_16x16x32_bf16 v[102:105], v[158:161], v[210:213], v[102:105]
	v_mfma_f32_16x16x32_bf16 v[94:97], v[170:173], v[210:213], v[94:97]
	v_mfma_f32_16x16x32_bf16 v[86:89], v[158:161], v[218:221], v[86:89]
	v_mfma_f32_16x16x32_bf16 v[78:81], v[170:173], v[218:221], v[78:81]
	v_mfma_f32_16x16x32_bf16 v[114:117], v[174:177], v[190:193], v[114:117]
	v_mfma_f32_16x16x32_bf16 v[106:109], v[182:185], v[190:193], v[106:109]
	v_mfma_f32_16x16x32_bf16 v[98:101], v[174:177], v[198:201], v[98:101]
	v_mfma_f32_16x16x32_bf16 v[90:93], v[182:185], v[198:201], v[90:93]
	v_mfma_f32_16x16x32_bf16 v[82:85], v[174:177], v[206:209], v[82:85]
	v_mfma_f32_16x16x32_bf16 v[74:77], v[182:185], v[206:209], v[74:77]
	v_mfma_f32_16x16x32_bf16 v[70:73], v[174:177], v[214:217], v[70:73]
	v_mfma_f32_16x16x32_bf16 v[66:69], v[182:185], v[214:217], v[66:69]
	v_mfma_f32_16x16x32_bf16 v[114:117], v[178:181], v[194:197], v[114:117]
	v_mfma_f32_16x16x32_bf16 v[106:109], v[186:189], v[194:197], v[106:109]
	v_mfma_f32_16x16x32_bf16 v[98:101], v[178:181], v[202:205], v[98:101]
	v_mfma_f32_16x16x32_bf16 v[90:93], v[186:189], v[202:205], v[90:93]
	v_mfma_f32_16x16x32_bf16 v[82:85], v[178:181], v[210:213], v[82:85]
	v_mfma_f32_16x16x32_bf16 v[74:77], v[186:189], v[210:213], v[74:77]
	v_mfma_f32_16x16x32_bf16 v[70:73], v[178:181], v[218:221], v[70:73]
	v_mfma_f32_16x16x32_bf16 v[66:69], v[186:189], v[218:221], v[66:69]
	s_setprio 0
	s_barrier
	s_add_i32 s22, s38, s25
	v_lshl_add_u64 v[146:147], v[146:147], 0, s[8:9]
	s_mov_b32 m0, s22
	ds_read_b128 v[190:193], v151 offset:49152
	ds_read_b128 v[194:197], v151 offset:50176
	ds_read_b128 v[198:201], v151 offset:51200
	ds_read_b128 v[202:205], v151 offset:52224
	ds_read_b128 v[206:209], v151 offset:53248
	ds_read_b128 v[210:213], v151 offset:54272
	ds_read_b128 v[214:217], v151 offset:55296
	ds_read_b128 v[218:221], v151 offset:56320
	global_load_lds_dwordx4 v[146:147], off
	s_add_i32 m0, s22, 0x2000
	s_add_u32 s20, s20, 0x160080
	v_lshl_add_u64 v[146:147], v[222:223], 0, s[8:9]
	s_addc_u32 s21, s21, 0
	s_add_i32 s22, s39, s25
	global_load_lds_dwordx4 v[146:147], off
	s_mov_b32 m0, s22
	s_nop 0
	global_load_lds_dwordx4 v132, s[20:21]
	s_add_i32 m0, s22, 0x2000
	s_nop 0
	global_load_lds_dwordx4 v136, s[20:21]
	v_lshl_add_u64 v[146:147], v[224:225], 0, s[8:9]
	s_mov_b32 m0, s30
	s_nop 0
	global_load_lds_dwordx4 v[146:147], off
	v_lshl_add_u64 v[146:147], v[226:227], 0, s[8:9]
	s_mov_b32 m0, s31
	s_nop 0
	global_load_lds_dwordx4 v[146:147], off
	s_waitcnt vmcnt(8)
	s_waitcnt lgkmcnt(0)
	s_barrier
	s_setprio 1
	v_mfma_f32_16x16x32_bf16 v[62:65], v[154:157], v[190:193], v[62:65]
	v_mfma_f32_16x16x32_bf16 v[58:61], v[162:165], v[190:193], v[58:61]
	v_mfma_f32_16x16x32_bf16 v[54:57], v[154:157], v[198:201], v[54:57]
	v_mfma_f32_16x16x32_bf16 v[46:49], v[162:165], v[198:201], v[46:49]
	v_mfma_f32_16x16x32_bf16 v[38:41], v[154:157], v[206:209], v[38:41]
	v_mfma_f32_16x16x32_bf16 v[30:33], v[162:165], v[206:209], v[30:33]
	v_mfma_f32_16x16x32_bf16 v[22:25], v[154:157], v[214:217], v[22:25]
	v_mfma_f32_16x16x32_bf16 v[14:17], v[162:165], v[214:217], v[14:17]
	v_mfma_f32_16x16x32_bf16 v[62:65], v[158:161], v[194:197], v[62:65]
	v_mfma_f32_16x16x32_bf16 v[58:61], v[170:173], v[194:197], v[58:61]
	v_mfma_f32_16x16x32_bf16 v[54:57], v[158:161], v[202:205], v[54:57]
	v_mfma_f32_16x16x32_bf16 v[46:49], v[170:173], v[202:205], v[46:49]
	v_mfma_f32_16x16x32_bf16 v[38:41], v[158:161], v[210:213], v[38:41]
	v_mfma_f32_16x16x32_bf16 v[30:33], v[170:173], v[210:213], v[30:33]
	v_mfma_f32_16x16x32_bf16 v[22:25], v[158:161], v[218:221], v[22:25]
	v_mfma_f32_16x16x32_bf16 v[14:17], v[170:173], v[218:221], v[14:17]
	v_mfma_f32_16x16x32_bf16 v[50:53], v[174:177], v[190:193], v[50:53]
	v_mfma_f32_16x16x32_bf16 v[42:45], v[182:185], v[190:193], v[42:45]
	v_mfma_f32_16x16x32_bf16 v[34:37], v[174:177], v[198:201], v[34:37]
	v_mfma_f32_16x16x32_bf16 v[26:29], v[182:185], v[198:201], v[26:29]
	v_mfma_f32_16x16x32_bf16 v[18:21], v[174:177], v[206:209], v[18:21]
	v_mfma_f32_16x16x32_bf16 v[10:13], v[182:185], v[206:209], v[10:13]
	v_mfma_f32_16x16x32_bf16 v[6:9], v[174:177], v[214:217], v[6:9]
	v_mfma_f32_16x16x32_bf16 v[2:5], v[182:185], v[214:217], v[2:5]
	v_mfma_f32_16x16x32_bf16 v[50:53], v[178:181], v[194:197], v[50:53]
	v_mfma_f32_16x16x32_bf16 v[42:45], v[186:189], v[194:197], v[42:45]
	v_mfma_f32_16x16x32_bf16 v[34:37], v[178:181], v[202:205], v[34:37]
	v_mfma_f32_16x16x32_bf16 v[26:29], v[186:189], v[202:205], v[26:29]
	v_mfma_f32_16x16x32_bf16 v[18:21], v[178:181], v[210:213], v[18:21]
	v_mfma_f32_16x16x32_bf16 v[10:13], v[186:189], v[210:213], v[10:13]
	v_mfma_f32_16x16x32_bf16 v[6:9], v[178:181], v[218:221], v[6:9]
	v_mfma_f32_16x16x32_bf16 v[2:5], v[186:189], v[218:221], v[2:5]
	s_setprio 0
	s_barrier
	s_add_i32 s46, s46, 2
	s_add_u32 s18, s18, 0x100
	s_addc_u32 s19, s19, 0
	s_add_u32 s44, s44, 0x100
	s_addc_u32 s45, s45, 0
	s_cmpk_gt_u32 s46, 0x55
	s_cbranch_scc0 .LBB0_846
	s_and_b64 vcc, exec, s[14:15]
	s_cbranch_vccz .LBB0_849
	s_barrier

.LBB0_1262:
	ds_read_b128 v[148:151], v162
	ds_read_b128 v[152:155], v162 offset:1024
	ds_read_b128 v[156:159], v162 offset:2048
	ds_read_b128 v[170:173], v162 offset:3072
	ds_read_b128 v[174:177], v163
	ds_read_b128 v[178:181], v163 offset:1024
	ds_read_b128 v[182:185], v163 offset:2048
	ds_read_b128 v[186:189], v163 offset:3072
	s_add_u32 s26, s24, 0xfff80080
	s_addc_u32 s27, s25, -1
	s_cmp_eq_u32 s69, 28
	s_cselect_b32 s29, s17, s27
	s_cselect_b32 s28, s23, s26
	s_cselect_b32 s27, s15, s68
	s_cselect_b32 s26, s51, s63
	s_add_i32 m0, s35, 0xc000
	ds_read_b128 v[190:193], v164
	ds_read_b128 v[194:197], v164 offset:1024
	ds_read_b128 v[198:201], v164 offset:2048
	ds_read_b128 v[202:205], v164 offset:3072
	ds_read_b128 v[206:209], v164 offset:4096
	ds_read_b128 v[210:213], v164 offset:5120
	ds_read_b128 v[214:217], v164 offset:6144
	ds_read_b128 v[218:221], v164 offset:7168
	global_load_lds_dwordx4 v140, s[24:25]
	s_add_i32 m0, s35, 0xe000
	s_nop 0
	global_load_lds_dwordx4 v142, s[24:25]
	s_waitcnt vmcnt(8)
	s_waitcnt lgkmcnt(0)
	s_barrier
	s_setprio 1
	v_mfma_f32_16x16x32_bf16 v[126:129], v[148:151], v[190:193], v[126:129]
	v_mfma_f32_16x16x32_bf16 v[122:125], v[156:159], v[190:193], v[122:125]
	v_mfma_f32_16x16x32_bf16 v[118:121], v[148:151], v[198:201], v[118:121]
	v_mfma_f32_16x16x32_bf16 v[110:113], v[156:159], v[198:201], v[110:113]
	v_mfma_f32_16x16x32_bf16 v[102:105], v[148:151], v[206:209], v[102:105]
	v_mfma_f32_16x16x32_bf16 v[94:97], v[156:159], v[206:209], v[94:97]
	v_mfma_f32_16x16x32_bf16 v[86:89], v[148:151], v[214:217], v[86:89]
	v_mfma_f32_16x16x32_bf16 v[78:81], v[156:159], v[214:217], v[78:81]
	v_mfma_f32_16x16x32_bf16 v[126:129], v[152:155], v[194:197], v[126:129]
	v_mfma_f32_16x16x32_bf16 v[122:125], v[170:173], v[194:197], v[122:125]
	v_mfma_f32_16x16x32_bf16 v[118:121], v[152:155], v[202:205], v[118:121]
	v_mfma_f32_16x16x32_bf16 v[110:113], v[170:173], v[202:205], v[110:113]
	v_mfma_f32_16x16x32_bf16 v[102:105], v[152:155], v[210:213], v[102:105]
	v_mfma_f32_16x16x32_bf16 v[94:97], v[170:173], v[210:213], v[94:97]
	v_mfma_f32_16x16x32_bf16 v[86:89], v[152:155], v[218:221], v[86:89]
	v_mfma_f32_16x16x32_bf16 v[78:81], v[170:173], v[218:221], v[78:81]
	v_mfma_f32_16x16x32_bf16 v[114:117], v[174:177], v[190:193], v[114:117]
	v_mfma_f32_16x16x32_bf16 v[106:109], v[182:185], v[190:193], v[106:109]
	v_mfma_f32_16x16x32_bf16 v[98:101], v[174:177], v[198:201], v[98:101]
	v_mfma_f32_16x16x32_bf16 v[90:93], v[182:185], v[198:201], v[90:93]
	v_mfma_f32_16x16x32_bf16 v[82:85], v[174:177], v[206:209], v[82:85]
	v_mfma_f32_16x16x32_bf16 v[74:77], v[182:185], v[206:209], v[74:77]
	v_mfma_f32_16x16x32_bf16 v[70:73], v[174:177], v[214:217], v[70:73]
	v_mfma_f32_16x16x32_bf16 v[66:69], v[182:185], v[214:217], v[66:69]
	v_mfma_f32_16x16x32_bf16 v[114:117], v[178:181], v[194:197], v[114:117]
	v_mfma_f32_16x16x32_bf16 v[106:109], v[186:189], v[194:197], v[106:109]
	v_mfma_f32_16x16x32_bf16 v[98:101], v[178:181], v[202:205], v[98:101]
	v_mfma_f32_16x16x32_bf16 v[90:93], v[186:189], v[202:205], v[90:93]
	v_mfma_f32_16x16x32_bf16 v[82:85], v[178:181], v[210:213], v[82:85]
	v_mfma_f32_16x16x32_bf16 v[74:77], v[186:189], v[210:213], v[74:77]
	v_mfma_f32_16x16x32_bf16 v[70:73], v[178:181], v[218:221], v[70:73]
	v_mfma_f32_16x16x32_bf16 v[66:69], v[186:189], v[218:221], v[66:69]
	s_setprio 0
	s_barrier
	s_add_i32 s70, s43, s30
	v_lshl_add_u64 v[222:223], s[26:27], 0, v[134:135]
	s_mov_b32 m0, s70
	ds_read_b128 v[190:193], v164 offset:16384
	ds_read_b128 v[194:197], v164 offset:17408
	ds_read_b128 v[198:201], v164 offset:18432
	ds_read_b128 v[202:205], v164 offset:19456
	ds_read_b128 v[206:209], v164 offset:20480
	ds_read_b128 v[210:213], v164 offset:21504
	ds_read_b128 v[214:217], v164 offset:22528
	ds_read_b128 v[218:221], v164 offset:23552
	global_load_lds_dwordx4 v134, s[26:27]
	s_add_i32 m0, s70, 0x2000
	s_add_u32 s70, s26, 0x80000
	v_lshl_add_u64 v[224:225], s[26:27], 0, v[130:131]
	s_addc_u32 s71, s27, 0
	s_add_i32 s72, s44, s30
	global_load_lds_dwordx4 v130, s[26:27]
	s_mov_b32 m0, s72
	v_lshl_add_u64 v[228:229], s[28:29], 0, v[132:133]
	global_load_lds_dwordx4 v134, s[70:71]
	s_add_i32 m0, s72, 0x2000
	s_nop 0
	global_load_lds_dwordx4 v130, s[70:71]
	v_lshl_add_u64 v[226:227], s[28:29], 0, v[136:137]
	s_mov_b32 m0, s35
	s_nop 0
	global_load_lds_dwordx4 v136, s[28:29]
	s_mov_b32 m0, s36
	s_nop 0
	global_load_lds_dwordx4 v132, s[28:29]
	s_waitcnt vmcnt(8)
	s_waitcnt lgkmcnt(0)
	s_barrier
	s_setprio 1
	v_mfma_f32_16x16x32_bf16 v[62:65], v[148:151], v[190:193], v[62:65]
	v_mfma_f32_16x16x32_bf16 v[58:61], v[156:159], v[190:193], v[58:61]
	v_mfma_f32_16x16x32_bf16 v[50:53], v[148:151], v[198:201], v[50:53]
	v_mfma_f32_16x16x32_bf16 v[42:45], v[156:159], v[198:201], v[42:45]
	v_mfma_f32_16x16x32_bf16 v[38:41], v[148:151], v[206:209], v[38:41]
	v_mfma_f32_16x16x32_bf16 v[30:33], v[156:159], v[206:209], v[30:33]
	v_mfma_f32_16x16x32_bf16 v[22:25], v[148:151], v[214:217], v[22:25]
	v_mfma_f32_16x16x32_bf16 v[14:17], v[156:159], v[214:217], v[14:17]
	v_mfma_f32_16x16x32_bf16 v[62:65], v[152:155], v[194:197], v[62:65]
	v_mfma_f32_16x16x32_bf16 v[58:61], v[170:173], v[194:197], v[58:61]
	v_mfma_f32_16x16x32_bf16 v[50:53], v[152:155], v[202:205], v[50:53]
	v_mfma_f32_16x16x32_bf16 v[42:45], v[170:173], v[202:205], v[42:45]
	v_mfma_f32_16x16x32_bf16 v[38:41], v[152:155], v[210:213], v[38:41]
	v_mfma_f32_16x16x32_bf16 v[30:33], v[170:173], v[210:213], v[30:33]
	v_mfma_f32_16x16x32_bf16 v[22:25], v[152:155], v[218:221], v[22:25]
	v_mfma_f32_16x16x32_bf16 v[14:17], v[170:173], v[218:221], v[14:17]
	v_mfma_f32_16x16x32_bf16 v[54:57], v[174:177], v[190:193], v[54:57]
	v_mfma_f32_16x16x32_bf16 v[46:49], v[182:185], v[190:193], v[46:49]
	v_mfma_f32_16x16x32_bf16 v[34:37], v[174:177], v[198:201], v[34:37]
	v_mfma_f32_16x16x32_bf16 v[26:29], v[182:185], v[198:201], v[26:29]
	v_mfma_f32_16x16x32_bf16 v[18:21], v[174:177], v[206:209], v[18:21]
	v_mfma_f32_16x16x32_bf16 v[10:13], v[182:185], v[206:209], v[10:13]
	v_mfma_f32_16x16x32_bf16 v[6:9], v[174:177], v[214:217], v[6:9]
	v_mfma_f32_16x16x32_bf16 v[2:5], v[182:185], v[214:217], v[2:5]
	v_mfma_f32_16x16x32_bf16 v[54:57], v[178:181], v[194:197], v[54:57]
	v_mfma_f32_16x16x32_bf16 v[46:49], v[186:189], v[194:197], v[46:49]
	v_mfma_f32_16x16x32_bf16 v[34:37], v[178:181], v[202:205], v[34:37]
	v_mfma_f32_16x16x32_bf16 v[26:29], v[186:189], v[202:205], v[26:29]
	v_mfma_f32_16x16x32_bf16 v[18:21], v[178:181], v[210:213], v[18:21]
	v_mfma_f32_16x16x32_bf16 v[10:13], v[186:189], v[210:213], v[10:13]
	v_mfma_f32_16x16x32_bf16 v[6:9], v[178:181], v[218:221], v[6:9]
	v_mfma_f32_16x16x32_bf16 v[2:5], v[186:189], v[218:221], v[2:5]
	s_setprio 0
	s_barrier
	ds_read_b128 v[148:151], v165
	ds_read_b128 v[152:155], v165 offset:1024
	ds_read_b128 v[156:159], v165 offset:2048
	ds_read_b128 v[170:173], v165 offset:3072
	ds_read_b128 v[174:177], v169
	ds_read_b128 v[178:181], v169 offset:1024
	ds_read_b128 v[182:185], v169 offset:2048
	ds_read_b128 v[186:189], v169 offset:3072
	s_add_u32 s28, s28, 0x80000
	s_addc_u32 s29, s29, 0
	s_mov_b32 m0, s37
	ds_read_b128 v[190:193], v164 offset:32768
	ds_read_b128 v[194:197], v164 offset:33792
	ds_read_b128 v[198:201], v164 offset:34816
	ds_read_b128 v[202:205], v164 offset:35840
	ds_read_b128 v[206:209], v164 offset:36864
	ds_read_b128 v[210:213], v164 offset:37888
	ds_read_b128 v[214:217], v164 offset:38912
	ds_read_b128 v[218:221], v164 offset:39936
	global_load_lds_dwordx4 v136, s[28:29]
	s_mov_b32 m0, s38
	s_nop 0
	global_load_lds_dwordx4 v132, s[28:29]
	s_waitcnt vmcnt(8)
	s_waitcnt lgkmcnt(0)
	s_barrier
	s_setprio 1
	v_mfma_f32_16x16x32_bf16 v[126:129], v[148:151], v[190:193], v[126:129]
	v_mfma_f32_16x16x32_bf16 v[122:125], v[156:159], v[190:193], v[122:125]
	v_mfma_f32_16x16x32_bf16 v[118:121], v[148:151], v[198:201], v[118:121]
	v_mfma_f32_16x16x32_bf16 v[110:113], v[156:159], v[198:201], v[110:113]
	v_mfma_f32_16x16x32_bf16 v[102:105], v[148:151], v[206:209], v[102:105]
	v_mfma_f32_16x16x32_bf16 v[94:97], v[156:159], v[206:209], v[94:97]
	v_mfma_f32_16x16x32_bf16 v[86:89], v[148:151], v[214:217], v[86:89]
	v_mfma_f32_16x16x32_bf16 v[78:81], v[156:159], v[214:217], v[78:81]
	v_mfma_f32_16x16x32_bf16 v[126:129], v[152:155], v[194:197], v[126:129]
	v_mfma_f32_16x16x32_bf16 v[122:125], v[170:173], v[194:197], v[122:125]
	v_mfma_f32_16x16x32_bf16 v[118:121], v[152:155], v[202:205], v[118:121]
	v_mfma_f32_16x16x32_bf16 v[110:113], v[170:173], v[202:205], v[110:113]
	v_mfma_f32_16x16x32_bf16 v[102:105], v[152:155], v[210:213], v[102:105]
	v_mfma_f32_16x16x32_bf16 v[94:97], v[170:173], v[210:213], v[94:97]
	v_mfma_f32_16x16x32_bf16 v[86:89], v[152:155], v[218:221], v[86:89]
	v_mfma_f32_16x16x32_bf16 v[78:81], v[170:173], v[218:221], v[78:81]
	v_mfma_f32_16x16x32_bf16 v[114:117], v[174:177], v[190:193], v[114:117]
	v_mfma_f32_16x16x32_bf16 v[106:109], v[182:185], v[190:193], v[106:109]
	v_mfma_f32_16x16x32_bf16 v[98:101], v[174:177], v[198:201], v[98:101]
	v_mfma_f32_16x16x32_bf16 v[90:93], v[182:185], v[198:201], v[90:93]
	v_mfma_f32_16x16x32_bf16 v[82:85], v[174:177], v[206:209], v[82:85]
	v_mfma_f32_16x16x32_bf16 v[74:77], v[182:185], v[206:209], v[74:77]
	v_mfma_f32_16x16x32_bf16 v[70:73], v[174:177], v[214:217], v[70:73]
	v_mfma_f32_16x16x32_bf16 v[66:69], v[182:185], v[214:217], v[66:69]
	v_mfma_f32_16x16x32_bf16 v[114:117], v[178:181], v[194:197], v[114:117]
	v_mfma_f32_16x16x32_bf16 v[106:109], v[186:189], v[194:197], v[106:109]
	v_mfma_f32_16x16x32_bf16 v[98:101], v[178:181], v[202:205], v[98:101]
	v_mfma_f32_16x16x32_bf16 v[90:93], v[186:189], v[202:205], v[90:93]
	v_mfma_f32_16x16x32_bf16 v[82:85], v[178:181], v[210:213], v[82:85]
	v_mfma_f32_16x16x32_bf16 v[74:77], v[186:189], v[210:213], v[74:77]
	v_mfma_f32_16x16x32_bf16 v[70:73], v[178:181], v[218:221], v[70:73]
	v_mfma_f32_16x16x32_bf16 v[66:69], v[186:189], v[218:221], v[66:69]
	s_setprio 0
	s_barrier
	s_add_i32 s28, s45, s30
	v_lshl_add_u64 v[222:223], v[222:223], 0, s[8:9]
	s_mov_b32 m0, s28
	ds_read_b128 v[190:193], v164 offset:49152
	ds_read_b128 v[194:197], v164 offset:50176
	ds_read_b128 v[198:201], v164 offset:51200
	ds_read_b128 v[202:205], v164 offset:52224
	ds_read_b128 v[206:209], v164 offset:53248
	ds_read_b128 v[210:213], v164 offset:54272
	ds_read_b128 v[214:217], v164 offset:55296
	ds_read_b128 v[218:221], v164 offset:56320
	global_load_lds_dwordx4 v[222:223], off
	s_add_i32 m0, s28, 0x2000
	s_add_u32 s26, s26, 0x80080
	v_lshl_add_u64 v[222:223], v[224:225], 0, s[8:9]
	s_addc_u32 s27, s27, 0
	s_add_i32 s28, s46, s30
	global_load_lds_dwordx4 v[222:223], off
	s_mov_b32 m0, s28
	s_nop 0
	global_load_lds_dwordx4 v134, s[26:27]
	s_add_i32 m0, s28, 0x2000
	s_nop 0
	global_load_lds_dwordx4 v130, s[26:27]
	v_lshl_add_u64 v[222:223], v[226:227], 0, s[8:9]
	s_mov_b32 m0, s39
	s_nop 0
	global_load_lds_dwordx4 v[222:223], off
	v_lshl_add_u64 v[222:223], v[228:229], 0, s[8:9]
	s_mov_b32 m0, s40
	s_nop 0
	global_load_lds_dwordx4 v[222:223], off
	s_waitcnt vmcnt(8)
	s_waitcnt lgkmcnt(0)
	s_barrier
	s_setprio 1
	v_mfma_f32_16x16x32_bf16 v[62:65], v[148:151], v[190:193], v[62:65]
	v_mfma_f32_16x16x32_bf16 v[58:61], v[156:159], v[190:193], v[58:61]
	v_mfma_f32_16x16x32_bf16 v[50:53], v[148:151], v[198:201], v[50:53]
	v_mfma_f32_16x16x32_bf16 v[42:45], v[156:159], v[198:201], v[42:45]
	v_mfma_f32_16x16x32_bf16 v[38:41], v[148:151], v[206:209], v[38:41]
	v_mfma_f32_16x16x32_bf16 v[30:33], v[156:159], v[206:209], v[30:33]
	v_mfma_f32_16x16x32_bf16 v[22:25], v[148:151], v[214:217], v[22:25]
	v_mfma_f32_16x16x32_bf16 v[14:17], v[156:159], v[214:217], v[14:17]
	v_mfma_f32_16x16x32_bf16 v[62:65], v[152:155], v[194:197], v[62:65]
	v_mfma_f32_16x16x32_bf16 v[58:61], v[170:173], v[194:197], v[58:61]
	v_mfma_f32_16x16x32_bf16 v[50:53], v[152:155], v[202:205], v[50:53]
	v_mfma_f32_16x16x32_bf16 v[42:45], v[170:173], v[202:205], v[42:45]
	v_mfma_f32_16x16x32_bf16 v[38:41], v[152:155], v[210:213], v[38:41]
	v_mfma_f32_16x16x32_bf16 v[30:33], v[170:173], v[210:213], v[30:33]
	v_mfma_f32_16x16x32_bf16 v[22:25], v[152:155], v[218:221], v[22:25]
	v_mfma_f32_16x16x32_bf16 v[14:17], v[170:173], v[218:221], v[14:17]
	v_mfma_f32_16x16x32_bf16 v[54:57], v[174:177], v[190:193], v[54:57]
	v_mfma_f32_16x16x32_bf16 v[46:49], v[182:185], v[190:193], v[46:49]
	v_mfma_f32_16x16x32_bf16 v[34:37], v[174:177], v[198:201], v[34:37]
	v_mfma_f32_16x16x32_bf16 v[26:29], v[182:185], v[198:201], v[26:29]
	v_mfma_f32_16x16x32_bf16 v[18:21], v[174:177], v[206:209], v[18:21]
	v_mfma_f32_16x16x32_bf16 v[10:13], v[182:185], v[206:209], v[10:13]
	v_mfma_f32_16x16x32_bf16 v[6:9], v[174:177], v[214:217], v[6:9]
	v_mfma_f32_16x16x32_bf16 v[2:5], v[182:185], v[214:217], v[2:5]
	v_mfma_f32_16x16x32_bf16 v[54:57], v[178:181], v[194:197], v[54:57]
	v_mfma_f32_16x16x32_bf16 v[46:49], v[186:189], v[194:197], v[46:49]
	v_mfma_f32_16x16x32_bf16 v[34:37], v[178:181], v[202:205], v[34:37]
	v_mfma_f32_16x16x32_bf16 v[26:29], v[186:189], v[202:205], v[26:29]
	v_mfma_f32_16x16x32_bf16 v[18:21], v[178:181], v[210:213], v[18:21]
	v_mfma_f32_16x16x32_bf16 v[10:13], v[186:189], v[210:213], v[10:13]
	v_mfma_f32_16x16x32_bf16 v[6:9], v[178:181], v[218:221], v[6:9]
	v_mfma_f32_16x16x32_bf16 v[2:5], v[186:189], v[218:221], v[2:5]
	s_setprio 0
	s_barrier
	s_add_i32 s69, s69, 2
	s_add_u32 s24, s24, 0x100
	s_addc_u32 s25, s25, 0
	s_add_u32 s63, s63, 0x100
	s_addc_u32 s68, s68, 0
	s_cmp_gt_u32 s69, 29
	s_cbranch_scc0 .LBB0_1262
	s_and_b64 vcc, exec, s[12:13]
	s_cbranch_vccz .LBB0_1265
	s_barrier

.LBB0_1433:
	ds_read_b128 v[154:157], v149
	ds_read_b128 v[158:161], v149 offset:1024
	ds_read_b128 v[162:165], v149 offset:2048
	ds_read_b128 v[170:173], v149 offset:3072
	ds_read_b128 v[174:177], v150
	ds_read_b128 v[178:181], v150 offset:1024
	ds_read_b128 v[182:185], v150 offset:2048
	ds_read_b128 v[186:189], v150 offset:3072
	s_add_u32 s28, s26, 0xfff80080
	s_addc_u32 s29, s27, -1
	s_cmp_eq_u32 s52, 28
	s_cselect_b32 s31, s17, s29
	s_cselect_b32 s30, s48, s28
	s_cselect_b32 s29, s15, s51
	s_cselect_b32 s28, s49, s50
	s_add_i32 m0, s25, 0xc000
	ds_read_b128 v[190:193], v151
	ds_read_b128 v[194:197], v151 offset:1024
	ds_read_b128 v[198:201], v151 offset:2048
	ds_read_b128 v[202:205], v151 offset:3072
	ds_read_b128 v[206:209], v151 offset:4096
	ds_read_b128 v[210:213], v151 offset:5120
	ds_read_b128 v[214:217], v151 offset:6144
	ds_read_b128 v[218:221], v151 offset:7168
	global_load_lds_dwordx4 v138, s[26:27]
	s_add_i32 m0, s25, 0xe000
	s_nop 0
	global_load_lds_dwordx4 v140, s[26:27]
	s_waitcnt vmcnt(8)
	s_waitcnt lgkmcnt(0)
	s_barrier
	s_setprio 1
	v_mfma_f32_16x16x32_bf16 v[126:129], v[154:157], v[190:193], v[126:129]
	v_mfma_f32_16x16x32_bf16 v[122:125], v[162:165], v[190:193], v[122:125]
	v_mfma_f32_16x16x32_bf16 v[118:121], v[154:157], v[198:201], v[118:121]
	v_mfma_f32_16x16x32_bf16 v[110:113], v[162:165], v[198:201], v[110:113]
	v_mfma_f32_16x16x32_bf16 v[102:105], v[154:157], v[206:209], v[102:105]
	v_mfma_f32_16x16x32_bf16 v[94:97], v[162:165], v[206:209], v[94:97]
	v_mfma_f32_16x16x32_bf16 v[86:89], v[154:157], v[214:217], v[86:89]
	v_mfma_f32_16x16x32_bf16 v[78:81], v[162:165], v[214:217], v[78:81]
	v_mfma_f32_16x16x32_bf16 v[126:129], v[158:161], v[194:197], v[126:129]
	v_mfma_f32_16x16x32_bf16 v[122:125], v[170:173], v[194:197], v[122:125]
	v_mfma_f32_16x16x32_bf16 v[118:121], v[158:161], v[202:205], v[118:121]
	v_mfma_f32_16x16x32_bf16 v[110:113], v[170:173], v[202:205], v[110:113]
	v_mfma_f32_16x16x32_bf16 v[102:105], v[158:161], v[210:213], v[102:105]
	v_mfma_f32_16x16x32_bf16 v[94:97], v[170:173], v[210:213], v[94:97]
	v_mfma_f32_16x16x32_bf16 v[86:89], v[158:161], v[218:221], v[86:89]
	v_mfma_f32_16x16x32_bf16 v[78:81], v[170:173], v[218:221], v[78:81]
	v_mfma_f32_16x16x32_bf16 v[114:117], v[174:177], v[190:193], v[114:117]
	v_mfma_f32_16x16x32_bf16 v[106:109], v[182:185], v[190:193], v[106:109]
	v_mfma_f32_16x16x32_bf16 v[98:101], v[174:177], v[198:201], v[98:101]
	v_mfma_f32_16x16x32_bf16 v[90:93], v[182:185], v[198:201], v[90:93]
	v_mfma_f32_16x16x32_bf16 v[82:85], v[174:177], v[206:209], v[82:85]
	v_mfma_f32_16x16x32_bf16 v[74:77], v[182:185], v[206:209], v[74:77]
	v_mfma_f32_16x16x32_bf16 v[70:73], v[174:177], v[214:217], v[70:73]
	v_mfma_f32_16x16x32_bf16 v[66:69], v[182:185], v[214:217], v[66:69]
	v_mfma_f32_16x16x32_bf16 v[114:117], v[178:181], v[194:197], v[114:117]
	v_mfma_f32_16x16x32_bf16 v[106:109], v[186:189], v[194:197], v[106:109]
	v_mfma_f32_16x16x32_bf16 v[98:101], v[178:181], v[202:205], v[98:101]
	v_mfma_f32_16x16x32_bf16 v[90:93], v[186:189], v[202:205], v[90:93]
	v_mfma_f32_16x16x32_bf16 v[82:85], v[178:181], v[210:213], v[82:85]
	v_mfma_f32_16x16x32_bf16 v[74:77], v[186:189], v[210:213], v[74:77]
	v_mfma_f32_16x16x32_bf16 v[70:73], v[178:181], v[218:221], v[70:73]
	v_mfma_f32_16x16x32_bf16 v[66:69], v[186:189], v[218:221], v[66:69]
	s_setprio 0
	s_barrier
	s_add_i32 s53, s43, s35
	v_lshl_add_u64 v[146:147], s[28:29], 0, v[132:133]
	s_mov_b32 m0, s53
	ds_read_b128 v[190:193], v151 offset:16384
	ds_read_b128 v[194:197], v151 offset:17408
	ds_read_b128 v[198:201], v151 offset:18432
	ds_read_b128 v[202:205], v151 offset:19456
	ds_read_b128 v[206:209], v151 offset:20480
	ds_read_b128 v[210:213], v151 offset:21504
	ds_read_b128 v[214:217], v151 offset:22528
	ds_read_b128 v[218:221], v151 offset:23552
	global_load_lds_dwordx4 v132, s[28:29]
	s_add_i32 m0, s53, 0x2000
	s_add_u32 s68, s28, 0x80000
	v_lshl_add_u64 v[222:223], s[28:29], 0, v[136:137]
	s_addc_u32 s69, s29, 0
	s_add_i32 s53, s44, s35
	global_load_lds_dwordx4 v136, s[28:29]
	s_mov_b32 m0, s53
	v_lshl_add_u64 v[226:227], s[30:31], 0, v[134:135]
	global_load_lds_dwordx4 v132, s[68:69]
	s_add_i32 m0, s53, 0x2000
	s_nop 0
	global_load_lds_dwordx4 v136, s[68:69]
	v_lshl_add_u64 v[224:225], s[30:31], 0, v[130:131]
	s_mov_b32 m0, s25
	s_nop 0
	global_load_lds_dwordx4 v130, s[30:31]
	s_mov_b32 m0, s36
	s_nop 0
	global_load_lds_dwordx4 v134, s[30:31]
	s_waitcnt vmcnt(8)
	s_waitcnt lgkmcnt(0)
	s_barrier
	s_setprio 1
	v_mfma_f32_16x16x32_bf16 v[62:65], v[154:157], v[190:193], v[62:65]
	v_mfma_f32_16x16x32_bf16 v[58:61], v[162:165], v[190:193], v[58:61]
	v_mfma_f32_16x16x32_bf16 v[54:57], v[154:157], v[198:201], v[54:57]
	v_mfma_f32_16x16x32_bf16 v[46:49], v[162:165], v[198:201], v[46:49]
	v_mfma_f32_16x16x32_bf16 v[38:41], v[154:157], v[206:209], v[38:41]
	v_mfma_f32_16x16x32_bf16 v[30:33], v[162:165], v[206:209], v[30:33]
	v_mfma_f32_16x16x32_bf16 v[22:25], v[154:157], v[214:217], v[22:25]
	v_mfma_f32_16x16x32_bf16 v[14:17], v[162:165], v[214:217], v[14:17]
	v_mfma_f32_16x16x32_bf16 v[62:65], v[158:161], v[194:197], v[62:65]
	v_mfma_f32_16x16x32_bf16 v[58:61], v[170:173], v[194:197], v[58:61]
	v_mfma_f32_16x16x32_bf16 v[54:57], v[158:161], v[202:205], v[54:57]
	v_mfma_f32_16x16x32_bf16 v[46:49], v[170:173], v[202:205], v[46:49]
	v_mfma_f32_16x16x32_bf16 v[38:41], v[158:161], v[210:213], v[38:41]
	v_mfma_f32_16x16x32_bf16 v[30:33], v[170:173], v[210:213], v[30:33]
	v_mfma_f32_16x16x32_bf16 v[22:25], v[158:161], v[218:221], v[22:25]
	v_mfma_f32_16x16x32_bf16 v[14:17], v[170:173], v[218:221], v[14:17]
	v_mfma_f32_16x16x32_bf16 v[50:53], v[174:177], v[190:193], v[50:53]
	v_mfma_f32_16x16x32_bf16 v[42:45], v[182:185], v[190:193], v[42:45]
	v_mfma_f32_16x16x32_bf16 v[34:37], v[174:177], v[198:201], v[34:37]
	v_mfma_f32_16x16x32_bf16 v[26:29], v[182:185], v[198:201], v[26:29]
	v_mfma_f32_16x16x32_bf16 v[18:21], v[174:177], v[206:209], v[18:21]
	v_mfma_f32_16x16x32_bf16 v[10:13], v[182:185], v[206:209], v[10:13]
	v_mfma_f32_16x16x32_bf16 v[6:9], v[174:177], v[214:217], v[6:9]
	v_mfma_f32_16x16x32_bf16 v[2:5], v[182:185], v[214:217], v[2:5]
	v_mfma_f32_16x16x32_bf16 v[50:53], v[178:181], v[194:197], v[50:53]
	v_mfma_f32_16x16x32_bf16 v[42:45], v[186:189], v[194:197], v[42:45]
	v_mfma_f32_16x16x32_bf16 v[34:37], v[178:181], v[202:205], v[34:37]
	v_mfma_f32_16x16x32_bf16 v[26:29], v[186:189], v[202:205], v[26:29]
	v_mfma_f32_16x16x32_bf16 v[18:21], v[178:181], v[210:213], v[18:21]
	v_mfma_f32_16x16x32_bf16 v[10:13], v[186:189], v[210:213], v[10:13]
	v_mfma_f32_16x16x32_bf16 v[6:9], v[178:181], v[218:221], v[6:9]
	v_mfma_f32_16x16x32_bf16 v[2:5], v[186:189], v[218:221], v[2:5]
	s_setprio 0
	s_barrier
	ds_read_b128 v[154:157], v152
	ds_read_b128 v[158:161], v152 offset:1024
	ds_read_b128 v[162:165], v152 offset:2048
	ds_read_b128 v[170:173], v152 offset:3072
	ds_read_b128 v[174:177], v153
	ds_read_b128 v[178:181], v153 offset:1024
	ds_read_b128 v[182:185], v153 offset:2048
	ds_read_b128 v[186:189], v153 offset:3072
	s_add_u32 s30, s30, 0x80000
	s_addc_u32 s31, s31, 0
	s_mov_b32 m0, s37
	ds_read_b128 v[190:193], v151 offset:32768
	ds_read_b128 v[194:197], v151 offset:33792
	ds_read_b128 v[198:201], v151 offset:34816
	ds_read_b128 v[202:205], v151 offset:35840
	ds_read_b128 v[206:209], v151 offset:36864
	ds_read_b128 v[210:213], v151 offset:37888
	ds_read_b128 v[214:217], v151 offset:38912
	ds_read_b128 v[218:221], v151 offset:39936
	global_load_lds_dwordx4 v130, s[30:31]
	s_mov_b32 m0, s38
	s_nop 0
	global_load_lds_dwordx4 v134, s[30:31]
	s_waitcnt vmcnt(8)
	s_waitcnt lgkmcnt(0)
	s_barrier
	s_setprio 1
	v_mfma_f32_16x16x32_bf16 v[126:129], v[154:157], v[190:193], v[126:129]
	v_mfma_f32_16x16x32_bf16 v[122:125], v[162:165], v[190:193], v[122:125]
	v_mfma_f32_16x16x32_bf16 v[118:121], v[154:157], v[198:201], v[118:121]
	v_mfma_f32_16x16x32_bf16 v[110:113], v[162:165], v[198:201], v[110:113]
	v_mfma_f32_16x16x32_bf16 v[102:105], v[154:157], v[206:209], v[102:105]
	v_mfma_f32_16x16x32_bf16 v[94:97], v[162:165], v[206:209], v[94:97]
	v_mfma_f32_16x16x32_bf16 v[86:89], v[154:157], v[214:217], v[86:89]
	v_mfma_f32_16x16x32_bf16 v[78:81], v[162:165], v[214:217], v[78:81]
	v_mfma_f32_16x16x32_bf16 v[126:129], v[158:161], v[194:197], v[126:129]
	v_mfma_f32_16x16x32_bf16 v[122:125], v[170:173], v[194:197], v[122:125]
	v_mfma_f32_16x16x32_bf16 v[118:121], v[158:161], v[202:205], v[118:121]
	v_mfma_f32_16x16x32_bf16 v[110:113], v[170:173], v[202:205], v[110:113]
	v_mfma_f32_16x16x32_bf16 v[102:105], v[158:161], v[210:213], v[102:105]
	v_mfma_f32_16x16x32_bf16 v[94:97], v[170:173], v[210:213], v[94:97]
	v_mfma_f32_16x16x32_bf16 v[86:89], v[158:161], v[218:221], v[86:89]
	v_mfma_f32_16x16x32_bf16 v[78:81], v[170:173], v[218:221], v[78:81]
	v_mfma_f32_16x16x32_bf16 v[114:117], v[174:177], v[190:193], v[114:117]
	v_mfma_f32_16x16x32_bf16 v[106:109], v[182:185], v[190:193], v[106:109]
	v_mfma_f32_16x16x32_bf16 v[98:101], v[174:177], v[198:201], v[98:101]
	v_mfma_f32_16x16x32_bf16 v[90:93], v[182:185], v[198:201], v[90:93]
	v_mfma_f32_16x16x32_bf16 v[82:85], v[174:177], v[206:209], v[82:85]
	v_mfma_f32_16x16x32_bf16 v[74:77], v[182:185], v[206:209], v[74:77]
	v_mfma_f32_16x16x32_bf16 v[70:73], v[174:177], v[214:217], v[70:73]
	v_mfma_f32_16x16x32_bf16 v[66:69], v[182:185], v[214:217], v[66:69]
	v_mfma_f32_16x16x32_bf16 v[114:117], v[178:181], v[194:197], v[114:117]
	v_mfma_f32_16x16x32_bf16 v[106:109], v[186:189], v[194:197], v[106:109]
	v_mfma_f32_16x16x32_bf16 v[98:101], v[178:181], v[202:205], v[98:101]
	v_mfma_f32_16x16x32_bf16 v[90:93], v[186:189], v[202:205], v[90:93]
	v_mfma_f32_16x16x32_bf16 v[82:85], v[178:181], v[210:213], v[82:85]
	v_mfma_f32_16x16x32_bf16 v[74:77], v[186:189], v[210:213], v[74:77]
	v_mfma_f32_16x16x32_bf16 v[70:73], v[178:181], v[218:221], v[70:73]
	v_mfma_f32_16x16x32_bf16 v[66:69], v[186:189], v[218:221], v[66:69]
	s_setprio 0
	s_barrier
	s_add_i32 s30, s45, s35
	v_lshl_add_u64 v[146:147], v[146:147], 0, s[8:9]
	s_mov_b32 m0, s30
	ds_read_b128 v[190:193], v151 offset:49152
	ds_read_b128 v[194:197], v151 offset:50176
	ds_read_b128 v[198:201], v151 offset:51200
	ds_read_b128 v[202:205], v151 offset:52224
	ds_read_b128 v[206:209], v151 offset:53248
	ds_read_b128 v[210:213], v151 offset:54272
	ds_read_b128 v[214:217], v151 offset:55296
	ds_read_b128 v[218:221], v151 offset:56320
	global_load_lds_dwordx4 v[146:147], off
	s_add_i32 m0, s30, 0x2000
	s_add_u32 s28, s28, 0x80080
	v_lshl_add_u64 v[146:147], v[222:223], 0, s[8:9]
	s_addc_u32 s29, s29, 0
	s_add_i32 s30, s46, s35
	global_load_lds_dwordx4 v[146:147], off
	s_mov_b32 m0, s30
	s_nop 0
	global_load_lds_dwordx4 v132, s[28:29]
	s_add_i32 m0, s30, 0x2000
	s_nop 0
	global_load_lds_dwordx4 v136, s[28:29]
	v_lshl_add_u64 v[146:147], v[224:225], 0, s[8:9]
	s_mov_b32 m0, s39
	s_nop 0
	global_load_lds_dwordx4 v[146:147], off
	v_lshl_add_u64 v[146:147], v[226:227], 0, s[8:9]
	s_mov_b32 m0, s40
	s_nop 0
	global_load_lds_dwordx4 v[146:147], off
	s_waitcnt vmcnt(8)
	s_waitcnt lgkmcnt(0)
	s_barrier
	s_setprio 1
	v_mfma_f32_16x16x32_bf16 v[62:65], v[154:157], v[190:193], v[62:65]
	v_mfma_f32_16x16x32_bf16 v[58:61], v[162:165], v[190:193], v[58:61]
	v_mfma_f32_16x16x32_bf16 v[54:57], v[154:157], v[198:201], v[54:57]
	v_mfma_f32_16x16x32_bf16 v[46:49], v[162:165], v[198:201], v[46:49]
	v_mfma_f32_16x16x32_bf16 v[38:41], v[154:157], v[206:209], v[38:41]
	v_mfma_f32_16x16x32_bf16 v[30:33], v[162:165], v[206:209], v[30:33]
	v_mfma_f32_16x16x32_bf16 v[22:25], v[154:157], v[214:217], v[22:25]
	v_mfma_f32_16x16x32_bf16 v[14:17], v[162:165], v[214:217], v[14:17]
	v_mfma_f32_16x16x32_bf16 v[62:65], v[158:161], v[194:197], v[62:65]
	v_mfma_f32_16x16x32_bf16 v[58:61], v[170:173], v[194:197], v[58:61]
	v_mfma_f32_16x16x32_bf16 v[54:57], v[158:161], v[202:205], v[54:57]
	v_mfma_f32_16x16x32_bf16 v[46:49], v[170:173], v[202:205], v[46:49]
	v_mfma_f32_16x16x32_bf16 v[38:41], v[158:161], v[210:213], v[38:41]
	v_mfma_f32_16x16x32_bf16 v[30:33], v[170:173], v[210:213], v[30:33]
	v_mfma_f32_16x16x32_bf16 v[22:25], v[158:161], v[218:221], v[22:25]
	v_mfma_f32_16x16x32_bf16 v[14:17], v[170:173], v[218:221], v[14:17]
	v_mfma_f32_16x16x32_bf16 v[50:53], v[174:177], v[190:193], v[50:53]
	v_mfma_f32_16x16x32_bf16 v[42:45], v[182:185], v[190:193], v[42:45]
	v_mfma_f32_16x16x32_bf16 v[34:37], v[174:177], v[198:201], v[34:37]
	v_mfma_f32_16x16x32_bf16 v[26:29], v[182:185], v[198:201], v[26:29]
	v_mfma_f32_16x16x32_bf16 v[18:21], v[174:177], v[206:209], v[18:21]
	v_mfma_f32_16x16x32_bf16 v[10:13], v[182:185], v[206:209], v[10:13]
	v_mfma_f32_16x16x32_bf16 v[6:9], v[174:177], v[214:217], v[6:9]
	v_mfma_f32_16x16x32_bf16 v[2:5], v[182:185], v[214:217], v[2:5]
	v_mfma_f32_16x16x32_bf16 v[50:53], v[178:181], v[194:197], v[50:53]
	v_mfma_f32_16x16x32_bf16 v[42:45], v[186:189], v[194:197], v[42:45]
	v_mfma_f32_16x16x32_bf16 v[34:37], v[178:181], v[202:205], v[34:37]
	v_mfma_f32_16x16x32_bf16 v[26:29], v[186:189], v[202:205], v[26:29]
	v_mfma_f32_16x16x32_bf16 v[18:21], v[178:181], v[210:213], v[18:21]
	v_mfma_f32_16x16x32_bf16 v[10:13], v[186:189], v[210:213], v[10:13]
	v_mfma_f32_16x16x32_bf16 v[6:9], v[178:181], v[218:221], v[6:9]
	v_mfma_f32_16x16x32_bf16 v[2:5], v[186:189], v[218:221], v[2:5]
	s_setprio 0
	s_barrier
	s_add_i32 s52, s52, 2
	s_add_u32 s26, s26, 0x100
	s_addc_u32 s27, s27, 0
	s_add_u32 s50, s50, 0x100
	s_addc_u32 s51, s51, 0
	s_cmp_gt_u32 s52, 29
	s_cbranch_scc0 .LBB0_1433
	s_and_b64 vcc, exec, s[12:13]
	s_cbranch_vccz .LBB0_1436
	s_barrier

.LBB0_1595:
	ds_read_b128 v[146:149], v178
	ds_read_b128 v[150:153], v178 offset:1024
	ds_read_b128 v[154:157], v178 offset:2048
	ds_read_b128 v[158:161], v178 offset:3072
	ds_read_b128 v[182:185], v179
	ds_read_b128 v[186:189], v179 offset:1024
	ds_read_b128 v[190:193], v179 offset:2048
	ds_read_b128 v[194:197], v179 offset:3072
	s_add_u32 s34, s30, 0xfffc0080
	s_addc_u32 s35, s31, -1
	s_cmp_eq_u32 s72, 12
	s_cselect_b32 s37, s23, s35
	s_cselect_b32 s36, s68, s34
	s_cselect_b32 s35, s21, s71
	s_cselect_b32 s34, s69, s70
	s_add_i32 m0, s29, 0xc000
	ds_read_b128 v[198:201], v180
	ds_read_b128 v[202:205], v180 offset:1024
	ds_read_b128 v[206:209], v180 offset:2048
	ds_read_b128 v[210:213], v180 offset:3072
	ds_read_b128 v[214:217], v180 offset:4096
	ds_read_b128 v[218:221], v180 offset:5120
	ds_read_b128 v[222:225], v180 offset:6144
	ds_read_b128 v[226:229], v180 offset:7168
	global_load_lds_dwordx4 v138, s[30:31]
	s_add_i32 m0, s29, 0xe000
	s_nop 0
	global_load_lds_dwordx4 v140, s[30:31]
	s_waitcnt vmcnt(8)
	s_waitcnt lgkmcnt(0)
	s_barrier
	s_setprio 1
	v_mfma_i32_16x16x64_i8 v[126:129], v[146:149], v[198:201], v[126:129]
	v_mfma_i32_16x16x64_i8 v[118:121], v[154:157], v[198:201], v[118:121]
	v_mfma_i32_16x16x64_i8 v[110:113], v[146:149], v[206:209], v[110:113]
	v_mfma_i32_16x16x64_i8 v[102:105], v[154:157], v[206:209], v[102:105]
	v_mfma_i32_16x16x64_i8 v[94:97], v[146:149], v[214:217], v[94:97]
	v_mfma_i32_16x16x64_i8 v[86:89], v[154:157], v[214:217], v[86:89]
	v_mfma_i32_16x16x64_i8 v[78:81], v[146:149], v[222:225], v[78:81]
	v_mfma_i32_16x16x64_i8 v[70:73], v[154:157], v[222:225], v[70:73]
	v_mfma_i32_16x16x64_i8 v[126:129], v[150:153], v[202:205], v[126:129]
	v_mfma_i32_16x16x64_i8 v[118:121], v[158:161], v[202:205], v[118:121]
	v_mfma_i32_16x16x64_i8 v[110:113], v[150:153], v[210:213], v[110:113]
	v_mfma_i32_16x16x64_i8 v[102:105], v[158:161], v[210:213], v[102:105]
	v_mfma_i32_16x16x64_i8 v[94:97], v[150:153], v[218:221], v[94:97]
	v_mfma_i32_16x16x64_i8 v[86:89], v[158:161], v[218:221], v[86:89]
	v_mfma_i32_16x16x64_i8 v[78:81], v[150:153], v[226:229], v[78:81]
	v_mfma_i32_16x16x64_i8 v[70:73], v[158:161], v[226:229], v[70:73]
	v_mfma_i32_16x16x64_i8 v[122:125], v[182:185], v[198:201], v[122:125]
	v_mfma_i32_16x16x64_i8 v[114:117], v[190:193], v[198:201], v[114:117]
	v_mfma_i32_16x16x64_i8 v[106:109], v[182:185], v[206:209], v[106:109]
	v_mfma_i32_16x16x64_i8 v[98:101], v[190:193], v[206:209], v[98:101]
	v_mfma_i32_16x16x64_i8 v[90:93], v[182:185], v[214:217], v[90:93]
	v_mfma_i32_16x16x64_i8 v[82:85], v[190:193], v[214:217], v[82:85]
	v_mfma_i32_16x16x64_i8 v[74:77], v[182:185], v[222:225], v[74:77]
	v_mfma_i32_16x16x64_i8 v[66:69], v[190:193], v[222:225], v[66:69]
	v_mfma_i32_16x16x64_i8 v[122:125], v[186:189], v[202:205], v[122:125]
	v_mfma_i32_16x16x64_i8 v[114:117], v[194:197], v[202:205], v[114:117]
	v_mfma_i32_16x16x64_i8 v[106:109], v[186:189], v[210:213], v[106:109]
	v_mfma_i32_16x16x64_i8 v[98:101], v[194:197], v[210:213], v[98:101]
	v_mfma_i32_16x16x64_i8 v[90:93], v[186:189], v[218:221], v[90:93]
	v_mfma_i32_16x16x64_i8 v[82:85], v[194:197], v[218:221], v[82:85]
	v_mfma_i32_16x16x64_i8 v[74:77], v[186:189], v[226:229], v[74:77]
	v_mfma_i32_16x16x64_i8 v[66:69], v[194:197], v[226:229], v[66:69]
	s_setprio 0
	s_barrier
	s_add_i32 s73, s48, s40
	v_lshl_add_u64 v[162:163], s[34:35], 0, v[134:135]
	s_mov_b32 m0, s73
	ds_read_b128 v[198:201], v180 offset:16384
	ds_read_b128 v[202:205], v180 offset:17408
	ds_read_b128 v[206:209], v180 offset:18432
	ds_read_b128 v[210:213], v180 offset:19456
	ds_read_b128 v[214:217], v180 offset:20480
	ds_read_b128 v[218:221], v180 offset:21504
	ds_read_b128 v[222:225], v180 offset:22528
	ds_read_b128 v[226:229], v180 offset:23552
	global_load_lds_dwordx4 v134, s[34:35]
	s_add_i32 m0, s73, 0x2000
	s_add_u32 s74, s34, 0x40000
	v_lshl_add_u64 v[230:231], s[34:35], 0, v[130:131]
	s_addc_u32 s75, s35, 0
	s_add_i32 s73, s49, s40
	global_load_lds_dwordx4 v130, s[34:35]
	s_mov_b32 m0, s73
	v_lshl_add_u64 v[234:235], s[36:37], 0, v[132:133]
	global_load_lds_dwordx4 v134, s[74:75]
	s_add_i32 m0, s73, 0x2000
	s_nop 0
	global_load_lds_dwordx4 v130, s[74:75]
	v_lshl_add_u64 v[232:233], s[36:37], 0, v[136:137]
	s_mov_b32 m0, s29
	s_nop 0
	global_load_lds_dwordx4 v136, s[36:37]
	s_mov_b32 m0, s42
	s_nop 0
	global_load_lds_dwordx4 v132, s[36:37]
	s_waitcnt vmcnt(8)
	s_waitcnt lgkmcnt(0)
	s_barrier
	s_setprio 1
	v_mfma_i32_16x16x64_i8 v[62:65], v[146:149], v[198:201], v[62:65]
	v_mfma_i32_16x16x64_i8 v[54:57], v[154:157], v[198:201], v[54:57]
	v_mfma_i32_16x16x64_i8 v[46:49], v[146:149], v[206:209], v[46:49]
	v_mfma_i32_16x16x64_i8 v[38:41], v[154:157], v[206:209], v[38:41]
	v_mfma_i32_16x16x64_i8 v[30:33], v[146:149], v[214:217], v[30:33]
	v_mfma_i32_16x16x64_i8 v[22:25], v[154:157], v[214:217], v[22:25]
	v_mfma_i32_16x16x64_i8 v[14:17], v[146:149], v[222:225], v[14:17]
	v_mfma_i32_16x16x64_i8 v[6:9], v[154:157], v[222:225], v[6:9]
	v_mfma_i32_16x16x64_i8 v[62:65], v[150:153], v[202:205], v[62:65]
	v_mfma_i32_16x16x64_i8 v[54:57], v[158:161], v[202:205], v[54:57]
	v_mfma_i32_16x16x64_i8 v[46:49], v[150:153], v[210:213], v[46:49]
	v_mfma_i32_16x16x64_i8 v[38:41], v[158:161], v[210:213], v[38:41]
	v_mfma_i32_16x16x64_i8 v[30:33], v[150:153], v[218:221], v[30:33]
	v_mfma_i32_16x16x64_i8 v[22:25], v[158:161], v[218:221], v[22:25]
	v_mfma_i32_16x16x64_i8 v[14:17], v[150:153], v[226:229], v[14:17]
	v_mfma_i32_16x16x64_i8 v[6:9], v[158:161], v[226:229], v[6:9]
	v_mfma_i32_16x16x64_i8 v[58:61], v[182:185], v[198:201], v[58:61]
	v_mfma_i32_16x16x64_i8 v[50:53], v[190:193], v[198:201], v[50:53]
	v_mfma_i32_16x16x64_i8 v[42:45], v[182:185], v[206:209], v[42:45]
	v_mfma_i32_16x16x64_i8 v[34:37], v[190:193], v[206:209], v[34:37]
	v_mfma_i32_16x16x64_i8 v[26:29], v[182:185], v[214:217], v[26:29]
	v_mfma_i32_16x16x64_i8 v[18:21], v[190:193], v[214:217], v[18:21]
	v_mfma_i32_16x16x64_i8 v[10:13], v[182:185], v[222:225], v[10:13]
	v_mfma_i32_16x16x64_i8 v[2:5], v[190:193], v[222:225], v[2:5]
	v_mfma_i32_16x16x64_i8 v[58:61], v[186:189], v[202:205], v[58:61]
	v_mfma_i32_16x16x64_i8 v[50:53], v[194:197], v[202:205], v[50:53]
	v_mfma_i32_16x16x64_i8 v[42:45], v[186:189], v[210:213], v[42:45]
	v_mfma_i32_16x16x64_i8 v[34:37], v[194:197], v[210:213], v[34:37]
	v_mfma_i32_16x16x64_i8 v[26:29], v[186:189], v[218:221], v[26:29]
	v_mfma_i32_16x16x64_i8 v[18:21], v[194:197], v[218:221], v[18:21]
	v_mfma_i32_16x16x64_i8 v[10:13], v[186:189], v[226:229], v[10:13]
	v_mfma_i32_16x16x64_i8 v[2:5], v[194:197], v[226:229], v[2:5]
	s_setprio 0
	s_barrier
	s_add_i32 s73, 0, 0x18000
	v_add_u32_e32 v158, s73, v169
	ds_read_b128 v[146:149], v158
	ds_read_b128 v[150:153], v158 offset:1024
	ds_read_b128 v[154:157], v158 offset:2048
	ds_read_b128 v[158:161], v158 offset:3072
	ds_read_b128 v[182:185], v181
	ds_read_b128 v[186:189], v181 offset:1024
	ds_read_b128 v[190:193], v181 offset:2048
	ds_read_b128 v[194:197], v181 offset:3072
	s_add_u32 s36, s36, 0x40000
	s_addc_u32 s37, s37, 0
	s_mov_b32 m0, s43
	ds_read_b128 v[198:201], v180 offset:32768
	ds_read_b128 v[202:205], v180 offset:33792
	ds_read_b128 v[206:209], v180 offset:34816
	ds_read_b128 v[210:213], v180 offset:35840
	ds_read_b128 v[214:217], v180 offset:36864
	ds_read_b128 v[218:221], v180 offset:37888
	ds_read_b128 v[222:225], v180 offset:38912
	ds_read_b128 v[226:229], v180 offset:39936
	global_load_lds_dwordx4 v136, s[36:37]
	s_mov_b32 m0, s44
	s_nop 0
	global_load_lds_dwordx4 v132, s[36:37]
	s_waitcnt vmcnt(8)
	s_waitcnt lgkmcnt(0)
	s_barrier
	s_setprio 1
	v_mfma_i32_16x16x64_i8 v[126:129], v[146:149], v[198:201], v[126:129]
	v_mfma_i32_16x16x64_i8 v[118:121], v[154:157], v[198:201], v[118:121]
	v_mfma_i32_16x16x64_i8 v[110:113], v[146:149], v[206:209], v[110:113]
	v_mfma_i32_16x16x64_i8 v[102:105], v[154:157], v[206:209], v[102:105]
	v_mfma_i32_16x16x64_i8 v[94:97], v[146:149], v[214:217], v[94:97]
	v_mfma_i32_16x16x64_i8 v[86:89], v[154:157], v[214:217], v[86:89]
	v_mfma_i32_16x16x64_i8 v[78:81], v[146:149], v[222:225], v[78:81]
	v_mfma_i32_16x16x64_i8 v[70:73], v[154:157], v[222:225], v[70:73]
	v_mfma_i32_16x16x64_i8 v[126:129], v[150:153], v[202:205], v[126:129]
	v_mfma_i32_16x16x64_i8 v[118:121], v[158:161], v[202:205], v[118:121]
	v_mfma_i32_16x16x64_i8 v[110:113], v[150:153], v[210:213], v[110:113]
	v_mfma_i32_16x16x64_i8 v[102:105], v[158:161], v[210:213], v[102:105]
	v_mfma_i32_16x16x64_i8 v[94:97], v[150:153], v[218:221], v[94:97]
	v_mfma_i32_16x16x64_i8 v[86:89], v[158:161], v[218:221], v[86:89]
	v_mfma_i32_16x16x64_i8 v[78:81], v[150:153], v[226:229], v[78:81]
	v_mfma_i32_16x16x64_i8 v[70:73], v[158:161], v[226:229], v[70:73]
	v_mfma_i32_16x16x64_i8 v[122:125], v[182:185], v[198:201], v[122:125]
	v_mfma_i32_16x16x64_i8 v[114:117], v[190:193], v[198:201], v[114:117]
	v_mfma_i32_16x16x64_i8 v[106:109], v[182:185], v[206:209], v[106:109]
	v_mfma_i32_16x16x64_i8 v[98:101], v[190:193], v[206:209], v[98:101]
	v_mfma_i32_16x16x64_i8 v[90:93], v[182:185], v[214:217], v[90:93]
	v_mfma_i32_16x16x64_i8 v[82:85], v[190:193], v[214:217], v[82:85]
	v_mfma_i32_16x16x64_i8 v[74:77], v[182:185], v[222:225], v[74:77]
	v_mfma_i32_16x16x64_i8 v[66:69], v[190:193], v[222:225], v[66:69]
	v_mfma_i32_16x16x64_i8 v[122:125], v[186:189], v[202:205], v[122:125]
	v_mfma_i32_16x16x64_i8 v[114:117], v[194:197], v[202:205], v[114:117]
	v_mfma_i32_16x16x64_i8 v[106:109], v[186:189], v[210:213], v[106:109]
	v_mfma_i32_16x16x64_i8 v[98:101], v[194:197], v[210:213], v[98:101]
	v_mfma_i32_16x16x64_i8 v[90:93], v[186:189], v[218:221], v[90:93]
	v_mfma_i32_16x16x64_i8 v[82:85], v[194:197], v[218:221], v[82:85]
	v_mfma_i32_16x16x64_i8 v[74:77], v[186:189], v[226:229], v[74:77]
	v_mfma_i32_16x16x64_i8 v[66:69], v[194:197], v[226:229], v[66:69]
	s_setprio 0
	s_barrier
	s_add_i32 s36, s73, s40
	v_lshl_add_u64 v[162:163], v[162:163], 0, s[10:11]
	s_mov_b32 m0, s36
	ds_read_b128 v[198:201], v180 offset:49152
	ds_read_b128 v[202:205], v180 offset:50176
	ds_read_b128 v[206:209], v180 offset:51200
	ds_read_b128 v[210:213], v180 offset:52224
	ds_read_b128 v[214:217], v180 offset:53248
	ds_read_b128 v[218:221], v180 offset:54272
	ds_read_b128 v[222:225], v180 offset:55296
	ds_read_b128 v[226:229], v180 offset:56320
	global_load_lds_dwordx4 v[162:163], off
	s_add_i32 m0, s36, 0x2000
	s_add_u32 s34, s34, 0x40080
	v_lshl_add_u64 v[162:163], v[230:231], 0, s[10:11]
	s_addc_u32 s35, s35, 0
	s_add_i32 s36, s50, s40
	global_load_lds_dwordx4 v[162:163], off
	s_mov_b32 m0, s36
	s_nop 0
	global_load_lds_dwordx4 v134, s[34:35]
	s_add_i32 m0, s36, 0x2000
	s_nop 0
	global_load_lds_dwordx4 v130, s[34:35]
	v_lshl_add_u64 v[162:163], v[232:233], 0, s[10:11]
	s_mov_b32 m0, s45
	s_nop 0
	global_load_lds_dwordx4 v[162:163], off
	v_lshl_add_u64 v[162:163], v[234:235], 0, s[10:11]
	s_mov_b32 m0, s46
	s_nop 0
	global_load_lds_dwordx4 v[162:163], off
	s_waitcnt vmcnt(8)
	s_waitcnt lgkmcnt(0)
	s_barrier
	s_setprio 1
	v_mfma_i32_16x16x64_i8 v[62:65], v[146:149], v[198:201], v[62:65]
	v_mfma_i32_16x16x64_i8 v[54:57], v[154:157], v[198:201], v[54:57]
	v_mfma_i32_16x16x64_i8 v[46:49], v[146:149], v[206:209], v[46:49]
	v_mfma_i32_16x16x64_i8 v[38:41], v[154:157], v[206:209], v[38:41]
	v_mfma_i32_16x16x64_i8 v[30:33], v[146:149], v[214:217], v[30:33]
	v_mfma_i32_16x16x64_i8 v[22:25], v[154:157], v[214:217], v[22:25]
	v_mfma_i32_16x16x64_i8 v[14:17], v[146:149], v[222:225], v[14:17]
	v_mfma_i32_16x16x64_i8 v[6:9], v[154:157], v[222:225], v[6:9]
	v_mfma_i32_16x16x64_i8 v[62:65], v[150:153], v[202:205], v[62:65]
	v_mfma_i32_16x16x64_i8 v[54:57], v[158:161], v[202:205], v[54:57]
	v_mfma_i32_16x16x64_i8 v[46:49], v[150:153], v[210:213], v[46:49]
	v_mfma_i32_16x16x64_i8 v[38:41], v[158:161], v[210:213], v[38:41]
	v_mfma_i32_16x16x64_i8 v[30:33], v[150:153], v[218:221], v[30:33]
	v_mfma_i32_16x16x64_i8 v[22:25], v[158:161], v[218:221], v[22:25]
	v_mfma_i32_16x16x64_i8 v[14:17], v[150:153], v[226:229], v[14:17]
	v_mfma_i32_16x16x64_i8 v[6:9], v[158:161], v[226:229], v[6:9]
	v_mfma_i32_16x16x64_i8 v[58:61], v[182:185], v[198:201], v[58:61]
	v_mfma_i32_16x16x64_i8 v[50:53], v[190:193], v[198:201], v[50:53]
	v_mfma_i32_16x16x64_i8 v[42:45], v[182:185], v[206:209], v[42:45]
	v_mfma_i32_16x16x64_i8 v[34:37], v[190:193], v[206:209], v[34:37]
	v_mfma_i32_16x16x64_i8 v[26:29], v[182:185], v[214:217], v[26:29]
	v_mfma_i32_16x16x64_i8 v[18:21], v[190:193], v[214:217], v[18:21]
	v_mfma_i32_16x16x64_i8 v[10:13], v[182:185], v[222:225], v[10:13]
	v_mfma_i32_16x16x64_i8 v[2:5], v[190:193], v[222:225], v[2:5]
	v_mfma_i32_16x16x64_i8 v[58:61], v[186:189], v[202:205], v[58:61]
	v_mfma_i32_16x16x64_i8 v[50:53], v[194:197], v[202:205], v[50:53]
	v_mfma_i32_16x16x64_i8 v[42:45], v[186:189], v[210:213], v[42:45]
	v_mfma_i32_16x16x64_i8 v[34:37], v[194:197], v[210:213], v[34:37]
	v_mfma_i32_16x16x64_i8 v[26:29], v[186:189], v[218:221], v[26:29]
	v_mfma_i32_16x16x64_i8 v[18:21], v[194:197], v[218:221], v[18:21]
	v_mfma_i32_16x16x64_i8 v[10:13], v[186:189], v[226:229], v[10:13]
	v_mfma_i32_16x16x64_i8 v[2:5], v[194:197], v[226:229], v[2:5]
	s_setprio 0
	s_barrier
	s_add_i32 s72, s72, 2
	s_add_u32 s30, s30, 0x100
	s_addc_u32 s31, s31, 0
	s_add_u32 s70, s70, 0x100
	s_addc_u32 s71, s71, 0
	s_cmp_gt_u32 s72, 13
	s_cbranch_scc0 .LBB0_1595
	s_and_b64 vcc, exec, s[14:15]
	s_cbranch_vccz .LBB0_1598
	s_barrier

.LBB0_1704:
	ds_read_b128 v[154:157], v149
	ds_read_b128 v[158:161], v149 offset:1024
	ds_read_b128 v[162:165], v149 offset:2048
	ds_read_b128 v[170:173], v149 offset:3072
	ds_read_b128 v[174:177], v150
	ds_read_b128 v[178:181], v150 offset:1024
	ds_read_b128 v[182:185], v150 offset:2048
	ds_read_b128 v[186:189], v150 offset:3072
	s_add_u32 s22, s20, 0xffea0080
	s_addc_u32 s23, s21, -1
	s_cmpk_eq_i32 s48, 0x54
	s_cselect_b32 s25, s7, s23
	s_cselect_b32 s24, s6, s22
	s_cselect_b32 s23, s17, s47
	s_cselect_b32 s22, s16, s46
	s_add_i32 m0, s28, 0xc000
	ds_read_b128 v[190:193], v151
	ds_read_b128 v[194:197], v151 offset:1024
	ds_read_b128 v[198:201], v151 offset:2048
	ds_read_b128 v[202:205], v151 offset:3072
	ds_read_b128 v[206:209], v151 offset:4096
	ds_read_b128 v[210:213], v151 offset:5120
	ds_read_b128 v[214:217], v151 offset:6144
	ds_read_b128 v[218:221], v151 offset:7168
	global_load_lds_dwordx4 v138, s[20:21]
	s_add_i32 m0, s28, 0xe000
	s_nop 0
	global_load_lds_dwordx4 v140, s[20:21]
	s_waitcnt vmcnt(8)
	s_waitcnt lgkmcnt(0)
	s_barrier
	s_setprio 1
	v_mfma_f32_16x16x32_bf16 v[126:129], v[154:157], v[190:193], v[126:129]
	v_mfma_f32_16x16x32_bf16 v[122:125], v[162:165], v[190:193], v[122:125]
	v_mfma_f32_16x16x32_bf16 v[118:121], v[154:157], v[198:201], v[118:121]
	v_mfma_f32_16x16x32_bf16 v[110:113], v[162:165], v[198:201], v[110:113]
	v_mfma_f32_16x16x32_bf16 v[102:105], v[154:157], v[206:209], v[102:105]
	v_mfma_f32_16x16x32_bf16 v[94:97], v[162:165], v[206:209], v[94:97]
	v_mfma_f32_16x16x32_bf16 v[86:89], v[154:157], v[214:217], v[86:89]
	v_mfma_f32_16x16x32_bf16 v[78:81], v[162:165], v[214:217], v[78:81]
	v_mfma_f32_16x16x32_bf16 v[126:129], v[158:161], v[194:197], v[126:129]
	v_mfma_f32_16x16x32_bf16 v[122:125], v[170:173], v[194:197], v[122:125]
	v_mfma_f32_16x16x32_bf16 v[118:121], v[158:161], v[202:205], v[118:121]
	v_mfma_f32_16x16x32_bf16 v[110:113], v[170:173], v[202:205], v[110:113]
	v_mfma_f32_16x16x32_bf16 v[102:105], v[158:161], v[210:213], v[102:105]
	v_mfma_f32_16x16x32_bf16 v[94:97], v[170:173], v[210:213], v[94:97]
	v_mfma_f32_16x16x32_bf16 v[86:89], v[158:161], v[218:221], v[86:89]
	v_mfma_f32_16x16x32_bf16 v[78:81], v[170:173], v[218:221], v[78:81]
	v_mfma_f32_16x16x32_bf16 v[114:117], v[174:177], v[190:193], v[114:117]
	v_mfma_f32_16x16x32_bf16 v[106:109], v[182:185], v[190:193], v[106:109]
	v_mfma_f32_16x16x32_bf16 v[98:101], v[174:177], v[198:201], v[98:101]
	v_mfma_f32_16x16x32_bf16 v[90:93], v[182:185], v[198:201], v[90:93]
	v_mfma_f32_16x16x32_bf16 v[82:85], v[174:177], v[206:209], v[82:85]
	v_mfma_f32_16x16x32_bf16 v[74:77], v[182:185], v[206:209], v[74:77]
	v_mfma_f32_16x16x32_bf16 v[70:73], v[174:177], v[214:217], v[70:73]
	v_mfma_f32_16x16x32_bf16 v[66:69], v[182:185], v[214:217], v[66:69]
	v_mfma_f32_16x16x32_bf16 v[114:117], v[178:181], v[194:197], v[114:117]
	v_mfma_f32_16x16x32_bf16 v[106:109], v[186:189], v[194:197], v[106:109]
	v_mfma_f32_16x16x32_bf16 v[98:101], v[178:181], v[202:205], v[98:101]
	v_mfma_f32_16x16x32_bf16 v[90:93], v[186:189], v[202:205], v[90:93]
	v_mfma_f32_16x16x32_bf16 v[82:85], v[178:181], v[210:213], v[82:85]
	v_mfma_f32_16x16x32_bf16 v[74:77], v[186:189], v[210:213], v[74:77]
	v_mfma_f32_16x16x32_bf16 v[70:73], v[178:181], v[218:221], v[70:73]
	v_mfma_f32_16x16x32_bf16 v[66:69], v[186:189], v[218:221], v[66:69]
	s_setprio 0
	s_barrier
	s_add_i32 s49, s38, s27
	v_lshl_add_u64 v[146:147], s[22:23], 0, v[132:133]
	s_mov_b32 m0, s49
	ds_read_b128 v[190:193], v151 offset:16384
	ds_read_b128 v[194:197], v151 offset:17408
	ds_read_b128 v[198:201], v151 offset:18432
	ds_read_b128 v[202:205], v151 offset:19456
	ds_read_b128 v[206:209], v151 offset:20480
	ds_read_b128 v[210:213], v151 offset:21504
	ds_read_b128 v[214:217], v151 offset:22528
	ds_read_b128 v[218:221], v151 offset:23552
	global_load_lds_dwordx4 v132, s[22:23]
	s_add_i32 m0, s49, 0x2000
	s_add_u32 s50, s22, 0x160000
	v_lshl_add_u64 v[222:223], s[22:23], 0, v[136:137]
	s_addc_u32 s51, s23, 0
	s_add_i32 s49, s39, s27
	global_load_lds_dwordx4 v136, s[22:23]
	s_mov_b32 m0, s49
	v_lshl_add_u64 v[226:227], s[24:25], 0, v[134:135]
	global_load_lds_dwordx4 v132, s[50:51]
	s_add_i32 m0, s49, 0x2000
	s_nop 0
	global_load_lds_dwordx4 v136, s[50:51]
	v_lshl_add_u64 v[224:225], s[24:25], 0, v[130:131]
	s_mov_b32 m0, s28
	s_nop 0
	global_load_lds_dwordx4 v130, s[24:25]
	s_mov_b32 m0, s29
	s_nop 0
	global_load_lds_dwordx4 v134, s[24:25]
	s_waitcnt vmcnt(8)
	s_waitcnt lgkmcnt(0)
	s_barrier
	s_setprio 1
	v_mfma_f32_16x16x32_bf16 v[62:65], v[154:157], v[190:193], v[62:65]
	v_mfma_f32_16x16x32_bf16 v[58:61], v[162:165], v[190:193], v[58:61]
	v_mfma_f32_16x16x32_bf16 v[54:57], v[154:157], v[198:201], v[54:57]
	v_mfma_f32_16x16x32_bf16 v[46:49], v[162:165], v[198:201], v[46:49]
	v_mfma_f32_16x16x32_bf16 v[38:41], v[154:157], v[206:209], v[38:41]
	v_mfma_f32_16x16x32_bf16 v[30:33], v[162:165], v[206:209], v[30:33]
	v_mfma_f32_16x16x32_bf16 v[22:25], v[154:157], v[214:217], v[22:25]
	v_mfma_f32_16x16x32_bf16 v[14:17], v[162:165], v[214:217], v[14:17]
	v_mfma_f32_16x16x32_bf16 v[62:65], v[158:161], v[194:197], v[62:65]
	v_mfma_f32_16x16x32_bf16 v[58:61], v[170:173], v[194:197], v[58:61]
	v_mfma_f32_16x16x32_bf16 v[54:57], v[158:161], v[202:205], v[54:57]
	v_mfma_f32_16x16x32_bf16 v[46:49], v[170:173], v[202:205], v[46:49]
	v_mfma_f32_16x16x32_bf16 v[38:41], v[158:161], v[210:213], v[38:41]
	v_mfma_f32_16x16x32_bf16 v[30:33], v[170:173], v[210:213], v[30:33]
	v_mfma_f32_16x16x32_bf16 v[22:25], v[158:161], v[218:221], v[22:25]
	v_mfma_f32_16x16x32_bf16 v[14:17], v[170:173], v[218:221], v[14:17]
	v_mfma_f32_16x16x32_bf16 v[50:53], v[174:177], v[190:193], v[50:53]
	v_mfma_f32_16x16x32_bf16 v[42:45], v[182:185], v[190:193], v[42:45]
	v_mfma_f32_16x16x32_bf16 v[34:37], v[174:177], v[198:201], v[34:37]
	v_mfma_f32_16x16x32_bf16 v[26:29], v[182:185], v[198:201], v[26:29]
	v_mfma_f32_16x16x32_bf16 v[18:21], v[174:177], v[206:209], v[18:21]
	v_mfma_f32_16x16x32_bf16 v[10:13], v[182:185], v[206:209], v[10:13]
	v_mfma_f32_16x16x32_bf16 v[6:9], v[174:177], v[214:217], v[6:9]
	v_mfma_f32_16x16x32_bf16 v[2:5], v[182:185], v[214:217], v[2:5]
	v_mfma_f32_16x16x32_bf16 v[50:53], v[178:181], v[194:197], v[50:53]
	v_mfma_f32_16x16x32_bf16 v[42:45], v[186:189], v[194:197], v[42:45]
	v_mfma_f32_16x16x32_bf16 v[34:37], v[178:181], v[202:205], v[34:37]
	v_mfma_f32_16x16x32_bf16 v[26:29], v[186:189], v[202:205], v[26:29]
	v_mfma_f32_16x16x32_bf16 v[18:21], v[178:181], v[210:213], v[18:21]
	v_mfma_f32_16x16x32_bf16 v[10:13], v[186:189], v[210:213], v[10:13]
	v_mfma_f32_16x16x32_bf16 v[6:9], v[178:181], v[218:221], v[6:9]
	v_mfma_f32_16x16x32_bf16 v[2:5], v[186:189], v[218:221], v[2:5]
	s_setprio 0
	s_barrier
	ds_read_b128 v[154:157], v152
	ds_read_b128 v[158:161], v152 offset:1024
	ds_read_b128 v[162:165], v152 offset:2048
	ds_read_b128 v[170:173], v152 offset:3072
	ds_read_b128 v[174:177], v153
	ds_read_b128 v[178:181], v153 offset:1024
	ds_read_b128 v[182:185], v153 offset:2048
	ds_read_b128 v[186:189], v153 offset:3072
	s_add_u32 s24, s24, 0x160000
	s_addc_u32 s25, s25, 0
	s_mov_b32 m0, s30
	ds_read_b128 v[190:193], v151 offset:32768
	ds_read_b128 v[194:197], v151 offset:33792
	ds_read_b128 v[198:201], v151 offset:34816
	ds_read_b128 v[202:205], v151 offset:35840
	ds_read_b128 v[206:209], v151 offset:36864
	ds_read_b128 v[210:213], v151 offset:37888
	ds_read_b128 v[214:217], v151 offset:38912
	ds_read_b128 v[218:221], v151 offset:39936
	global_load_lds_dwordx4 v130, s[24:25]
	s_mov_b32 m0, s31
	s_nop 0
	global_load_lds_dwordx4 v134, s[24:25]
	s_waitcnt vmcnt(8)
	s_waitcnt lgkmcnt(0)
	s_barrier
	s_setprio 1
	v_mfma_f32_16x16x32_bf16 v[126:129], v[154:157], v[190:193], v[126:129]
	v_mfma_f32_16x16x32_bf16 v[122:125], v[162:165], v[190:193], v[122:125]
	v_mfma_f32_16x16x32_bf16 v[118:121], v[154:157], v[198:201], v[118:121]
	v_mfma_f32_16x16x32_bf16 v[110:113], v[162:165], v[198:201], v[110:113]
	v_mfma_f32_16x16x32_bf16 v[102:105], v[154:157], v[206:209], v[102:105]
	v_mfma_f32_16x16x32_bf16 v[94:97], v[162:165], v[206:209], v[94:97]
	v_mfma_f32_16x16x32_bf16 v[86:89], v[154:157], v[214:217], v[86:89]
	v_mfma_f32_16x16x32_bf16 v[78:81], v[162:165], v[214:217], v[78:81]
	v_mfma_f32_16x16x32_bf16 v[126:129], v[158:161], v[194:197], v[126:129]
	v_mfma_f32_16x16x32_bf16 v[122:125], v[170:173], v[194:197], v[122:125]
	v_mfma_f32_16x16x32_bf16 v[118:121], v[158:161], v[202:205], v[118:121]
	v_mfma_f32_16x16x32_bf16 v[110:113], v[170:173], v[202:205], v[110:113]
	v_mfma_f32_16x16x32_bf16 v[102:105], v[158:161], v[210:213], v[102:105]
	v_mfma_f32_16x16x32_bf16 v[94:97], v[170:173], v[210:213], v[94:97]
	v_mfma_f32_16x16x32_bf16 v[86:89], v[158:161], v[218:221], v[86:89]
	v_mfma_f32_16x16x32_bf16 v[78:81], v[170:173], v[218:221], v[78:81]
	v_mfma_f32_16x16x32_bf16 v[114:117], v[174:177], v[190:193], v[114:117]
	v_mfma_f32_16x16x32_bf16 v[106:109], v[182:185], v[190:193], v[106:109]
	v_mfma_f32_16x16x32_bf16 v[98:101], v[174:177], v[198:201], v[98:101]
	v_mfma_f32_16x16x32_bf16 v[90:93], v[182:185], v[198:201], v[90:93]
	v_mfma_f32_16x16x32_bf16 v[82:85], v[174:177], v[206:209], v[82:85]
	v_mfma_f32_16x16x32_bf16 v[74:77], v[182:185], v[206:209], v[74:77]
	v_mfma_f32_16x16x32_bf16 v[70:73], v[174:177], v[214:217], v[70:73]
	v_mfma_f32_16x16x32_bf16 v[66:69], v[182:185], v[214:217], v[66:69]
	v_mfma_f32_16x16x32_bf16 v[114:117], v[178:181], v[194:197], v[114:117]
	v_mfma_f32_16x16x32_bf16 v[106:109], v[186:189], v[194:197], v[106:109]
	v_mfma_f32_16x16x32_bf16 v[98:101], v[178:181], v[202:205], v[98:101]
	v_mfma_f32_16x16x32_bf16 v[90:93], v[186:189], v[202:205], v[90:93]
	v_mfma_f32_16x16x32_bf16 v[82:85], v[178:181], v[210:213], v[82:85]
	v_mfma_f32_16x16x32_bf16 v[74:77], v[186:189], v[210:213], v[74:77]
	v_mfma_f32_16x16x32_bf16 v[70:73], v[178:181], v[218:221], v[70:73]
	v_mfma_f32_16x16x32_bf16 v[66:69], v[186:189], v[218:221], v[66:69]
	s_setprio 0
	s_barrier
	s_add_i32 s24, s40, s27
	v_lshl_add_u64 v[146:147], v[146:147], 0, s[8:9]
	s_mov_b32 m0, s24
	ds_read_b128 v[190:193], v151 offset:49152
	ds_read_b128 v[194:197], v151 offset:50176
	ds_read_b128 v[198:201], v151 offset:51200
	ds_read_b128 v[202:205], v151 offset:52224
	ds_read_b128 v[206:209], v151 offset:53248
	ds_read_b128 v[210:213], v151 offset:54272
	ds_read_b128 v[214:217], v151 offset:55296
	ds_read_b128 v[218:221], v151 offset:56320
	global_load_lds_dwordx4 v[146:147], off
	s_add_i32 m0, s24, 0x2000
	s_add_u32 s22, s22, 0x160080
	v_lshl_add_u64 v[146:147], v[222:223], 0, s[8:9]
	s_addc_u32 s23, s23, 0
	s_add_i32 s24, s41, s27
	global_load_lds_dwordx4 v[146:147], off
	s_mov_b32 m0, s24
	s_nop 0
	global_load_lds_dwordx4 v132, s[22:23]
	s_add_i32 m0, s24, 0x2000
	s_nop 0
	global_load_lds_dwordx4 v136, s[22:23]
	v_lshl_add_u64 v[146:147], v[224:225], 0, s[8:9]
	s_mov_b32 m0, s34
	s_nop 0
	global_load_lds_dwordx4 v[146:147], off
	v_lshl_add_u64 v[146:147], v[226:227], 0, s[8:9]
	s_mov_b32 m0, s35
	s_nop 0
	global_load_lds_dwordx4 v[146:147], off
	s_waitcnt vmcnt(8)
	s_waitcnt lgkmcnt(0)
	s_barrier
	s_setprio 1
	v_mfma_f32_16x16x32_bf16 v[62:65], v[154:157], v[190:193], v[62:65]
	v_mfma_f32_16x16x32_bf16 v[58:61], v[162:165], v[190:193], v[58:61]
	v_mfma_f32_16x16x32_bf16 v[54:57], v[154:157], v[198:201], v[54:57]
	v_mfma_f32_16x16x32_bf16 v[46:49], v[162:165], v[198:201], v[46:49]
	v_mfma_f32_16x16x32_bf16 v[38:41], v[154:157], v[206:209], v[38:41]
	v_mfma_f32_16x16x32_bf16 v[30:33], v[162:165], v[206:209], v[30:33]
	v_mfma_f32_16x16x32_bf16 v[22:25], v[154:157], v[214:217], v[22:25]
	v_mfma_f32_16x16x32_bf16 v[14:17], v[162:165], v[214:217], v[14:17]
	v_mfma_f32_16x16x32_bf16 v[62:65], v[158:161], v[194:197], v[62:65]
	v_mfma_f32_16x16x32_bf16 v[58:61], v[170:173], v[194:197], v[58:61]
	v_mfma_f32_16x16x32_bf16 v[54:57], v[158:161], v[202:205], v[54:57]
	v_mfma_f32_16x16x32_bf16 v[46:49], v[170:173], v[202:205], v[46:49]
	v_mfma_f32_16x16x32_bf16 v[38:41], v[158:161], v[210:213], v[38:41]
	v_mfma_f32_16x16x32_bf16 v[30:33], v[170:173], v[210:213], v[30:33]
	v_mfma_f32_16x16x32_bf16 v[22:25], v[158:161], v[218:221], v[22:25]
	v_mfma_f32_16x16x32_bf16 v[14:17], v[170:173], v[218:221], v[14:17]
	v_mfma_f32_16x16x32_bf16 v[50:53], v[174:177], v[190:193], v[50:53]
	v_mfma_f32_16x16x32_bf16 v[42:45], v[182:185], v[190:193], v[42:45]
	v_mfma_f32_16x16x32_bf16 v[34:37], v[174:177], v[198:201], v[34:37]
	v_mfma_f32_16x16x32_bf16 v[26:29], v[182:185], v[198:201], v[26:29]
	v_mfma_f32_16x16x32_bf16 v[18:21], v[174:177], v[206:209], v[18:21]
	v_mfma_f32_16x16x32_bf16 v[10:13], v[182:185], v[206:209], v[10:13]
	v_mfma_f32_16x16x32_bf16 v[6:9], v[174:177], v[214:217], v[6:9]
	v_mfma_f32_16x16x32_bf16 v[2:5], v[182:185], v[214:217], v[2:5]
	v_mfma_f32_16x16x32_bf16 v[50:53], v[178:181], v[194:197], v[50:53]
	v_mfma_f32_16x16x32_bf16 v[42:45], v[186:189], v[194:197], v[42:45]
	v_mfma_f32_16x16x32_bf16 v[34:37], v[178:181], v[202:205], v[34:37]
	v_mfma_f32_16x16x32_bf16 v[26:29], v[186:189], v[202:205], v[26:29]
	v_mfma_f32_16x16x32_bf16 v[18:21], v[178:181], v[210:213], v[18:21]
	v_mfma_f32_16x16x32_bf16 v[10:13], v[186:189], v[210:213], v[10:13]
	v_mfma_f32_16x16x32_bf16 v[6:9], v[178:181], v[218:221], v[6:9]
	v_mfma_f32_16x16x32_bf16 v[2:5], v[186:189], v[218:221], v[2:5]
	s_setprio 0
	s_barrier
	s_add_i32 s48, s48, 2
	s_add_u32 s20, s20, 0x100
	s_addc_u32 s21, s21, 0
	s_add_u32 s46, s46, 0x100
	s_addc_u32 s47, s47, 0
	s_cmpk_gt_u32 s48, 0x55
	s_cbranch_scc0 .LBB0_1704
	s_and_b64 vcc, exec, s[14:15]
	s_cbranch_vccz .LBB0_1707
	s_barrier

.LBB0_2308:
	ds_read_b128 v[74:77], v198
	ds_read_b128 v[78:81], v198 offset:1024
	ds_read_b128 v[86:89], v198 offset:2048
	ds_read_b128 v[98:101], v198 offset:3072
	ds_read_b128 v[146:149], v199
	ds_read_b128 v[150:153], v199 offset:1024
	ds_read_b128 v[154:157], v199 offset:2048
	ds_read_b128 v[158:161], v199 offset:3072
	s_add_u32 s28, s26, 0xfff80080
	s_addc_u32 s29, s27, -1
	s_cmp_eq_u32 s52, 28
	s_cselect_b32 s31, s17, s29
	s_cselect_b32 s30, s48, s28
	s_cselect_b32 s29, s15, s51
	s_cselect_b32 s28, s49, s50
	s_add_i32 m0, s25, 0xc000
	ds_read_b128 v[162:165], v200
	ds_read_b128 v[186:189], v200 offset:1024
	ds_read_b128 v[190:193], v200 offset:2048
	ds_read_b128 v[194:197], v200 offset:3072
	ds_read_b128 v[204:207], v200 offset:4096
	ds_read_b128 v[208:211], v200 offset:5120
	ds_read_b128 v[212:215], v200 offset:6144
	ds_read_b128 v[216:219], v200 offset:7168
	global_load_lds_dwordx4 v178, s[26:27]
	s_add_i32 m0, s25, 0xe000
	s_nop 0
	global_load_lds_dwordx4 v180, s[26:27]
	s_waitcnt vmcnt(8)
	s_waitcnt lgkmcnt(0)
	s_barrier
	s_setprio 1
	v_mfma_f32_16x16x32_bf16 v[142:145], v[74:77], v[162:165], v[142:145]
	v_mfma_f32_16x16x32_bf16 v[138:141], v[86:89], v[162:165], v[138:141]
	v_mfma_f32_16x16x32_bf16 v[126:129], v[74:77], v[190:193], v[126:129]
	v_mfma_f32_16x16x32_bf16 v[122:125], v[86:89], v[190:193], v[122:125]
	v_mfma_f32_16x16x32_bf16 v[110:113], v[74:77], v[204:207], v[110:113]
	v_mfma_f32_16x16x32_bf16 v[106:109], v[86:89], v[204:207], v[106:109]
	v_mfma_f32_16x16x32_bf16 v[90:93], v[74:77], v[212:215], v[90:93]
	v_mfma_f32_16x16x32_bf16 v[82:85], v[86:89], v[212:215], v[82:85]
	v_mfma_f32_16x16x32_bf16 v[142:145], v[78:81], v[186:189], v[142:145]
	v_mfma_f32_16x16x32_bf16 v[138:141], v[98:101], v[186:189], v[138:141]
	v_mfma_f32_16x16x32_bf16 v[126:129], v[78:81], v[194:197], v[126:129]
	v_mfma_f32_16x16x32_bf16 v[122:125], v[98:101], v[194:197], v[122:125]
	v_mfma_f32_16x16x32_bf16 v[110:113], v[78:81], v[208:211], v[110:113]
	v_mfma_f32_16x16x32_bf16 v[106:109], v[98:101], v[208:211], v[106:109]
	v_mfma_f32_16x16x32_bf16 v[90:93], v[78:81], v[216:219], v[90:93]
	v_mfma_f32_16x16x32_bf16 v[82:85], v[98:101], v[216:219], v[82:85]
	v_mfma_f32_16x16x32_bf16 v[134:137], v[146:149], v[162:165], v[134:137]
	v_mfma_f32_16x16x32_bf16 v[130:133], v[154:157], v[162:165], v[130:133]
	v_mfma_f32_16x16x32_bf16 v[118:121], v[146:149], v[190:193], v[118:121]
	v_mfma_f32_16x16x32_bf16 v[114:117], v[154:157], v[190:193], v[114:117]
	v_mfma_f32_16x16x32_bf16 v[102:105], v[146:149], v[204:207], v[102:105]
	v_mfma_f32_16x16x32_bf16 v[94:97], v[154:157], v[204:207], v[94:97]
	v_mfma_f32_16x16x32_bf16 v[70:73], v[146:149], v[212:215], v[70:73]
	v_mfma_f32_16x16x32_bf16 v[66:69], v[154:157], v[212:215], v[66:69]
	v_mfma_f32_16x16x32_bf16 v[134:137], v[150:153], v[186:189], v[134:137]
	v_mfma_f32_16x16x32_bf16 v[130:133], v[158:161], v[186:189], v[130:133]
	v_mfma_f32_16x16x32_bf16 v[118:121], v[150:153], v[194:197], v[118:121]
	v_mfma_f32_16x16x32_bf16 v[114:117], v[158:161], v[194:197], v[114:117]
	v_mfma_f32_16x16x32_bf16 v[102:105], v[150:153], v[208:211], v[102:105]
	v_mfma_f32_16x16x32_bf16 v[94:97], v[158:161], v[208:211], v[94:97]
	v_mfma_f32_16x16x32_bf16 v[70:73], v[150:153], v[216:219], v[70:73]
	v_mfma_f32_16x16x32_bf16 v[66:69], v[158:161], v[216:219], v[66:69]
	s_setprio 0
	s_barrier
	s_add_i32 s53, s43, s35
	v_lshl_add_u64 v[220:221], s[28:29], 0, v[172:173]
	s_mov_b32 m0, s53
	ds_read_b128 v[162:165], v200 offset:16384
	ds_read_b128 v[186:189], v200 offset:17408
	ds_read_b128 v[190:193], v200 offset:18432
	ds_read_b128 v[194:197], v200 offset:19456
	ds_read_b128 v[204:207], v200 offset:20480
	ds_read_b128 v[208:211], v200 offset:21504
	ds_read_b128 v[212:215], v200 offset:22528
	ds_read_b128 v[216:219], v200 offset:23552
	global_load_lds_dwordx4 v172, s[28:29]
	s_add_i32 m0, s53, 0x2000
	s_add_u32 s54, s28, 0x80000
	v_lshl_add_u64 v[222:223], s[28:29], 0, v[176:177]
	s_addc_u32 s55, s29, 0
	s_add_i32 s53, s44, s35
	global_load_lds_dwordx4 v176, s[28:29]
	s_mov_b32 m0, s53
	v_lshl_add_u64 v[226:227], s[30:31], 0, v[174:175]
	global_load_lds_dwordx4 v172, s[54:55]
	s_add_i32 m0, s53, 0x2000
	s_nop 0
	global_load_lds_dwordx4 v176, s[54:55]
	v_lshl_add_u64 v[224:225], s[30:31], 0, v[170:171]
	s_mov_b32 m0, s25
	s_nop 0
	global_load_lds_dwordx4 v170, s[30:31]
	s_mov_b32 m0, s36
	s_nop 0
	global_load_lds_dwordx4 v174, s[30:31]
	s_waitcnt vmcnt(8)
	s_waitcnt lgkmcnt(0)
	s_barrier
	s_setprio 1
	v_mfma_f32_16x16x32_bf16 v[62:65], v[74:77], v[162:165], v[62:65]
	v_mfma_f32_16x16x32_bf16 v[58:61], v[86:89], v[162:165], v[58:61]
	v_mfma_f32_16x16x32_bf16 v[46:49], v[74:77], v[190:193], v[46:49]
	v_mfma_f32_16x16x32_bf16 v[42:45], v[86:89], v[190:193], v[42:45]
	v_mfma_f32_16x16x32_bf16 v[30:33], v[74:77], v[204:207], v[30:33]
	v_mfma_f32_16x16x32_bf16 v[26:29], v[86:89], v[204:207], v[26:29]
	v_mfma_f32_16x16x32_bf16 v[14:17], v[74:77], v[212:215], v[14:17]
	v_mfma_f32_16x16x32_bf16 v[10:13], v[86:89], v[212:215], v[10:13]
	v_mfma_f32_16x16x32_bf16 v[62:65], v[78:81], v[186:189], v[62:65]
	v_mfma_f32_16x16x32_bf16 v[58:61], v[98:101], v[186:189], v[58:61]
	v_mfma_f32_16x16x32_bf16 v[46:49], v[78:81], v[194:197], v[46:49]
	v_mfma_f32_16x16x32_bf16 v[42:45], v[98:101], v[194:197], v[42:45]
	v_mfma_f32_16x16x32_bf16 v[30:33], v[78:81], v[208:211], v[30:33]
	v_mfma_f32_16x16x32_bf16 v[26:29], v[98:101], v[208:211], v[26:29]
	v_mfma_f32_16x16x32_bf16 v[14:17], v[78:81], v[216:219], v[14:17]
	v_mfma_f32_16x16x32_bf16 v[10:13], v[98:101], v[216:219], v[10:13]
	v_mfma_f32_16x16x32_bf16 v[54:57], v[146:149], v[162:165], v[54:57]
	v_mfma_f32_16x16x32_bf16 v[50:53], v[154:157], v[162:165], v[50:53]
	v_mfma_f32_16x16x32_bf16 v[38:41], v[146:149], v[190:193], v[38:41]
	v_mfma_f32_16x16x32_bf16 v[34:37], v[154:157], v[190:193], v[34:37]
	v_mfma_f32_16x16x32_bf16 v[22:25], v[146:149], v[204:207], v[22:25]
	v_mfma_f32_16x16x32_bf16 v[18:21], v[154:157], v[204:207], v[18:21]
	v_mfma_f32_16x16x32_bf16 v[6:9], v[146:149], v[212:215], v[6:9]
	v_mfma_f32_16x16x32_bf16 v[2:5], v[154:157], v[212:215], v[2:5]
	v_mfma_f32_16x16x32_bf16 v[54:57], v[150:153], v[186:189], v[54:57]
	v_mfma_f32_16x16x32_bf16 v[50:53], v[158:161], v[186:189], v[50:53]
	v_mfma_f32_16x16x32_bf16 v[38:41], v[150:153], v[194:197], v[38:41]
	v_mfma_f32_16x16x32_bf16 v[34:37], v[158:161], v[194:197], v[34:37]
	v_mfma_f32_16x16x32_bf16 v[22:25], v[150:153], v[208:211], v[22:25]
	v_mfma_f32_16x16x32_bf16 v[18:21], v[158:161], v[208:211], v[18:21]
	v_mfma_f32_16x16x32_bf16 v[6:9], v[150:153], v[216:219], v[6:9]
	v_mfma_f32_16x16x32_bf16 v[2:5], v[158:161], v[216:219], v[2:5]
	s_setprio 0
	s_barrier
	ds_read_b128 v[74:77], v201
	ds_read_b128 v[78:81], v201 offset:1024
	ds_read_b128 v[86:89], v201 offset:2048
	ds_read_b128 v[98:101], v201 offset:3072
	ds_read_b128 v[146:149], v202
	ds_read_b128 v[150:153], v202 offset:1024
	ds_read_b128 v[154:157], v202 offset:2048
	ds_read_b128 v[158:161], v202 offset:3072
	s_add_u32 s30, s30, 0x80000
	s_addc_u32 s31, s31, 0
	s_mov_b32 m0, s37
	ds_read_b128 v[162:165], v200 offset:32768
	ds_read_b128 v[186:189], v200 offset:33792
	ds_read_b128 v[190:193], v200 offset:34816
	ds_read_b128 v[194:197], v200 offset:35840
	ds_read_b128 v[204:207], v200 offset:36864
	ds_read_b128 v[208:211], v200 offset:37888
	ds_read_b128 v[212:215], v200 offset:38912
	ds_read_b128 v[216:219], v200 offset:39936
	global_load_lds_dwordx4 v170, s[30:31]
	s_mov_b32 m0, s38
	s_nop 0
	global_load_lds_dwordx4 v174, s[30:31]
	s_waitcnt vmcnt(8)
	s_waitcnt lgkmcnt(0)
	s_barrier
	s_setprio 1
	v_mfma_f32_16x16x32_bf16 v[142:145], v[74:77], v[162:165], v[142:145]
	v_mfma_f32_16x16x32_bf16 v[138:141], v[86:89], v[162:165], v[138:141]
	v_mfma_f32_16x16x32_bf16 v[126:129], v[74:77], v[190:193], v[126:129]
	v_mfma_f32_16x16x32_bf16 v[122:125], v[86:89], v[190:193], v[122:125]
	v_mfma_f32_16x16x32_bf16 v[110:113], v[74:77], v[204:207], v[110:113]
	v_mfma_f32_16x16x32_bf16 v[106:109], v[86:89], v[204:207], v[106:109]
	v_mfma_f32_16x16x32_bf16 v[90:93], v[74:77], v[212:215], v[90:93]
	v_mfma_f32_16x16x32_bf16 v[82:85], v[86:89], v[212:215], v[82:85]
	v_mfma_f32_16x16x32_bf16 v[142:145], v[78:81], v[186:189], v[142:145]
	v_mfma_f32_16x16x32_bf16 v[138:141], v[98:101], v[186:189], v[138:141]
	v_mfma_f32_16x16x32_bf16 v[126:129], v[78:81], v[194:197], v[126:129]
	v_mfma_f32_16x16x32_bf16 v[122:125], v[98:101], v[194:197], v[122:125]
	v_mfma_f32_16x16x32_bf16 v[110:113], v[78:81], v[208:211], v[110:113]
	v_mfma_f32_16x16x32_bf16 v[106:109], v[98:101], v[208:211], v[106:109]
	v_mfma_f32_16x16x32_bf16 v[90:93], v[78:81], v[216:219], v[90:93]
	v_mfma_f32_16x16x32_bf16 v[82:85], v[98:101], v[216:219], v[82:85]
	v_mfma_f32_16x16x32_bf16 v[134:137], v[146:149], v[162:165], v[134:137]
	v_mfma_f32_16x16x32_bf16 v[130:133], v[154:157], v[162:165], v[130:133]
	v_mfma_f32_16x16x32_bf16 v[118:121], v[146:149], v[190:193], v[118:121]
	v_mfma_f32_16x16x32_bf16 v[114:117], v[154:157], v[190:193], v[114:117]
	v_mfma_f32_16x16x32_bf16 v[102:105], v[146:149], v[204:207], v[102:105]
	v_mfma_f32_16x16x32_bf16 v[94:97], v[154:157], v[204:207], v[94:97]
	v_mfma_f32_16x16x32_bf16 v[70:73], v[146:149], v[212:215], v[70:73]
	v_mfma_f32_16x16x32_bf16 v[66:69], v[154:157], v[212:215], v[66:69]
	v_mfma_f32_16x16x32_bf16 v[134:137], v[150:153], v[186:189], v[134:137]
	v_mfma_f32_16x16x32_bf16 v[130:133], v[158:161], v[186:189], v[130:133]
	v_mfma_f32_16x16x32_bf16 v[118:121], v[150:153], v[194:197], v[118:121]
	v_mfma_f32_16x16x32_bf16 v[114:117], v[158:161], v[194:197], v[114:117]
	v_mfma_f32_16x16x32_bf16 v[102:105], v[150:153], v[208:211], v[102:105]
	v_mfma_f32_16x16x32_bf16 v[94:97], v[158:161], v[208:211], v[94:97]
	v_mfma_f32_16x16x32_bf16 v[70:73], v[150:153], v[216:219], v[70:73]
	v_mfma_f32_16x16x32_bf16 v[66:69], v[158:161], v[216:219], v[66:69]
	s_setprio 0
	s_barrier
	s_add_i32 s30, s45, s35
	v_lshl_add_u64 v[220:221], v[220:221], 0, s[6:7]
	s_mov_b32 m0, s30
	ds_read_b128 v[162:165], v200 offset:49152
	ds_read_b128 v[186:189], v200 offset:50176
	ds_read_b128 v[190:193], v200 offset:51200
	ds_read_b128 v[194:197], v200 offset:52224
	ds_read_b128 v[204:207], v200 offset:53248
	ds_read_b128 v[208:211], v200 offset:54272
	ds_read_b128 v[212:215], v200 offset:55296
	ds_read_b128 v[216:219], v200 offset:56320
	global_load_lds_dwordx4 v[220:221], off
	s_add_i32 m0, s30, 0x2000
	s_add_u32 s28, s28, 0x80080
	v_lshl_add_u64 v[220:221], v[222:223], 0, s[6:7]
	s_addc_u32 s29, s29, 0
	s_add_i32 s30, s46, s35
	global_load_lds_dwordx4 v[220:221], off
	s_mov_b32 m0, s30
	s_nop 0
	global_load_lds_dwordx4 v172, s[28:29]
	s_add_i32 m0, s30, 0x2000
	s_nop 0
	global_load_lds_dwordx4 v176, s[28:29]
	v_lshl_add_u64 v[220:221], v[224:225], 0, s[6:7]
	s_mov_b32 m0, s39
	s_nop 0
	global_load_lds_dwordx4 v[220:221], off
	v_lshl_add_u64 v[220:221], v[226:227], 0, s[6:7]
	s_mov_b32 m0, s40
	s_nop 0
	global_load_lds_dwordx4 v[220:221], off
	s_waitcnt vmcnt(8)
	s_waitcnt lgkmcnt(0)
	s_barrier
	s_setprio 1
	v_mfma_f32_16x16x32_bf16 v[62:65], v[74:77], v[162:165], v[62:65]
	v_mfma_f32_16x16x32_bf16 v[58:61], v[86:89], v[162:165], v[58:61]
	v_mfma_f32_16x16x32_bf16 v[46:49], v[74:77], v[190:193], v[46:49]
	v_mfma_f32_16x16x32_bf16 v[42:45], v[86:89], v[190:193], v[42:45]
	v_mfma_f32_16x16x32_bf16 v[30:33], v[74:77], v[204:207], v[30:33]
	v_mfma_f32_16x16x32_bf16 v[26:29], v[86:89], v[204:207], v[26:29]
	v_mfma_f32_16x16x32_bf16 v[14:17], v[74:77], v[212:215], v[14:17]
	v_mfma_f32_16x16x32_bf16 v[10:13], v[86:89], v[212:215], v[10:13]
	v_mfma_f32_16x16x32_bf16 v[62:65], v[78:81], v[186:189], v[62:65]
	v_mfma_f32_16x16x32_bf16 v[58:61], v[98:101], v[186:189], v[58:61]
	v_mfma_f32_16x16x32_bf16 v[46:49], v[78:81], v[194:197], v[46:49]
	v_mfma_f32_16x16x32_bf16 v[42:45], v[98:101], v[194:197], v[42:45]
	v_mfma_f32_16x16x32_bf16 v[30:33], v[78:81], v[208:211], v[30:33]
	v_mfma_f32_16x16x32_bf16 v[26:29], v[98:101], v[208:211], v[26:29]
	v_mfma_f32_16x16x32_bf16 v[14:17], v[78:81], v[216:219], v[14:17]
	v_mfma_f32_16x16x32_bf16 v[10:13], v[98:101], v[216:219], v[10:13]
	v_mfma_f32_16x16x32_bf16 v[54:57], v[146:149], v[162:165], v[54:57]
	v_mfma_f32_16x16x32_bf16 v[50:53], v[154:157], v[162:165], v[50:53]
	v_mfma_f32_16x16x32_bf16 v[38:41], v[146:149], v[190:193], v[38:41]
	v_mfma_f32_16x16x32_bf16 v[34:37], v[154:157], v[190:193], v[34:37]
	v_mfma_f32_16x16x32_bf16 v[22:25], v[146:149], v[204:207], v[22:25]
	v_mfma_f32_16x16x32_bf16 v[18:21], v[154:157], v[204:207], v[18:21]
	v_mfma_f32_16x16x32_bf16 v[6:9], v[146:149], v[212:215], v[6:9]
	v_mfma_f32_16x16x32_bf16 v[2:5], v[154:157], v[212:215], v[2:5]
	v_mfma_f32_16x16x32_bf16 v[54:57], v[150:153], v[186:189], v[54:57]
	v_mfma_f32_16x16x32_bf16 v[50:53], v[158:161], v[186:189], v[50:53]
	v_mfma_f32_16x16x32_bf16 v[38:41], v[150:153], v[194:197], v[38:41]
	v_mfma_f32_16x16x32_bf16 v[34:37], v[158:161], v[194:197], v[34:37]
	v_mfma_f32_16x16x32_bf16 v[22:25], v[150:153], v[208:211], v[22:25]
	v_mfma_f32_16x16x32_bf16 v[18:21], v[158:161], v[208:211], v[18:21]
	v_mfma_f32_16x16x32_bf16 v[6:9], v[150:153], v[216:219], v[6:9]
	v_mfma_f32_16x16x32_bf16 v[2:5], v[158:161], v[216:219], v[2:5]
	s_setprio 0
	s_barrier
	s_add_i32 s52, s52, 2
	s_add_u32 s26, s26, 0x100
	s_addc_u32 s27, s27, 0
	s_add_u32 s50, s50, 0x100
	s_addc_u32 s51, s51, 0
	s_cmp_gt_u32 s52, 29
	s_cbranch_scc0 .LBB0_2308
	s_and_b64 vcc, exec, s[10:11]
	s_cbranch_vccz .LBB0_2311
	s_barrier

.LBB0_2470:
	ds_read_b128 v[146:149], v178
	ds_read_b128 v[150:153], v178 offset:1024
	ds_read_b128 v[154:157], v178 offset:2048
	ds_read_b128 v[158:161], v178 offset:3072
	ds_read_b128 v[182:185], v179
	ds_read_b128 v[186:189], v179 offset:1024
	ds_read_b128 v[190:193], v179 offset:2048
	ds_read_b128 v[194:197], v179 offset:3072
	s_add_u32 s30, s28, 0xfffc0080
	s_addc_u32 s31, s29, -1
	s_cmp_eq_u32 s57, 12
	s_cselect_b32 s35, s21, s31
	s_cselect_b32 s34, s53, s30
	s_cselect_b32 s31, s17, s56
	s_cselect_b32 s30, s54, s55
	s_add_i32 m0, s27, 0xc000
	ds_read_b128 v[198:201], v180
	ds_read_b128 v[202:205], v180 offset:1024
	ds_read_b128 v[206:209], v180 offset:2048
	ds_read_b128 v[210:213], v180 offset:3072
	ds_read_b128 v[214:217], v180 offset:4096
	ds_read_b128 v[218:221], v180 offset:5120
	ds_read_b128 v[222:225], v180 offset:6144
	ds_read_b128 v[226:229], v180 offset:7168
	global_load_lds_dwordx4 v138, s[28:29]
	s_add_i32 m0, s27, 0xe000
	s_nop 0
	global_load_lds_dwordx4 v140, s[28:29]
	s_waitcnt vmcnt(8)
	s_waitcnt lgkmcnt(0)
	s_barrier
	s_setprio 1
	v_mfma_i32_16x16x64_i8 v[126:129], v[146:149], v[198:201], v[126:129]
	v_mfma_i32_16x16x64_i8 v[118:121], v[154:157], v[198:201], v[118:121]
	v_mfma_i32_16x16x64_i8 v[110:113], v[146:149], v[206:209], v[110:113]
	v_mfma_i32_16x16x64_i8 v[102:105], v[154:157], v[206:209], v[102:105]
	v_mfma_i32_16x16x64_i8 v[94:97], v[146:149], v[214:217], v[94:97]
	v_mfma_i32_16x16x64_i8 v[86:89], v[154:157], v[214:217], v[86:89]
	v_mfma_i32_16x16x64_i8 v[78:81], v[146:149], v[222:225], v[78:81]
	v_mfma_i32_16x16x64_i8 v[70:73], v[154:157], v[222:225], v[70:73]
	v_mfma_i32_16x16x64_i8 v[126:129], v[150:153], v[202:205], v[126:129]
	v_mfma_i32_16x16x64_i8 v[118:121], v[158:161], v[202:205], v[118:121]
	v_mfma_i32_16x16x64_i8 v[110:113], v[150:153], v[210:213], v[110:113]
	v_mfma_i32_16x16x64_i8 v[102:105], v[158:161], v[210:213], v[102:105]
	v_mfma_i32_16x16x64_i8 v[94:97], v[150:153], v[218:221], v[94:97]
	v_mfma_i32_16x16x64_i8 v[86:89], v[158:161], v[218:221], v[86:89]
	v_mfma_i32_16x16x64_i8 v[78:81], v[150:153], v[226:229], v[78:81]
	v_mfma_i32_16x16x64_i8 v[70:73], v[158:161], v[226:229], v[70:73]
	v_mfma_i32_16x16x64_i8 v[122:125], v[182:185], v[198:201], v[122:125]
	v_mfma_i32_16x16x64_i8 v[114:117], v[190:193], v[198:201], v[114:117]
	v_mfma_i32_16x16x64_i8 v[106:109], v[182:185], v[206:209], v[106:109]
	v_mfma_i32_16x16x64_i8 v[98:101], v[190:193], v[206:209], v[98:101]
	v_mfma_i32_16x16x64_i8 v[90:93], v[182:185], v[214:217], v[90:93]
	v_mfma_i32_16x16x64_i8 v[82:85], v[190:193], v[214:217], v[82:85]
	v_mfma_i32_16x16x64_i8 v[74:77], v[182:185], v[222:225], v[74:77]
	v_mfma_i32_16x16x64_i8 v[66:69], v[190:193], v[222:225], v[66:69]
	v_mfma_i32_16x16x64_i8 v[122:125], v[186:189], v[202:205], v[122:125]
	v_mfma_i32_16x16x64_i8 v[114:117], v[194:197], v[202:205], v[114:117]
	v_mfma_i32_16x16x64_i8 v[106:109], v[186:189], v[210:213], v[106:109]
	v_mfma_i32_16x16x64_i8 v[98:101], v[194:197], v[210:213], v[98:101]
	v_mfma_i32_16x16x64_i8 v[90:93], v[186:189], v[218:221], v[90:93]
	v_mfma_i32_16x16x64_i8 v[82:85], v[194:197], v[218:221], v[82:85]
	v_mfma_i32_16x16x64_i8 v[74:77], v[186:189], v[226:229], v[74:77]
	v_mfma_i32_16x16x64_i8 v[66:69], v[194:197], v[226:229], v[66:69]
	s_setprio 0
	s_barrier
	s_add_i32 s63, s46, s38
	v_lshl_add_u64 v[162:163], s[30:31], 0, v[134:135]
	s_mov_b32 m0, s63
	ds_read_b128 v[198:201], v180 offset:16384
	ds_read_b128 v[202:205], v180 offset:17408
	ds_read_b128 v[206:209], v180 offset:18432
	ds_read_b128 v[210:213], v180 offset:19456
	ds_read_b128 v[214:217], v180 offset:20480
	ds_read_b128 v[218:221], v180 offset:21504
	ds_read_b128 v[222:225], v180 offset:22528
	ds_read_b128 v[226:229], v180 offset:23552
	global_load_lds_dwordx4 v134, s[30:31]
	s_add_i32 m0, s63, 0x2000
	s_add_u32 s68, s30, 0x40000
	v_lshl_add_u64 v[230:231], s[30:31], 0, v[130:131]
	s_addc_u32 s69, s31, 0
	s_add_i32 s63, s47, s38
	global_load_lds_dwordx4 v130, s[30:31]
	s_mov_b32 m0, s63
	v_lshl_add_u64 v[234:235], s[34:35], 0, v[132:133]
	global_load_lds_dwordx4 v134, s[68:69]
	s_add_i32 m0, s63, 0x2000
	s_nop 0
	global_load_lds_dwordx4 v130, s[68:69]
	v_lshl_add_u64 v[232:233], s[34:35], 0, v[136:137]
	s_mov_b32 m0, s27
	s_nop 0
	global_load_lds_dwordx4 v136, s[34:35]
	s_mov_b32 m0, s40
	s_nop 0
	global_load_lds_dwordx4 v132, s[34:35]
	s_waitcnt vmcnt(8)
	s_waitcnt lgkmcnt(0)
	s_barrier
	s_setprio 1
	v_mfma_i32_16x16x64_i8 v[62:65], v[146:149], v[198:201], v[62:65]
	v_mfma_i32_16x16x64_i8 v[54:57], v[154:157], v[198:201], v[54:57]
	v_mfma_i32_16x16x64_i8 v[46:49], v[146:149], v[206:209], v[46:49]
	v_mfma_i32_16x16x64_i8 v[38:41], v[154:157], v[206:209], v[38:41]
	v_mfma_i32_16x16x64_i8 v[30:33], v[146:149], v[214:217], v[30:33]
	v_mfma_i32_16x16x64_i8 v[22:25], v[154:157], v[214:217], v[22:25]
	v_mfma_i32_16x16x64_i8 v[14:17], v[146:149], v[222:225], v[14:17]
	v_mfma_i32_16x16x64_i8 v[6:9], v[154:157], v[222:225], v[6:9]
	v_mfma_i32_16x16x64_i8 v[62:65], v[150:153], v[202:205], v[62:65]
	v_mfma_i32_16x16x64_i8 v[54:57], v[158:161], v[202:205], v[54:57]
	v_mfma_i32_16x16x64_i8 v[46:49], v[150:153], v[210:213], v[46:49]
	v_mfma_i32_16x16x64_i8 v[38:41], v[158:161], v[210:213], v[38:41]
	v_mfma_i32_16x16x64_i8 v[30:33], v[150:153], v[218:221], v[30:33]
	v_mfma_i32_16x16x64_i8 v[22:25], v[158:161], v[218:221], v[22:25]
	v_mfma_i32_16x16x64_i8 v[14:17], v[150:153], v[226:229], v[14:17]
	v_mfma_i32_16x16x64_i8 v[6:9], v[158:161], v[226:229], v[6:9]
	v_mfma_i32_16x16x64_i8 v[58:61], v[182:185], v[198:201], v[58:61]
	v_mfma_i32_16x16x64_i8 v[50:53], v[190:193], v[198:201], v[50:53]
	v_mfma_i32_16x16x64_i8 v[42:45], v[182:185], v[206:209], v[42:45]
	v_mfma_i32_16x16x64_i8 v[34:37], v[190:193], v[206:209], v[34:37]
	v_mfma_i32_16x16x64_i8 v[26:29], v[182:185], v[214:217], v[26:29]
	v_mfma_i32_16x16x64_i8 v[18:21], v[190:193], v[214:217], v[18:21]
	v_mfma_i32_16x16x64_i8 v[10:13], v[182:185], v[222:225], v[10:13]
	v_mfma_i32_16x16x64_i8 v[2:5], v[190:193], v[222:225], v[2:5]
	v_mfma_i32_16x16x64_i8 v[58:61], v[186:189], v[202:205], v[58:61]
	v_mfma_i32_16x16x64_i8 v[50:53], v[194:197], v[202:205], v[50:53]
	v_mfma_i32_16x16x64_i8 v[42:45], v[186:189], v[210:213], v[42:45]
	v_mfma_i32_16x16x64_i8 v[34:37], v[194:197], v[210:213], v[34:37]
	v_mfma_i32_16x16x64_i8 v[26:29], v[186:189], v[218:221], v[26:29]
	v_mfma_i32_16x16x64_i8 v[18:21], v[194:197], v[218:221], v[18:21]
	v_mfma_i32_16x16x64_i8 v[10:13], v[186:189], v[226:229], v[10:13]
	v_mfma_i32_16x16x64_i8 v[2:5], v[194:197], v[226:229], v[2:5]
	s_setprio 0
	s_barrier
	s_add_i32 s63, 0, 0x18000
	v_add_u32_e32 v158, s63, v169
	ds_read_b128 v[146:149], v158
	ds_read_b128 v[150:153], v158 offset:1024
	ds_read_b128 v[154:157], v158 offset:2048
	ds_read_b128 v[158:161], v158 offset:3072
	ds_read_b128 v[182:185], v181
	ds_read_b128 v[186:189], v181 offset:1024
	ds_read_b128 v[190:193], v181 offset:2048
	ds_read_b128 v[194:197], v181 offset:3072
	s_add_u32 s34, s34, 0x40000
	s_addc_u32 s35, s35, 0
	s_mov_b32 m0, s41
	ds_read_b128 v[198:201], v180 offset:32768
	ds_read_b128 v[202:205], v180 offset:33792
	ds_read_b128 v[206:209], v180 offset:34816
	ds_read_b128 v[210:213], v180 offset:35840
	ds_read_b128 v[214:217], v180 offset:36864
	ds_read_b128 v[218:221], v180 offset:37888
	ds_read_b128 v[222:225], v180 offset:38912
	ds_read_b128 v[226:229], v180 offset:39936
	global_load_lds_dwordx4 v136, s[34:35]
	s_mov_b32 m0, s42
	s_nop 0
	global_load_lds_dwordx4 v132, s[34:35]
	s_waitcnt vmcnt(8)
	s_waitcnt lgkmcnt(0)
	s_barrier
	s_setprio 1
	v_mfma_i32_16x16x64_i8 v[126:129], v[146:149], v[198:201], v[126:129]
	v_mfma_i32_16x16x64_i8 v[118:121], v[154:157], v[198:201], v[118:121]
	v_mfma_i32_16x16x64_i8 v[110:113], v[146:149], v[206:209], v[110:113]
	v_mfma_i32_16x16x64_i8 v[102:105], v[154:157], v[206:209], v[102:105]
	v_mfma_i32_16x16x64_i8 v[94:97], v[146:149], v[214:217], v[94:97]
	v_mfma_i32_16x16x64_i8 v[86:89], v[154:157], v[214:217], v[86:89]
	v_mfma_i32_16x16x64_i8 v[78:81], v[146:149], v[222:225], v[78:81]
	v_mfma_i32_16x16x64_i8 v[70:73], v[154:157], v[222:225], v[70:73]
	v_mfma_i32_16x16x64_i8 v[126:129], v[150:153], v[202:205], v[126:129]
	v_mfma_i32_16x16x64_i8 v[118:121], v[158:161], v[202:205], v[118:121]
	v_mfma_i32_16x16x64_i8 v[110:113], v[150:153], v[210:213], v[110:113]
	v_mfma_i32_16x16x64_i8 v[102:105], v[158:161], v[210:213], v[102:105]
	v_mfma_i32_16x16x64_i8 v[94:97], v[150:153], v[218:221], v[94:97]
	v_mfma_i32_16x16x64_i8 v[86:89], v[158:161], v[218:221], v[86:89]
	v_mfma_i32_16x16x64_i8 v[78:81], v[150:153], v[226:229], v[78:81]
	v_mfma_i32_16x16x64_i8 v[70:73], v[158:161], v[226:229], v[70:73]
	v_mfma_i32_16x16x64_i8 v[122:125], v[182:185], v[198:201], v[122:125]
	v_mfma_i32_16x16x64_i8 v[114:117], v[190:193], v[198:201], v[114:117]
	v_mfma_i32_16x16x64_i8 v[106:109], v[182:185], v[206:209], v[106:109]
	v_mfma_i32_16x16x64_i8 v[98:101], v[190:193], v[206:209], v[98:101]
	v_mfma_i32_16x16x64_i8 v[90:93], v[182:185], v[214:217], v[90:93]
	v_mfma_i32_16x16x64_i8 v[82:85], v[190:193], v[214:217], v[82:85]
	v_mfma_i32_16x16x64_i8 v[74:77], v[182:185], v[222:225], v[74:77]
	v_mfma_i32_16x16x64_i8 v[66:69], v[190:193], v[222:225], v[66:69]
	v_mfma_i32_16x16x64_i8 v[122:125], v[186:189], v[202:205], v[122:125]
	v_mfma_i32_16x16x64_i8 v[114:117], v[194:197], v[202:205], v[114:117]
	v_mfma_i32_16x16x64_i8 v[106:109], v[186:189], v[210:213], v[106:109]
	v_mfma_i32_16x16x64_i8 v[98:101], v[194:197], v[210:213], v[98:101]
	v_mfma_i32_16x16x64_i8 v[90:93], v[186:189], v[218:221], v[90:93]
	v_mfma_i32_16x16x64_i8 v[82:85], v[194:197], v[218:221], v[82:85]
	v_mfma_i32_16x16x64_i8 v[74:77], v[186:189], v[226:229], v[74:77]
	v_mfma_i32_16x16x64_i8 v[66:69], v[194:197], v[226:229], v[66:69]
	s_setprio 0
	s_barrier
	s_add_i32 s34, s63, s38
	v_lshl_add_u64 v[162:163], v[162:163], 0, s[8:9]
	s_mov_b32 m0, s34
	ds_read_b128 v[198:201], v180 offset:49152
	ds_read_b128 v[202:205], v180 offset:50176
	ds_read_b128 v[206:209], v180 offset:51200
	ds_read_b128 v[210:213], v180 offset:52224
	ds_read_b128 v[214:217], v180 offset:53248
	ds_read_b128 v[218:221], v180 offset:54272
	ds_read_b128 v[222:225], v180 offset:55296
	ds_read_b128 v[226:229], v180 offset:56320
	global_load_lds_dwordx4 v[162:163], off
	s_add_i32 m0, s34, 0x2000
	s_add_u32 s30, s30, 0x40080
	v_lshl_add_u64 v[162:163], v[230:231], 0, s[8:9]
	s_addc_u32 s31, s31, 0
	s_add_i32 s34, s48, s38
	global_load_lds_dwordx4 v[162:163], off
	s_mov_b32 m0, s34
	s_nop 0
	global_load_lds_dwordx4 v134, s[30:31]
	s_add_i32 m0, s34, 0x2000
	s_nop 0
	global_load_lds_dwordx4 v130, s[30:31]
	v_lshl_add_u64 v[162:163], v[232:233], 0, s[8:9]
	s_mov_b32 m0, s43
	s_nop 0
	global_load_lds_dwordx4 v[162:163], off
	v_lshl_add_u64 v[162:163], v[234:235], 0, s[8:9]
	s_mov_b32 m0, s44
	s_nop 0
	global_load_lds_dwordx4 v[162:163], off
	s_waitcnt vmcnt(8)
	s_waitcnt lgkmcnt(0)
	s_barrier
	s_setprio 1
	v_mfma_i32_16x16x64_i8 v[62:65], v[146:149], v[198:201], v[62:65]
	v_mfma_i32_16x16x64_i8 v[54:57], v[154:157], v[198:201], v[54:57]
	v_mfma_i32_16x16x64_i8 v[46:49], v[146:149], v[206:209], v[46:49]
	v_mfma_i32_16x16x64_i8 v[38:41], v[154:157], v[206:209], v[38:41]
	v_mfma_i32_16x16x64_i8 v[30:33], v[146:149], v[214:217], v[30:33]
	v_mfma_i32_16x16x64_i8 v[22:25], v[154:157], v[214:217], v[22:25]
	v_mfma_i32_16x16x64_i8 v[14:17], v[146:149], v[222:225], v[14:17]
	v_mfma_i32_16x16x64_i8 v[6:9], v[154:157], v[222:225], v[6:9]
	v_mfma_i32_16x16x64_i8 v[62:65], v[150:153], v[202:205], v[62:65]
	v_mfma_i32_16x16x64_i8 v[54:57], v[158:161], v[202:205], v[54:57]
	v_mfma_i32_16x16x64_i8 v[46:49], v[150:153], v[210:213], v[46:49]
	v_mfma_i32_16x16x64_i8 v[38:41], v[158:161], v[210:213], v[38:41]
	v_mfma_i32_16x16x64_i8 v[30:33], v[150:153], v[218:221], v[30:33]
	v_mfma_i32_16x16x64_i8 v[22:25], v[158:161], v[218:221], v[22:25]
	v_mfma_i32_16x16x64_i8 v[14:17], v[150:153], v[226:229], v[14:17]
	v_mfma_i32_16x16x64_i8 v[6:9], v[158:161], v[226:229], v[6:9]
	v_mfma_i32_16x16x64_i8 v[58:61], v[182:185], v[198:201], v[58:61]
	v_mfma_i32_16x16x64_i8 v[50:53], v[190:193], v[198:201], v[50:53]
	v_mfma_i32_16x16x64_i8 v[42:45], v[182:185], v[206:209], v[42:45]
	v_mfma_i32_16x16x64_i8 v[34:37], v[190:193], v[206:209], v[34:37]
	v_mfma_i32_16x16x64_i8 v[26:29], v[182:185], v[214:217], v[26:29]
	v_mfma_i32_16x16x64_i8 v[18:21], v[190:193], v[214:217], v[18:21]
	v_mfma_i32_16x16x64_i8 v[10:13], v[182:185], v[222:225], v[10:13]
	v_mfma_i32_16x16x64_i8 v[2:5], v[190:193], v[222:225], v[2:5]
	v_mfma_i32_16x16x64_i8 v[58:61], v[186:189], v[202:205], v[58:61]
	v_mfma_i32_16x16x64_i8 v[50:53], v[194:197], v[202:205], v[50:53]
	v_mfma_i32_16x16x64_i8 v[42:45], v[186:189], v[210:213], v[42:45]
	v_mfma_i32_16x16x64_i8 v[34:37], v[194:197], v[210:213], v[34:37]
	v_mfma_i32_16x16x64_i8 v[26:29], v[186:189], v[218:221], v[26:29]
	v_mfma_i32_16x16x64_i8 v[18:21], v[194:197], v[218:221], v[18:21]
	v_mfma_i32_16x16x64_i8 v[10:13], v[186:189], v[226:229], v[10:13]
	v_mfma_i32_16x16x64_i8 v[2:5], v[194:197], v[226:229], v[2:5]
	s_setprio 0
	s_barrier
	s_add_i32 s57, s57, 2
	s_add_u32 s28, s28, 0x100
	s_addc_u32 s29, s29, 0
	s_add_u32 s55, s55, 0x100
	s_addc_u32 s56, s56, 0
	s_cmp_gt_u32 s57, 13
	s_cbranch_scc0 .LBB0_2470
	s_and_b64 vcc, exec, s[12:13]
	s_cbranch_vccz .LBB0_2473
	s_barrier

.LBB0_2579:
	ds_read_b128 v[154:157], v149
	ds_read_b128 v[158:161], v149 offset:1024
	ds_read_b128 v[162:165], v149 offset:2048
	ds_read_b128 v[170:173], v149 offset:3072
	ds_read_b128 v[174:177], v150
	ds_read_b128 v[178:181], v150 offset:1024
	ds_read_b128 v[182:185], v150 offset:2048
	ds_read_b128 v[186:189], v150 offset:3072
	s_add_u32 s24, s22, 0xffea0080
	s_addc_u32 s25, s23, -1
	s_cmpk_eq_i32 s53, 0x54
	s_cselect_b32 s27, s5, s25
	s_cselect_b32 s26, s4, s24
	s_cselect_b32 s25, s21, s52
	s_cselect_b32 s24, s20, s51
	s_add_i32 m0, s30, 0xc000
	ds_read_b128 v[190:193], v151
	ds_read_b128 v[194:197], v151 offset:1024
	ds_read_b128 v[198:201], v151 offset:2048
	ds_read_b128 v[202:205], v151 offset:3072
	ds_read_b128 v[206:209], v151 offset:4096
	ds_read_b128 v[210:213], v151 offset:5120
	ds_read_b128 v[214:217], v151 offset:6144
	ds_read_b128 v[218:221], v151 offset:7168
	global_load_lds_dwordx4 v138, s[22:23]
	s_add_i32 m0, s30, 0xe000
	s_nop 0
	global_load_lds_dwordx4 v140, s[22:23]
	s_waitcnt vmcnt(8)
	s_waitcnt lgkmcnt(0)
	s_barrier
	s_setprio 1
	v_mfma_f32_16x16x32_bf16 v[126:129], v[154:157], v[190:193], v[126:129]
	v_mfma_f32_16x16x32_bf16 v[122:125], v[162:165], v[190:193], v[122:125]
	v_mfma_f32_16x16x32_bf16 v[118:121], v[154:157], v[198:201], v[118:121]
	v_mfma_f32_16x16x32_bf16 v[110:113], v[162:165], v[198:201], v[110:113]
	v_mfma_f32_16x16x32_bf16 v[102:105], v[154:157], v[206:209], v[102:105]
	v_mfma_f32_16x16x32_bf16 v[94:97], v[162:165], v[206:209], v[94:97]
	v_mfma_f32_16x16x32_bf16 v[86:89], v[154:157], v[214:217], v[86:89]
	v_mfma_f32_16x16x32_bf16 v[78:81], v[162:165], v[214:217], v[78:81]
	v_mfma_f32_16x16x32_bf16 v[126:129], v[158:161], v[194:197], v[126:129]
	v_mfma_f32_16x16x32_bf16 v[122:125], v[170:173], v[194:197], v[122:125]
	v_mfma_f32_16x16x32_bf16 v[118:121], v[158:161], v[202:205], v[118:121]
	v_mfma_f32_16x16x32_bf16 v[110:113], v[170:173], v[202:205], v[110:113]
	v_mfma_f32_16x16x32_bf16 v[102:105], v[158:161], v[210:213], v[102:105]
	v_mfma_f32_16x16x32_bf16 v[94:97], v[170:173], v[210:213], v[94:97]
	v_mfma_f32_16x16x32_bf16 v[86:89], v[158:161], v[218:221], v[86:89]
	v_mfma_f32_16x16x32_bf16 v[78:81], v[170:173], v[218:221], v[78:81]
	v_mfma_f32_16x16x32_bf16 v[114:117], v[174:177], v[190:193], v[114:117]
	v_mfma_f32_16x16x32_bf16 v[106:109], v[182:185], v[190:193], v[106:109]
	v_mfma_f32_16x16x32_bf16 v[98:101], v[174:177], v[198:201], v[98:101]
	v_mfma_f32_16x16x32_bf16 v[90:93], v[182:185], v[198:201], v[90:93]
	v_mfma_f32_16x16x32_bf16 v[82:85], v[174:177], v[206:209], v[82:85]
	v_mfma_f32_16x16x32_bf16 v[74:77], v[182:185], v[206:209], v[74:77]
	v_mfma_f32_16x16x32_bf16 v[70:73], v[174:177], v[214:217], v[70:73]
	v_mfma_f32_16x16x32_bf16 v[66:69], v[182:185], v[214:217], v[66:69]
	v_mfma_f32_16x16x32_bf16 v[114:117], v[178:181], v[194:197], v[114:117]
	v_mfma_f32_16x16x32_bf16 v[106:109], v[186:189], v[194:197], v[106:109]
	v_mfma_f32_16x16x32_bf16 v[98:101], v[178:181], v[202:205], v[98:101]
	v_mfma_f32_16x16x32_bf16 v[90:93], v[186:189], v[202:205], v[90:93]
	v_mfma_f32_16x16x32_bf16 v[82:85], v[178:181], v[210:213], v[82:85]
	v_mfma_f32_16x16x32_bf16 v[74:77], v[186:189], v[210:213], v[74:77]
	v_mfma_f32_16x16x32_bf16 v[70:73], v[178:181], v[218:221], v[70:73]
	v_mfma_f32_16x16x32_bf16 v[66:69], v[186:189], v[218:221], v[66:69]
	s_setprio 0
	s_barrier
	s_add_i32 s54, s40, s29
	v_lshl_add_u64 v[146:147], s[24:25], 0, v[132:133]
	s_mov_b32 m0, s54
	ds_read_b128 v[190:193], v151 offset:16384
	ds_read_b128 v[194:197], v151 offset:17408
	ds_read_b128 v[198:201], v151 offset:18432
	ds_read_b128 v[202:205], v151 offset:19456
	ds_read_b128 v[206:209], v151 offset:20480
	ds_read_b128 v[210:213], v151 offset:21504
	ds_read_b128 v[214:217], v151 offset:22528
	ds_read_b128 v[218:221], v151 offset:23552
	global_load_lds_dwordx4 v132, s[24:25]
	s_add_i32 m0, s54, 0x2000
	s_add_u32 s54, s24, 0x160000
	v_lshl_add_u64 v[222:223], s[24:25], 0, v[136:137]
	s_addc_u32 s55, s25, 0
	s_add_i32 s56, s41, s29
	global_load_lds_dwordx4 v136, s[24:25]
	s_mov_b32 m0, s56
	v_lshl_add_u64 v[226:227], s[26:27], 0, v[134:135]
	global_load_lds_dwordx4 v132, s[54:55]
	s_add_i32 m0, s56, 0x2000
	s_nop 0
	global_load_lds_dwordx4 v136, s[54:55]
	v_lshl_add_u64 v[224:225], s[26:27], 0, v[130:131]
	s_mov_b32 m0, s30
	s_nop 0
	global_load_lds_dwordx4 v130, s[26:27]
	s_mov_b32 m0, s31
	s_nop 0
	global_load_lds_dwordx4 v134, s[26:27]
	s_waitcnt vmcnt(8)
	s_waitcnt lgkmcnt(0)
	s_barrier
	s_setprio 1
	v_mfma_f32_16x16x32_bf16 v[62:65], v[154:157], v[190:193], v[62:65]
	v_mfma_f32_16x16x32_bf16 v[58:61], v[162:165], v[190:193], v[58:61]
	v_mfma_f32_16x16x32_bf16 v[54:57], v[154:157], v[198:201], v[54:57]
	v_mfma_f32_16x16x32_bf16 v[46:49], v[162:165], v[198:201], v[46:49]
	v_mfma_f32_16x16x32_bf16 v[38:41], v[154:157], v[206:209], v[38:41]
	v_mfma_f32_16x16x32_bf16 v[30:33], v[162:165], v[206:209], v[30:33]
	v_mfma_f32_16x16x32_bf16 v[22:25], v[154:157], v[214:217], v[22:25]
	v_mfma_f32_16x16x32_bf16 v[14:17], v[162:165], v[214:217], v[14:17]
	v_mfma_f32_16x16x32_bf16 v[62:65], v[158:161], v[194:197], v[62:65]
	v_mfma_f32_16x16x32_bf16 v[58:61], v[170:173], v[194:197], v[58:61]
	v_mfma_f32_16x16x32_bf16 v[54:57], v[158:161], v[202:205], v[54:57]
	v_mfma_f32_16x16x32_bf16 v[46:49], v[170:173], v[202:205], v[46:49]
	v_mfma_f32_16x16x32_bf16 v[38:41], v[158:161], v[210:213], v[38:41]
	v_mfma_f32_16x16x32_bf16 v[30:33], v[170:173], v[210:213], v[30:33]
	v_mfma_f32_16x16x32_bf16 v[22:25], v[158:161], v[218:221], v[22:25]
	v_mfma_f32_16x16x32_bf16 v[14:17], v[170:173], v[218:221], v[14:17]
	v_mfma_f32_16x16x32_bf16 v[50:53], v[174:177], v[190:193], v[50:53]
	v_mfma_f32_16x16x32_bf16 v[42:45], v[182:185], v[190:193], v[42:45]
	v_mfma_f32_16x16x32_bf16 v[34:37], v[174:177], v[198:201], v[34:37]
	v_mfma_f32_16x16x32_bf16 v[26:29], v[182:185], v[198:201], v[26:29]
	v_mfma_f32_16x16x32_bf16 v[18:21], v[174:177], v[206:209], v[18:21]
	v_mfma_f32_16x16x32_bf16 v[10:13], v[182:185], v[206:209], v[10:13]
	v_mfma_f32_16x16x32_bf16 v[6:9], v[174:177], v[214:217], v[6:9]
	v_mfma_f32_16x16x32_bf16 v[2:5], v[182:185], v[214:217], v[2:5]
	v_mfma_f32_16x16x32_bf16 v[50:53], v[178:181], v[194:197], v[50:53]
	v_mfma_f32_16x16x32_bf16 v[42:45], v[186:189], v[194:197], v[42:45]
	v_mfma_f32_16x16x32_bf16 v[34:37], v[178:181], v[202:205], v[34:37]
	v_mfma_f32_16x16x32_bf16 v[26:29], v[186:189], v[202:205], v[26:29]
	v_mfma_f32_16x16x32_bf16 v[18:21], v[178:181], v[210:213], v[18:21]
	v_mfma_f32_16x16x32_bf16 v[10:13], v[186:189], v[210:213], v[10:13]
	v_mfma_f32_16x16x32_bf16 v[6:9], v[178:181], v[218:221], v[6:9]
	v_mfma_f32_16x16x32_bf16 v[2:5], v[186:189], v[218:221], v[2:5]
	s_setprio 0
	s_barrier
	ds_read_b128 v[154:157], v152
	ds_read_b128 v[158:161], v152 offset:1024
	ds_read_b128 v[162:165], v152 offset:2048
	ds_read_b128 v[170:173], v152 offset:3072
	ds_read_b128 v[174:177], v153
	ds_read_b128 v[178:181], v153 offset:1024
	ds_read_b128 v[182:185], v153 offset:2048
	ds_read_b128 v[186:189], v153 offset:3072
	s_add_u32 s26, s26, 0x160000
	s_addc_u32 s27, s27, 0
	s_mov_b32 m0, s34
	ds_read_b128 v[190:193], v151 offset:32768
	ds_read_b128 v[194:197], v151 offset:33792
	ds_read_b128 v[198:201], v151 offset:34816
	ds_read_b128 v[202:205], v151 offset:35840
	ds_read_b128 v[206:209], v151 offset:36864
	ds_read_b128 v[210:213], v151 offset:37888
	ds_read_b128 v[214:217], v151 offset:38912
	ds_read_b128 v[218:221], v151 offset:39936
	global_load_lds_dwordx4 v130, s[26:27]
	s_mov_b32 m0, s35
	s_nop 0
	global_load_lds_dwordx4 v134, s[26:27]
	s_waitcnt vmcnt(8)
	s_waitcnt lgkmcnt(0)
	s_barrier
	s_setprio 1
	v_mfma_f32_16x16x32_bf16 v[126:129], v[154:157], v[190:193], v[126:129]
	v_mfma_f32_16x16x32_bf16 v[122:125], v[162:165], v[190:193], v[122:125]
	v_mfma_f32_16x16x32_bf16 v[118:121], v[154:157], v[198:201], v[118:121]
	v_mfma_f32_16x16x32_bf16 v[110:113], v[162:165], v[198:201], v[110:113]
	v_mfma_f32_16x16x32_bf16 v[102:105], v[154:157], v[206:209], v[102:105]
	v_mfma_f32_16x16x32_bf16 v[94:97], v[162:165], v[206:209], v[94:97]
	v_mfma_f32_16x16x32_bf16 v[86:89], v[154:157], v[214:217], v[86:89]
	v_mfma_f32_16x16x32_bf16 v[78:81], v[162:165], v[214:217], v[78:81]
	v_mfma_f32_16x16x32_bf16 v[126:129], v[158:161], v[194:197], v[126:129]
	v_mfma_f32_16x16x32_bf16 v[122:125], v[170:173], v[194:197], v[122:125]
	v_mfma_f32_16x16x32_bf16 v[118:121], v[158:161], v[202:205], v[118:121]
	v_mfma_f32_16x16x32_bf16 v[110:113], v[170:173], v[202:205], v[110:113]
	v_mfma_f32_16x16x32_bf16 v[102:105], v[158:161], v[210:213], v[102:105]
	v_mfma_f32_16x16x32_bf16 v[94:97], v[170:173], v[210:213], v[94:97]
	v_mfma_f32_16x16x32_bf16 v[86:89], v[158:161], v[218:221], v[86:89]
	v_mfma_f32_16x16x32_bf16 v[78:81], v[170:173], v[218:221], v[78:81]
	v_mfma_f32_16x16x32_bf16 v[114:117], v[174:177], v[190:193], v[114:117]
	v_mfma_f32_16x16x32_bf16 v[106:109], v[182:185], v[190:193], v[106:109]
	v_mfma_f32_16x16x32_bf16 v[98:101], v[174:177], v[198:201], v[98:101]
	v_mfma_f32_16x16x32_bf16 v[90:93], v[182:185], v[198:201], v[90:93]
	v_mfma_f32_16x16x32_bf16 v[82:85], v[174:177], v[206:209], v[82:85]
	v_mfma_f32_16x16x32_bf16 v[74:77], v[182:185], v[206:209], v[74:77]
	v_mfma_f32_16x16x32_bf16 v[70:73], v[174:177], v[214:217], v[70:73]
	v_mfma_f32_16x16x32_bf16 v[66:69], v[182:185], v[214:217], v[66:69]
	v_mfma_f32_16x16x32_bf16 v[114:117], v[178:181], v[194:197], v[114:117]
	v_mfma_f32_16x16x32_bf16 v[106:109], v[186:189], v[194:197], v[106:109]
	v_mfma_f32_16x16x32_bf16 v[98:101], v[178:181], v[202:205], v[98:101]
	v_mfma_f32_16x16x32_bf16 v[90:93], v[186:189], v[202:205], v[90:93]
	v_mfma_f32_16x16x32_bf16 v[82:85], v[178:181], v[210:213], v[82:85]
	v_mfma_f32_16x16x32_bf16 v[74:77], v[186:189], v[210:213], v[74:77]
	v_mfma_f32_16x16x32_bf16 v[70:73], v[178:181], v[218:221], v[70:73]
	v_mfma_f32_16x16x32_bf16 v[66:69], v[186:189], v[218:221], v[66:69]
	s_setprio 0
	s_barrier
	s_add_i32 s26, s42, s29
	v_lshl_add_u64 v[146:147], v[146:147], 0, s[6:7]
	s_mov_b32 m0, s26
	ds_read_b128 v[190:193], v151 offset:49152
	ds_read_b128 v[194:197], v151 offset:50176
	ds_read_b128 v[198:201], v151 offset:51200
	ds_read_b128 v[202:205], v151 offset:52224
	ds_read_b128 v[206:209], v151 offset:53248
	ds_read_b128 v[210:213], v151 offset:54272
	ds_read_b128 v[214:217], v151 offset:55296
	ds_read_b128 v[218:221], v151 offset:56320
	global_load_lds_dwordx4 v[146:147], off
	s_add_i32 m0, s26, 0x2000
	s_add_u32 s24, s24, 0x160080
	v_lshl_add_u64 v[146:147], v[222:223], 0, s[6:7]
	s_addc_u32 s25, s25, 0
	s_add_i32 s26, s43, s29
	global_load_lds_dwordx4 v[146:147], off
	s_mov_b32 m0, s26
	s_nop 0
	global_load_lds_dwordx4 v132, s[24:25]
	s_add_i32 m0, s26, 0x2000
	s_nop 0
	global_load_lds_dwordx4 v136, s[24:25]
	v_lshl_add_u64 v[146:147], v[224:225], 0, s[6:7]
	s_mov_b32 m0, s36
	s_nop 0
	global_load_lds_dwordx4 v[146:147], off
	v_lshl_add_u64 v[146:147], v[226:227], 0, s[6:7]
	s_mov_b32 m0, s37
	s_nop 0
	global_load_lds_dwordx4 v[146:147], off
	s_waitcnt vmcnt(8)
	s_waitcnt lgkmcnt(0)
	s_barrier
	s_setprio 1
	v_mfma_f32_16x16x32_bf16 v[62:65], v[154:157], v[190:193], v[62:65]
	v_mfma_f32_16x16x32_bf16 v[58:61], v[162:165], v[190:193], v[58:61]
	v_mfma_f32_16x16x32_bf16 v[54:57], v[154:157], v[198:201], v[54:57]
	v_mfma_f32_16x16x32_bf16 v[46:49], v[162:165], v[198:201], v[46:49]
	v_mfma_f32_16x16x32_bf16 v[38:41], v[154:157], v[206:209], v[38:41]
	v_mfma_f32_16x16x32_bf16 v[30:33], v[162:165], v[206:209], v[30:33]
	v_mfma_f32_16x16x32_bf16 v[22:25], v[154:157], v[214:217], v[22:25]
	v_mfma_f32_16x16x32_bf16 v[14:17], v[162:165], v[214:217], v[14:17]
	v_mfma_f32_16x16x32_bf16 v[62:65], v[158:161], v[194:197], v[62:65]
	v_mfma_f32_16x16x32_bf16 v[58:61], v[170:173], v[194:197], v[58:61]
	v_mfma_f32_16x16x32_bf16 v[54:57], v[158:161], v[202:205], v[54:57]
	v_mfma_f32_16x16x32_bf16 v[46:49], v[170:173], v[202:205], v[46:49]
	v_mfma_f32_16x16x32_bf16 v[38:41], v[158:161], v[210:213], v[38:41]
	v_mfma_f32_16x16x32_bf16 v[30:33], v[170:173], v[210:213], v[30:33]
	v_mfma_f32_16x16x32_bf16 v[22:25], v[158:161], v[218:221], v[22:25]
	v_mfma_f32_16x16x32_bf16 v[14:17], v[170:173], v[218:221], v[14:17]
	v_mfma_f32_16x16x32_bf16 v[50:53], v[174:177], v[190:193], v[50:53]
	v_mfma_f32_16x16x32_bf16 v[42:45], v[182:185], v[190:193], v[42:45]
	v_mfma_f32_16x16x32_bf16 v[34:37], v[174:177], v[198:201], v[34:37]
	v_mfma_f32_16x16x32_bf16 v[26:29], v[182:185], v[198:201], v[26:29]
	v_mfma_f32_16x16x32_bf16 v[18:21], v[174:177], v[206:209], v[18:21]
	v_mfma_f32_16x16x32_bf16 v[10:13], v[182:185], v[206:209], v[10:13]
	v_mfma_f32_16x16x32_bf16 v[6:9], v[174:177], v[214:217], v[6:9]
	v_mfma_f32_16x16x32_bf16 v[2:5], v[182:185], v[214:217], v[2:5]
	v_mfma_f32_16x16x32_bf16 v[50:53], v[178:181], v[194:197], v[50:53]
	v_mfma_f32_16x16x32_bf16 v[42:45], v[186:189], v[194:197], v[42:45]
	v_mfma_f32_16x16x32_bf16 v[34:37], v[178:181], v[202:205], v[34:37]
	v_mfma_f32_16x16x32_bf16 v[26:29], v[186:189], v[202:205], v[26:29]
	v_mfma_f32_16x16x32_bf16 v[18:21], v[178:181], v[210:213], v[18:21]
	v_mfma_f32_16x16x32_bf16 v[10:13], v[186:189], v[210:213], v[10:13]
	v_mfma_f32_16x16x32_bf16 v[6:9], v[178:181], v[218:221], v[6:9]
	v_mfma_f32_16x16x32_bf16 v[2:5], v[186:189], v[218:221], v[2:5]
	s_setprio 0
	s_barrier
	s_add_i32 s53, s53, 2
	s_add_u32 s22, s22, 0x100
	s_addc_u32 s23, s23, 0
	s_add_u32 s51, s51, 0x100
	s_addc_u32 s52, s52, 0
	s_cmpk_gt_u32 s53, 0x55
	s_cbranch_scc0 .LBB0_2579
	s_and_b64 vcc, exec, s[12:13]
	s_cbranch_vccz .LBB0_2582
	s_barrier

.LBB0_3015:
	ds_read_b128 v[146:149], v151
	ds_read_b128 v[156:159], v151 offset:1024
	ds_read_b128 v[160:163], v151 offset:2048
	ds_read_b128 v[170:173], v151 offset:3072
	ds_read_b128 v[174:177], v152
	ds_read_b128 v[178:181], v152 offset:1024
	ds_read_b128 v[182:185], v152 offset:2048
	ds_read_b128 v[186:189], v152 offset:3072
	s_add_u32 s30, s28, 0xfff80080
	s_addc_u32 s31, s29, -1
	s_cmp_eq_u32 s52, 28
	s_cselect_b32 s35, s21, s31
	s_cselect_b32 s34, s48, s30
	s_cselect_b32 s31, s17, s51
	s_cselect_b32 s30, s49, s50
	s_add_i32 m0, s27, 0xc000
	ds_read_b128 v[190:193], v153
	ds_read_b128 v[194:197], v153 offset:1024
	ds_read_b128 v[198:201], v153 offset:2048
	ds_read_b128 v[202:205], v153 offset:3072
	ds_read_b128 v[206:209], v153 offset:4096
	ds_read_b128 v[210:213], v153 offset:5120
	ds_read_b128 v[214:217], v153 offset:6144
	ds_read_b128 v[218:221], v153 offset:7168
	global_load_lds_dwordx4 v138, s[28:29]
	s_add_i32 m0, s27, 0xe000
	s_nop 0
	global_load_lds_dwordx4 v140, s[28:29]
	s_waitcnt vmcnt(8)
	s_waitcnt lgkmcnt(0)
	s_barrier
	s_setprio 1
	v_mfma_f32_16x16x32_bf16 v[126:129], v[146:149], v[190:193], v[126:129]
	v_mfma_f32_16x16x32_bf16 v[122:125], v[160:163], v[190:193], v[122:125]
	v_mfma_f32_16x16x32_bf16 v[110:113], v[146:149], v[198:201], v[110:113]
	v_mfma_f32_16x16x32_bf16 v[106:109], v[160:163], v[198:201], v[106:109]
	v_mfma_f32_16x16x32_bf16 v[94:97], v[146:149], v[206:209], v[94:97]
	v_mfma_f32_16x16x32_bf16 v[90:93], v[160:163], v[206:209], v[90:93]
	v_mfma_f32_16x16x32_bf16 v[78:81], v[146:149], v[214:217], v[78:81]
	v_mfma_f32_16x16x32_bf16 v[74:77], v[160:163], v[214:217], v[74:77]
	v_mfma_f32_16x16x32_bf16 v[126:129], v[156:159], v[194:197], v[126:129]
	v_mfma_f32_16x16x32_bf16 v[122:125], v[170:173], v[194:197], v[122:125]
	v_mfma_f32_16x16x32_bf16 v[110:113], v[156:159], v[202:205], v[110:113]
	v_mfma_f32_16x16x32_bf16 v[106:109], v[170:173], v[202:205], v[106:109]
	v_mfma_f32_16x16x32_bf16 v[94:97], v[156:159], v[210:213], v[94:97]
	v_mfma_f32_16x16x32_bf16 v[90:93], v[170:173], v[210:213], v[90:93]
	v_mfma_f32_16x16x32_bf16 v[78:81], v[156:159], v[218:221], v[78:81]
	v_mfma_f32_16x16x32_bf16 v[74:77], v[170:173], v[218:221], v[74:77]
	v_mfma_f32_16x16x32_bf16 v[118:121], v[174:177], v[190:193], v[118:121]
	v_mfma_f32_16x16x32_bf16 v[114:117], v[182:185], v[190:193], v[114:117]
	v_mfma_f32_16x16x32_bf16 v[102:105], v[174:177], v[198:201], v[102:105]
	v_mfma_f32_16x16x32_bf16 v[98:101], v[182:185], v[198:201], v[98:101]
	v_mfma_f32_16x16x32_bf16 v[86:89], v[174:177], v[206:209], v[86:89]
	v_mfma_f32_16x16x32_bf16 v[82:85], v[182:185], v[206:209], v[82:85]
	v_mfma_f32_16x16x32_bf16 v[70:73], v[174:177], v[214:217], v[70:73]
	v_mfma_f32_16x16x32_bf16 v[66:69], v[182:185], v[214:217], v[66:69]
	v_mfma_f32_16x16x32_bf16 v[118:121], v[178:181], v[194:197], v[118:121]
	v_mfma_f32_16x16x32_bf16 v[114:117], v[186:189], v[194:197], v[114:117]
	v_mfma_f32_16x16x32_bf16 v[102:105], v[178:181], v[202:205], v[102:105]
	v_mfma_f32_16x16x32_bf16 v[98:101], v[186:189], v[202:205], v[98:101]
	v_mfma_f32_16x16x32_bf16 v[86:89], v[178:181], v[210:213], v[86:89]
	v_mfma_f32_16x16x32_bf16 v[82:85], v[186:189], v[210:213], v[82:85]
	v_mfma_f32_16x16x32_bf16 v[70:73], v[178:181], v[218:221], v[70:73]
	v_mfma_f32_16x16x32_bf16 v[66:69], v[186:189], v[218:221], v[66:69]
	s_setprio 0
	s_barrier
	s_add_i32 s53, s43, s15
	v_lshl_add_u64 v[164:165], s[30:31], 0, v[132:133]
	s_mov_b32 m0, s53
	ds_read_b128 v[190:193], v153 offset:16384
	ds_read_b128 v[194:197], v153 offset:17408
	ds_read_b128 v[198:201], v153 offset:18432
	ds_read_b128 v[202:205], v153 offset:19456
	ds_read_b128 v[206:209], v153 offset:20480
	ds_read_b128 v[210:213], v153 offset:21504
	ds_read_b128 v[214:217], v153 offset:22528
	ds_read_b128 v[218:221], v153 offset:23552
	global_load_lds_dwordx4 v132, s[30:31]
	s_add_i32 m0, s53, 0x2000
	s_add_u32 s54, s30, 0x80000
	v_lshl_add_u64 v[222:223], s[30:31], 0, v[136:137]
	s_addc_u32 s55, s31, 0
	s_add_i32 s53, s44, s15
	global_load_lds_dwordx4 v136, s[30:31]
	s_mov_b32 m0, s53
	v_lshl_add_u64 v[226:227], s[34:35], 0, v[134:135]
	global_load_lds_dwordx4 v132, s[54:55]
	s_add_i32 m0, s53, 0x2000
	s_nop 0
	global_load_lds_dwordx4 v136, s[54:55]
	v_lshl_add_u64 v[224:225], s[34:35], 0, v[130:131]
	s_mov_b32 m0, s27
	s_nop 0
	global_load_lds_dwordx4 v130, s[34:35]
	s_mov_b32 m0, s36
	s_nop 0
	global_load_lds_dwordx4 v134, s[34:35]
	s_waitcnt vmcnt(8)
	s_waitcnt lgkmcnt(0)
	s_barrier
	s_setprio 1
	v_mfma_f32_16x16x32_bf16 v[62:65], v[146:149], v[190:193], v[62:65]
	v_mfma_f32_16x16x32_bf16 v[58:61], v[160:163], v[190:193], v[58:61]
	v_mfma_f32_16x16x32_bf16 v[46:49], v[146:149], v[198:201], v[46:49]
	v_mfma_f32_16x16x32_bf16 v[42:45], v[160:163], v[198:201], v[42:45]
	v_mfma_f32_16x16x32_bf16 v[30:33], v[146:149], v[206:209], v[30:33]
	v_mfma_f32_16x16x32_bf16 v[26:29], v[160:163], v[206:209], v[26:29]
	v_mfma_f32_16x16x32_bf16 v[14:17], v[146:149], v[214:217], v[14:17]
	v_mfma_f32_16x16x32_bf16 v[10:13], v[160:163], v[214:217], v[10:13]
	v_mfma_f32_16x16x32_bf16 v[62:65], v[156:159], v[194:197], v[62:65]
	v_mfma_f32_16x16x32_bf16 v[58:61], v[170:173], v[194:197], v[58:61]
	v_mfma_f32_16x16x32_bf16 v[46:49], v[156:159], v[202:205], v[46:49]
	v_mfma_f32_16x16x32_bf16 v[42:45], v[170:173], v[202:205], v[42:45]
	v_mfma_f32_16x16x32_bf16 v[30:33], v[156:159], v[210:213], v[30:33]
	v_mfma_f32_16x16x32_bf16 v[26:29], v[170:173], v[210:213], v[26:29]
	v_mfma_f32_16x16x32_bf16 v[14:17], v[156:159], v[218:221], v[14:17]
	v_mfma_f32_16x16x32_bf16 v[10:13], v[170:173], v[218:221], v[10:13]
	v_mfma_f32_16x16x32_bf16 v[54:57], v[174:177], v[190:193], v[54:57]
	v_mfma_f32_16x16x32_bf16 v[50:53], v[182:185], v[190:193], v[50:53]
	v_mfma_f32_16x16x32_bf16 v[38:41], v[174:177], v[198:201], v[38:41]
	v_mfma_f32_16x16x32_bf16 v[34:37], v[182:185], v[198:201], v[34:37]
	v_mfma_f32_16x16x32_bf16 v[22:25], v[174:177], v[206:209], v[22:25]
	v_mfma_f32_16x16x32_bf16 v[18:21], v[182:185], v[206:209], v[18:21]
	v_mfma_f32_16x16x32_bf16 v[6:9], v[174:177], v[214:217], v[6:9]
	v_mfma_f32_16x16x32_bf16 v[2:5], v[182:185], v[214:217], v[2:5]
	v_mfma_f32_16x16x32_bf16 v[54:57], v[178:181], v[194:197], v[54:57]
	v_mfma_f32_16x16x32_bf16 v[50:53], v[186:189], v[194:197], v[50:53]
	v_mfma_f32_16x16x32_bf16 v[38:41], v[178:181], v[202:205], v[38:41]
	v_mfma_f32_16x16x32_bf16 v[34:37], v[186:189], v[202:205], v[34:37]
	v_mfma_f32_16x16x32_bf16 v[22:25], v[178:181], v[210:213], v[22:25]
	v_mfma_f32_16x16x32_bf16 v[18:21], v[186:189], v[210:213], v[18:21]
	v_mfma_f32_16x16x32_bf16 v[6:9], v[178:181], v[218:221], v[6:9]
	v_mfma_f32_16x16x32_bf16 v[2:5], v[186:189], v[218:221], v[2:5]
	s_setprio 0
	s_barrier
	ds_read_b128 v[146:149], v154
	ds_read_b128 v[156:159], v154 offset:1024
	ds_read_b128 v[160:163], v154 offset:2048
	ds_read_b128 v[170:173], v154 offset:3072
	ds_read_b128 v[174:177], v155
	ds_read_b128 v[178:181], v155 offset:1024
	ds_read_b128 v[182:185], v155 offset:2048
	ds_read_b128 v[186:189], v155 offset:3072
	s_add_u32 s34, s34, 0x80000
	s_addc_u32 s35, s35, 0
	s_mov_b32 m0, s37
	ds_read_b128 v[190:193], v153 offset:32768
	ds_read_b128 v[194:197], v153 offset:33792
	ds_read_b128 v[198:201], v153 offset:34816
	ds_read_b128 v[202:205], v153 offset:35840
	ds_read_b128 v[206:209], v153 offset:36864
	ds_read_b128 v[210:213], v153 offset:37888
	ds_read_b128 v[214:217], v153 offset:38912
	ds_read_b128 v[218:221], v153 offset:39936
	global_load_lds_dwordx4 v130, s[34:35]
	s_mov_b32 m0, s38
	s_nop 0
	global_load_lds_dwordx4 v134, s[34:35]
	s_waitcnt vmcnt(8)
	s_waitcnt lgkmcnt(0)
	s_barrier
	s_setprio 1
	v_mfma_f32_16x16x32_bf16 v[126:129], v[146:149], v[190:193], v[126:129]
	v_mfma_f32_16x16x32_bf16 v[122:125], v[160:163], v[190:193], v[122:125]
	v_mfma_f32_16x16x32_bf16 v[110:113], v[146:149], v[198:201], v[110:113]
	v_mfma_f32_16x16x32_bf16 v[106:109], v[160:163], v[198:201], v[106:109]
	v_mfma_f32_16x16x32_bf16 v[94:97], v[146:149], v[206:209], v[94:97]
	v_mfma_f32_16x16x32_bf16 v[90:93], v[160:163], v[206:209], v[90:93]
	v_mfma_f32_16x16x32_bf16 v[78:81], v[146:149], v[214:217], v[78:81]
	v_mfma_f32_16x16x32_bf16 v[74:77], v[160:163], v[214:217], v[74:77]
	v_mfma_f32_16x16x32_bf16 v[126:129], v[156:159], v[194:197], v[126:129]
	v_mfma_f32_16x16x32_bf16 v[122:125], v[170:173], v[194:197], v[122:125]
	v_mfma_f32_16x16x32_bf16 v[110:113], v[156:159], v[202:205], v[110:113]
	v_mfma_f32_16x16x32_bf16 v[106:109], v[170:173], v[202:205], v[106:109]
	v_mfma_f32_16x16x32_bf16 v[94:97], v[156:159], v[210:213], v[94:97]
	v_mfma_f32_16x16x32_bf16 v[90:93], v[170:173], v[210:213], v[90:93]
	v_mfma_f32_16x16x32_bf16 v[78:81], v[156:159], v[218:221], v[78:81]
	v_mfma_f32_16x16x32_bf16 v[74:77], v[170:173], v[218:221], v[74:77]
	v_mfma_f32_16x16x32_bf16 v[118:121], v[174:177], v[190:193], v[118:121]
	v_mfma_f32_16x16x32_bf16 v[114:117], v[182:185], v[190:193], v[114:117]
	v_mfma_f32_16x16x32_bf16 v[102:105], v[174:177], v[198:201], v[102:105]
	v_mfma_f32_16x16x32_bf16 v[98:101], v[182:185], v[198:201], v[98:101]
	v_mfma_f32_16x16x32_bf16 v[86:89], v[174:177], v[206:209], v[86:89]
	v_mfma_f32_16x16x32_bf16 v[82:85], v[182:185], v[206:209], v[82:85]
	v_mfma_f32_16x16x32_bf16 v[70:73], v[174:177], v[214:217], v[70:73]
	v_mfma_f32_16x16x32_bf16 v[66:69], v[182:185], v[214:217], v[66:69]
	v_mfma_f32_16x16x32_bf16 v[118:121], v[178:181], v[194:197], v[118:121]
	v_mfma_f32_16x16x32_bf16 v[114:117], v[186:189], v[194:197], v[114:117]
	v_mfma_f32_16x16x32_bf16 v[102:105], v[178:181], v[202:205], v[102:105]
	v_mfma_f32_16x16x32_bf16 v[98:101], v[186:189], v[202:205], v[98:101]
	v_mfma_f32_16x16x32_bf16 v[86:89], v[178:181], v[210:213], v[86:89]
	v_mfma_f32_16x16x32_bf16 v[82:85], v[186:189], v[210:213], v[82:85]
	v_mfma_f32_16x16x32_bf16 v[70:73], v[178:181], v[218:221], v[70:73]
	v_mfma_f32_16x16x32_bf16 v[66:69], v[186:189], v[218:221], v[66:69]
	s_setprio 0
	s_barrier
	s_add_i32 s34, s45, s15
	v_lshl_add_u64 v[164:165], v[164:165], 0, s[4:5]
	s_mov_b32 m0, s34
	ds_read_b128 v[190:193], v153 offset:49152
	ds_read_b128 v[194:197], v153 offset:50176
	ds_read_b128 v[198:201], v153 offset:51200
	ds_read_b128 v[202:205], v153 offset:52224
	ds_read_b128 v[206:209], v153 offset:53248
	ds_read_b128 v[210:213], v153 offset:54272
	ds_read_b128 v[214:217], v153 offset:55296
	ds_read_b128 v[218:221], v153 offset:56320
	global_load_lds_dwordx4 v[164:165], off
	s_add_i32 m0, s34, 0x2000
	s_add_u32 s30, s30, 0x80080
	v_lshl_add_u64 v[164:165], v[222:223], 0, s[4:5]
	s_addc_u32 s31, s31, 0
	s_add_i32 s34, s46, s15
	global_load_lds_dwordx4 v[164:165], off
	s_mov_b32 m0, s34
	s_nop 0
	global_load_lds_dwordx4 v132, s[30:31]
	s_add_i32 m0, s34, 0x2000
	s_nop 0
	global_load_lds_dwordx4 v136, s[30:31]
	v_lshl_add_u64 v[164:165], v[224:225], 0, s[4:5]
	s_mov_b32 m0, s39
	s_nop 0
	global_load_lds_dwordx4 v[164:165], off
	v_lshl_add_u64 v[164:165], v[226:227], 0, s[4:5]
	s_mov_b32 m0, s40
	s_nop 0
	global_load_lds_dwordx4 v[164:165], off
	s_waitcnt vmcnt(8)
	s_waitcnt lgkmcnt(0)
	s_barrier
	s_setprio 1
	v_mfma_f32_16x16x32_bf16 v[62:65], v[146:149], v[190:193], v[62:65]
	v_mfma_f32_16x16x32_bf16 v[58:61], v[160:163], v[190:193], v[58:61]
	v_mfma_f32_16x16x32_bf16 v[46:49], v[146:149], v[198:201], v[46:49]
	v_mfma_f32_16x16x32_bf16 v[42:45], v[160:163], v[198:201], v[42:45]
	v_mfma_f32_16x16x32_bf16 v[30:33], v[146:149], v[206:209], v[30:33]
	v_mfma_f32_16x16x32_bf16 v[26:29], v[160:163], v[206:209], v[26:29]
	v_mfma_f32_16x16x32_bf16 v[14:17], v[146:149], v[214:217], v[14:17]
	v_mfma_f32_16x16x32_bf16 v[10:13], v[160:163], v[214:217], v[10:13]
	v_mfma_f32_16x16x32_bf16 v[62:65], v[156:159], v[194:197], v[62:65]
	v_mfma_f32_16x16x32_bf16 v[58:61], v[170:173], v[194:197], v[58:61]
	v_mfma_f32_16x16x32_bf16 v[46:49], v[156:159], v[202:205], v[46:49]
	v_mfma_f32_16x16x32_bf16 v[42:45], v[170:173], v[202:205], v[42:45]
	v_mfma_f32_16x16x32_bf16 v[30:33], v[156:159], v[210:213], v[30:33]
	v_mfma_f32_16x16x32_bf16 v[26:29], v[170:173], v[210:213], v[26:29]
	v_mfma_f32_16x16x32_bf16 v[14:17], v[156:159], v[218:221], v[14:17]
	v_mfma_f32_16x16x32_bf16 v[10:13], v[170:173], v[218:221], v[10:13]
	v_mfma_f32_16x16x32_bf16 v[54:57], v[174:177], v[190:193], v[54:57]
	v_mfma_f32_16x16x32_bf16 v[50:53], v[182:185], v[190:193], v[50:53]
	v_mfma_f32_16x16x32_bf16 v[38:41], v[174:177], v[198:201], v[38:41]
	v_mfma_f32_16x16x32_bf16 v[34:37], v[182:185], v[198:201], v[34:37]
	v_mfma_f32_16x16x32_bf16 v[22:25], v[174:177], v[206:209], v[22:25]
	v_mfma_f32_16x16x32_bf16 v[18:21], v[182:185], v[206:209], v[18:21]
	v_mfma_f32_16x16x32_bf16 v[6:9], v[174:177], v[214:217], v[6:9]
	v_mfma_f32_16x16x32_bf16 v[2:5], v[182:185], v[214:217], v[2:5]
	v_mfma_f32_16x16x32_bf16 v[54:57], v[178:181], v[194:197], v[54:57]
	v_mfma_f32_16x16x32_bf16 v[50:53], v[186:189], v[194:197], v[50:53]
	v_mfma_f32_16x16x32_bf16 v[38:41], v[178:181], v[202:205], v[38:41]
	v_mfma_f32_16x16x32_bf16 v[34:37], v[186:189], v[202:205], v[34:37]
	v_mfma_f32_16x16x32_bf16 v[22:25], v[178:181], v[210:213], v[22:25]
	v_mfma_f32_16x16x32_bf16 v[18:21], v[186:189], v[210:213], v[18:21]
	v_mfma_f32_16x16x32_bf16 v[6:9], v[178:181], v[218:221], v[6:9]
	v_mfma_f32_16x16x32_bf16 v[2:5], v[186:189], v[218:221], v[2:5]
	s_setprio 0
	s_barrier
	s_add_i32 s52, s52, 2
	s_add_u32 s28, s28, 0x100
	s_addc_u32 s29, s29, 0
	s_add_u32 s50, s50, 0x100
	s_addc_u32 s51, s51, 0
	s_cmp_gt_u32 s52, 29
	s_cbranch_scc0 .LBB0_3015
	s_and_b64 vcc, exec, s[10:11]
	s_cbranch_vccz .LBB0_3018
	s_barrier

.LBB0_3225:
	ds_read_b128 v[154:157], v149
	ds_read_b128 v[158:161], v149 offset:1024
	ds_read_b128 v[162:165], v149 offset:2048
	ds_read_b128 v[170:173], v149 offset:3072
	ds_read_b128 v[174:177], v150
	ds_read_b128 v[178:181], v150 offset:1024
	ds_read_b128 v[182:185], v150 offset:2048
	ds_read_b128 v[186:189], v150 offset:3072
	s_add_u32 s34, s30, 0xfff80080
	s_addc_u32 s35, s31, -1
	s_cmp_eq_u32 s67, 28
	s_cselect_b32 s37, s23, s35
	s_cselect_b32 s36, s56, s34
	s_cselect_b32 s35, s21, s66
	s_cselect_b32 s34, s57, s63
	s_add_i32 m0, s29, 0xc000
	ds_read_b128 v[190:193], v151
	ds_read_b128 v[194:197], v151 offset:1024
	ds_read_b128 v[198:201], v151 offset:2048
	ds_read_b128 v[202:205], v151 offset:3072
	ds_read_b128 v[206:209], v151 offset:4096
	ds_read_b128 v[210:213], v151 offset:5120
	ds_read_b128 v[214:217], v151 offset:6144
	ds_read_b128 v[218:221], v151 offset:7168
	global_load_lds_dwordx4 v138, s[30:31]
	s_add_i32 m0, s29, 0xe000
	s_nop 0
	global_load_lds_dwordx4 v140, s[30:31]
	s_waitcnt vmcnt(8)
	s_waitcnt lgkmcnt(0)
	s_barrier
	s_setprio 1
	v_mfma_f32_16x16x32_bf16 v[126:129], v[154:157], v[190:193], v[126:129]
	v_mfma_f32_16x16x32_bf16 v[122:125], v[162:165], v[190:193], v[122:125]
	v_mfma_f32_16x16x32_bf16 v[118:121], v[154:157], v[198:201], v[118:121]
	v_mfma_f32_16x16x32_bf16 v[110:113], v[162:165], v[198:201], v[110:113]
	v_mfma_f32_16x16x32_bf16 v[102:105], v[154:157], v[206:209], v[102:105]
	v_mfma_f32_16x16x32_bf16 v[94:97], v[162:165], v[206:209], v[94:97]
	v_mfma_f32_16x16x32_bf16 v[86:89], v[154:157], v[214:217], v[86:89]
	v_mfma_f32_16x16x32_bf16 v[78:81], v[162:165], v[214:217], v[78:81]
	v_mfma_f32_16x16x32_bf16 v[126:129], v[158:161], v[194:197], v[126:129]
	v_mfma_f32_16x16x32_bf16 v[122:125], v[170:173], v[194:197], v[122:125]
	v_mfma_f32_16x16x32_bf16 v[118:121], v[158:161], v[202:205], v[118:121]
	v_mfma_f32_16x16x32_bf16 v[110:113], v[170:173], v[202:205], v[110:113]
	v_mfma_f32_16x16x32_bf16 v[102:105], v[158:161], v[210:213], v[102:105]
	v_mfma_f32_16x16x32_bf16 v[94:97], v[170:173], v[210:213], v[94:97]
	v_mfma_f32_16x16x32_bf16 v[86:89], v[158:161], v[218:221], v[86:89]
	v_mfma_f32_16x16x32_bf16 v[78:81], v[170:173], v[218:221], v[78:81]
	v_mfma_f32_16x16x32_bf16 v[114:117], v[174:177], v[190:193], v[114:117]
	v_mfma_f32_16x16x32_bf16 v[106:109], v[182:185], v[190:193], v[106:109]
	v_mfma_f32_16x16x32_bf16 v[98:101], v[174:177], v[198:201], v[98:101]
	v_mfma_f32_16x16x32_bf16 v[90:93], v[182:185], v[198:201], v[90:93]
	v_mfma_f32_16x16x32_bf16 v[82:85], v[174:177], v[206:209], v[82:85]
	v_mfma_f32_16x16x32_bf16 v[74:77], v[182:185], v[206:209], v[74:77]
	v_mfma_f32_16x16x32_bf16 v[70:73], v[174:177], v[214:217], v[70:73]
	v_mfma_f32_16x16x32_bf16 v[66:69], v[182:185], v[214:217], v[66:69]
	v_mfma_f32_16x16x32_bf16 v[114:117], v[178:181], v[194:197], v[114:117]
	v_mfma_f32_16x16x32_bf16 v[106:109], v[186:189], v[194:197], v[106:109]
	v_mfma_f32_16x16x32_bf16 v[98:101], v[178:181], v[202:205], v[98:101]
	v_mfma_f32_16x16x32_bf16 v[90:93], v[186:189], v[202:205], v[90:93]
	v_mfma_f32_16x16x32_bf16 v[82:85], v[178:181], v[210:213], v[82:85]
	v_mfma_f32_16x16x32_bf16 v[74:77], v[186:189], v[210:213], v[74:77]
	v_mfma_f32_16x16x32_bf16 v[70:73], v[178:181], v[218:221], v[70:73]
	v_mfma_f32_16x16x32_bf16 v[66:69], v[186:189], v[218:221], v[66:69]
	s_setprio 0
	s_barrier
	s_add_i32 s68, s47, s39
	v_lshl_add_u64 v[146:147], s[34:35], 0, v[132:133]
	s_mov_b32 m0, s68
	ds_read_b128 v[190:193], v151 offset:16384
	ds_read_b128 v[194:197], v151 offset:17408
	ds_read_b128 v[198:201], v151 offset:18432
	ds_read_b128 v[202:205], v151 offset:19456
	ds_read_b128 v[206:209], v151 offset:20480
	ds_read_b128 v[210:213], v151 offset:21504
	ds_read_b128 v[214:217], v151 offset:22528
	ds_read_b128 v[218:221], v151 offset:23552
	global_load_lds_dwordx4 v132, s[34:35]
	s_add_i32 m0, s68, 0x2000
	s_add_u32 s68, s34, 0x80000
	v_lshl_add_u64 v[222:223], s[34:35], 0, v[136:137]
	s_addc_u32 s69, s35, 0
	s_add_i32 s70, s48, s39
	global_load_lds_dwordx4 v136, s[34:35]
	s_mov_b32 m0, s70
	v_lshl_add_u64 v[226:227], s[36:37], 0, v[134:135]
	global_load_lds_dwordx4 v132, s[68:69]
	s_add_i32 m0, s70, 0x2000
	s_nop 0
	global_load_lds_dwordx4 v136, s[68:69]
	v_lshl_add_u64 v[224:225], s[36:37], 0, v[130:131]
	s_mov_b32 m0, s29
	s_nop 0
	global_load_lds_dwordx4 v130, s[36:37]
	s_mov_b32 m0, s40
	s_nop 0
	global_load_lds_dwordx4 v134, s[36:37]
	s_waitcnt vmcnt(8)
	s_waitcnt lgkmcnt(0)
	s_barrier
	s_setprio 1
	v_mfma_f32_16x16x32_bf16 v[62:65], v[154:157], v[190:193], v[62:65]
	v_mfma_f32_16x16x32_bf16 v[58:61], v[162:165], v[190:193], v[58:61]
	v_mfma_f32_16x16x32_bf16 v[54:57], v[154:157], v[198:201], v[54:57]
	v_mfma_f32_16x16x32_bf16 v[46:49], v[162:165], v[198:201], v[46:49]
	v_mfma_f32_16x16x32_bf16 v[38:41], v[154:157], v[206:209], v[38:41]
	v_mfma_f32_16x16x32_bf16 v[30:33], v[162:165], v[206:209], v[30:33]
	v_mfma_f32_16x16x32_bf16 v[22:25], v[154:157], v[214:217], v[22:25]
	v_mfma_f32_16x16x32_bf16 v[14:17], v[162:165], v[214:217], v[14:17]
	v_mfma_f32_16x16x32_bf16 v[62:65], v[158:161], v[194:197], v[62:65]
	v_mfma_f32_16x16x32_bf16 v[58:61], v[170:173], v[194:197], v[58:61]
	v_mfma_f32_16x16x32_bf16 v[54:57], v[158:161], v[202:205], v[54:57]
	v_mfma_f32_16x16x32_bf16 v[46:49], v[170:173], v[202:205], v[46:49]
	v_mfma_f32_16x16x32_bf16 v[38:41], v[158:161], v[210:213], v[38:41]
	v_mfma_f32_16x16x32_bf16 v[30:33], v[170:173], v[210:213], v[30:33]
	v_mfma_f32_16x16x32_bf16 v[22:25], v[158:161], v[218:221], v[22:25]
	v_mfma_f32_16x16x32_bf16 v[14:17], v[170:173], v[218:221], v[14:17]
	v_mfma_f32_16x16x32_bf16 v[50:53], v[174:177], v[190:193], v[50:53]
	v_mfma_f32_16x16x32_bf16 v[42:45], v[182:185], v[190:193], v[42:45]
	v_mfma_f32_16x16x32_bf16 v[34:37], v[174:177], v[198:201], v[34:37]
	v_mfma_f32_16x16x32_bf16 v[26:29], v[182:185], v[198:201], v[26:29]
	v_mfma_f32_16x16x32_bf16 v[18:21], v[174:177], v[206:209], v[18:21]
	v_mfma_f32_16x16x32_bf16 v[10:13], v[182:185], v[206:209], v[10:13]
	v_mfma_f32_16x16x32_bf16 v[6:9], v[174:177], v[214:217], v[6:9]
	v_mfma_f32_16x16x32_bf16 v[2:5], v[182:185], v[214:217], v[2:5]
	v_mfma_f32_16x16x32_bf16 v[50:53], v[178:181], v[194:197], v[50:53]
	v_mfma_f32_16x16x32_bf16 v[42:45], v[186:189], v[194:197], v[42:45]
	v_mfma_f32_16x16x32_bf16 v[34:37], v[178:181], v[202:205], v[34:37]
	v_mfma_f32_16x16x32_bf16 v[26:29], v[186:189], v[202:205], v[26:29]
	v_mfma_f32_16x16x32_bf16 v[18:21], v[178:181], v[210:213], v[18:21]
	v_mfma_f32_16x16x32_bf16 v[10:13], v[186:189], v[210:213], v[10:13]
	v_mfma_f32_16x16x32_bf16 v[6:9], v[178:181], v[218:221], v[6:9]
	v_mfma_f32_16x16x32_bf16 v[2:5], v[186:189], v[218:221], v[2:5]
	s_setprio 0
	s_barrier
	ds_read_b128 v[154:157], v152
	ds_read_b128 v[158:161], v152 offset:1024
	ds_read_b128 v[162:165], v152 offset:2048
	ds_read_b128 v[170:173], v152 offset:3072
	ds_read_b128 v[174:177], v153
	ds_read_b128 v[178:181], v153 offset:1024
	ds_read_b128 v[182:185], v153 offset:2048
	ds_read_b128 v[186:189], v153 offset:3072
	s_add_u32 s36, s36, 0x80000
	s_addc_u32 s37, s37, 0
	s_mov_b32 m0, s41
	ds_read_b128 v[190:193], v151 offset:32768
	ds_read_b128 v[194:197], v151 offset:33792
	ds_read_b128 v[198:201], v151 offset:34816
	ds_read_b128 v[202:205], v151 offset:35840
	ds_read_b128 v[206:209], v151 offset:36864
	ds_read_b128 v[210:213], v151 offset:37888
	ds_read_b128 v[214:217], v151 offset:38912
	ds_read_b128 v[218:221], v151 offset:39936
	global_load_lds_dwordx4 v130, s[36:37]
	s_mov_b32 m0, s42
	s_nop 0
	global_load_lds_dwordx4 v134, s[36:37]
	s_waitcnt vmcnt(8)
	s_waitcnt lgkmcnt(0)
	s_barrier
	s_setprio 1
	v_mfma_f32_16x16x32_bf16 v[126:129], v[154:157], v[190:193], v[126:129]
	v_mfma_f32_16x16x32_bf16 v[122:125], v[162:165], v[190:193], v[122:125]
	v_mfma_f32_16x16x32_bf16 v[118:121], v[154:157], v[198:201], v[118:121]
	v_mfma_f32_16x16x32_bf16 v[110:113], v[162:165], v[198:201], v[110:113]
	v_mfma_f32_16x16x32_bf16 v[102:105], v[154:157], v[206:209], v[102:105]
	v_mfma_f32_16x16x32_bf16 v[94:97], v[162:165], v[206:209], v[94:97]
	v_mfma_f32_16x16x32_bf16 v[86:89], v[154:157], v[214:217], v[86:89]
	v_mfma_f32_16x16x32_bf16 v[78:81], v[162:165], v[214:217], v[78:81]
	v_mfma_f32_16x16x32_bf16 v[126:129], v[158:161], v[194:197], v[126:129]
	v_mfma_f32_16x16x32_bf16 v[122:125], v[170:173], v[194:197], v[122:125]
	v_mfma_f32_16x16x32_bf16 v[118:121], v[158:161], v[202:205], v[118:121]
	v_mfma_f32_16x16x32_bf16 v[110:113], v[170:173], v[202:205], v[110:113]
	v_mfma_f32_16x16x32_bf16 v[102:105], v[158:161], v[210:213], v[102:105]
	v_mfma_f32_16x16x32_bf16 v[94:97], v[170:173], v[210:213], v[94:97]
	v_mfma_f32_16x16x32_bf16 v[86:89], v[158:161], v[218:221], v[86:89]
	v_mfma_f32_16x16x32_bf16 v[78:81], v[170:173], v[218:221], v[78:81]
	v_mfma_f32_16x16x32_bf16 v[114:117], v[174:177], v[190:193], v[114:117]
	v_mfma_f32_16x16x32_bf16 v[106:109], v[182:185], v[190:193], v[106:109]
	v_mfma_f32_16x16x32_bf16 v[98:101], v[174:177], v[198:201], v[98:101]
	v_mfma_f32_16x16x32_bf16 v[90:93], v[182:185], v[198:201], v[90:93]
	v_mfma_f32_16x16x32_bf16 v[82:85], v[174:177], v[206:209], v[82:85]
	v_mfma_f32_16x16x32_bf16 v[74:77], v[182:185], v[206:209], v[74:77]
	v_mfma_f32_16x16x32_bf16 v[70:73], v[174:177], v[214:217], v[70:73]
	v_mfma_f32_16x16x32_bf16 v[66:69], v[182:185], v[214:217], v[66:69]
	v_mfma_f32_16x16x32_bf16 v[114:117], v[178:181], v[194:197], v[114:117]
	v_mfma_f32_16x16x32_bf16 v[106:109], v[186:189], v[194:197], v[106:109]
	v_mfma_f32_16x16x32_bf16 v[98:101], v[178:181], v[202:205], v[98:101]
	v_mfma_f32_16x16x32_bf16 v[90:93], v[186:189], v[202:205], v[90:93]
	v_mfma_f32_16x16x32_bf16 v[82:85], v[178:181], v[210:213], v[82:85]
	v_mfma_f32_16x16x32_bf16 v[74:77], v[186:189], v[210:213], v[74:77]
	v_mfma_f32_16x16x32_bf16 v[70:73], v[178:181], v[218:221], v[70:73]
	v_mfma_f32_16x16x32_bf16 v[66:69], v[186:189], v[218:221], v[66:69]
	s_setprio 0
	s_barrier
	s_add_i32 s36, s49, s39
	v_lshl_add_u64 v[146:147], v[146:147], 0, s[6:7]
	s_mov_b32 m0, s36
	ds_read_b128 v[190:193], v151 offset:49152
	ds_read_b128 v[194:197], v151 offset:50176
	ds_read_b128 v[198:201], v151 offset:51200
	ds_read_b128 v[202:205], v151 offset:52224
	ds_read_b128 v[206:209], v151 offset:53248
	ds_read_b128 v[210:213], v151 offset:54272
	ds_read_b128 v[214:217], v151 offset:55296
	ds_read_b128 v[218:221], v151 offset:56320
	global_load_lds_dwordx4 v[146:147], off
	s_add_i32 m0, s36, 0x2000
	s_add_u32 s34, s34, 0x80080
	v_lshl_add_u64 v[146:147], v[222:223], 0, s[6:7]
	s_addc_u32 s35, s35, 0
	s_add_i32 s36, s50, s39
	global_load_lds_dwordx4 v[146:147], off
	s_mov_b32 m0, s36
	s_nop 0
	global_load_lds_dwordx4 v132, s[34:35]
	s_add_i32 m0, s36, 0x2000
	s_nop 0
	global_load_lds_dwordx4 v136, s[34:35]
	v_lshl_add_u64 v[146:147], v[224:225], 0, s[6:7]
	s_mov_b32 m0, s43
	s_nop 0
	global_load_lds_dwordx4 v[146:147], off
	v_lshl_add_u64 v[146:147], v[226:227], 0, s[6:7]
	s_mov_b32 m0, s44
	s_nop 0
	global_load_lds_dwordx4 v[146:147], off
	s_waitcnt vmcnt(8)
	s_waitcnt lgkmcnt(0)
	s_barrier
	s_setprio 1
	v_mfma_f32_16x16x32_bf16 v[62:65], v[154:157], v[190:193], v[62:65]
	v_mfma_f32_16x16x32_bf16 v[58:61], v[162:165], v[190:193], v[58:61]
	v_mfma_f32_16x16x32_bf16 v[54:57], v[154:157], v[198:201], v[54:57]
	v_mfma_f32_16x16x32_bf16 v[46:49], v[162:165], v[198:201], v[46:49]
	v_mfma_f32_16x16x32_bf16 v[38:41], v[154:157], v[206:209], v[38:41]
	v_mfma_f32_16x16x32_bf16 v[30:33], v[162:165], v[206:209], v[30:33]
	v_mfma_f32_16x16x32_bf16 v[22:25], v[154:157], v[214:217], v[22:25]
	v_mfma_f32_16x16x32_bf16 v[14:17], v[162:165], v[214:217], v[14:17]
	v_mfma_f32_16x16x32_bf16 v[62:65], v[158:161], v[194:197], v[62:65]
	v_mfma_f32_16x16x32_bf16 v[58:61], v[170:173], v[194:197], v[58:61]
	v_mfma_f32_16x16x32_bf16 v[54:57], v[158:161], v[202:205], v[54:57]
	v_mfma_f32_16x16x32_bf16 v[46:49], v[170:173], v[202:205], v[46:49]
	v_mfma_f32_16x16x32_bf16 v[38:41], v[158:161], v[210:213], v[38:41]
	v_mfma_f32_16x16x32_bf16 v[30:33], v[170:173], v[210:213], v[30:33]
	v_mfma_f32_16x16x32_bf16 v[22:25], v[158:161], v[218:221], v[22:25]
	v_mfma_f32_16x16x32_bf16 v[14:17], v[170:173], v[218:221], v[14:17]
	v_mfma_f32_16x16x32_bf16 v[50:53], v[174:177], v[190:193], v[50:53]
	v_mfma_f32_16x16x32_bf16 v[42:45], v[182:185], v[190:193], v[42:45]
	v_mfma_f32_16x16x32_bf16 v[34:37], v[174:177], v[198:201], v[34:37]
	v_mfma_f32_16x16x32_bf16 v[26:29], v[182:185], v[198:201], v[26:29]
	v_mfma_f32_16x16x32_bf16 v[18:21], v[174:177], v[206:209], v[18:21]
	v_mfma_f32_16x16x32_bf16 v[10:13], v[182:185], v[206:209], v[10:13]
	v_mfma_f32_16x16x32_bf16 v[6:9], v[174:177], v[214:217], v[6:9]
	v_mfma_f32_16x16x32_bf16 v[2:5], v[182:185], v[214:217], v[2:5]
	v_mfma_f32_16x16x32_bf16 v[50:53], v[178:181], v[194:197], v[50:53]
	v_mfma_f32_16x16x32_bf16 v[42:45], v[186:189], v[194:197], v[42:45]
	v_mfma_f32_16x16x32_bf16 v[34:37], v[178:181], v[202:205], v[34:37]
	v_mfma_f32_16x16x32_bf16 v[26:29], v[186:189], v[202:205], v[26:29]
	v_mfma_f32_16x16x32_bf16 v[18:21], v[178:181], v[210:213], v[18:21]
	v_mfma_f32_16x16x32_bf16 v[10:13], v[186:189], v[210:213], v[10:13]
	v_mfma_f32_16x16x32_bf16 v[6:9], v[178:181], v[218:221], v[6:9]
	v_mfma_f32_16x16x32_bf16 v[2:5], v[186:189], v[218:221], v[2:5]
	s_setprio 0
	s_barrier
	s_add_i32 s67, s67, 2
	s_add_u32 s30, s30, 0x100
	s_addc_u32 s31, s31, 0
	s_add_u32 s63, s63, 0x100
	s_addc_u32 s66, s66, 0
	s_cmp_gt_u32 s67, 29
	s_cbranch_scc0 .LBB0_3225
	s_and_b64 vcc, exec, s[12:13]
	s_cbranch_vccz .LBB0_3228
	s_barrier

.LBB0_3387:
	ds_read_b128 v[146:149], v177
	ds_read_b128 v[150:153], v177 offset:1024
	ds_read_b128 v[154:157], v177 offset:2048
	ds_read_b128 v[158:161], v177 offset:3072
	ds_read_b128 v[182:185], v178
	ds_read_b128 v[186:189], v178 offset:1024
	ds_read_b128 v[190:193], v178 offset:2048
	ds_read_b128 v[194:197], v178 offset:3072
	s_add_u32 s28, s26, 0xfffc0080
	s_addc_u32 s29, s27, -1
	s_cmp_eq_u32 s54, 12
	s_cselect_b32 s31, s19, s29
	s_cselect_b32 s30, s50, s28
	s_cselect_b32 s29, s17, s53
	s_cselect_b32 s28, s51, s52
	s_add_i32 m0, s25, 0xc000
	ds_read_b128 v[198:201], v179
	ds_read_b128 v[202:205], v179 offset:1024
	ds_read_b128 v[206:209], v179 offset:2048
	ds_read_b128 v[210:213], v179 offset:3072
	ds_read_b128 v[214:217], v179 offset:4096
	ds_read_b128 v[218:221], v179 offset:5120
	ds_read_b128 v[222:225], v179 offset:6144
	ds_read_b128 v[226:229], v179 offset:7168
	global_load_lds_dwordx4 v138, s[26:27]
	s_add_i32 m0, s25, 0xe000
	s_nop 0
	global_load_lds_dwordx4 v140, s[26:27]
	s_waitcnt vmcnt(8)
	s_waitcnt lgkmcnt(0)
	s_barrier
	s_setprio 1
	v_mfma_i32_16x16x64_i8 v[126:129], v[146:149], v[198:201], v[126:129]
	v_mfma_i32_16x16x64_i8 v[118:121], v[154:157], v[198:201], v[118:121]
	v_mfma_i32_16x16x64_i8 v[110:113], v[146:149], v[206:209], v[110:113]
	v_mfma_i32_16x16x64_i8 v[102:105], v[154:157], v[206:209], v[102:105]
	v_mfma_i32_16x16x64_i8 v[94:97], v[146:149], v[214:217], v[94:97]
	v_mfma_i32_16x16x64_i8 v[86:89], v[154:157], v[214:217], v[86:89]
	v_mfma_i32_16x16x64_i8 v[78:81], v[146:149], v[222:225], v[78:81]
	v_mfma_i32_16x16x64_i8 v[70:73], v[154:157], v[222:225], v[70:73]
	v_mfma_i32_16x16x64_i8 v[126:129], v[150:153], v[202:205], v[126:129]
	v_mfma_i32_16x16x64_i8 v[118:121], v[158:161], v[202:205], v[118:121]
	v_mfma_i32_16x16x64_i8 v[110:113], v[150:153], v[210:213], v[110:113]
	v_mfma_i32_16x16x64_i8 v[102:105], v[158:161], v[210:213], v[102:105]
	v_mfma_i32_16x16x64_i8 v[94:97], v[150:153], v[218:221], v[94:97]
	v_mfma_i32_16x16x64_i8 v[86:89], v[158:161], v[218:221], v[86:89]
	v_mfma_i32_16x16x64_i8 v[78:81], v[150:153], v[226:229], v[78:81]
	v_mfma_i32_16x16x64_i8 v[70:73], v[158:161], v[226:229], v[70:73]
	v_mfma_i32_16x16x64_i8 v[122:125], v[182:185], v[198:201], v[122:125]
	v_mfma_i32_16x16x64_i8 v[114:117], v[190:193], v[198:201], v[114:117]
	v_mfma_i32_16x16x64_i8 v[106:109], v[182:185], v[206:209], v[106:109]
	v_mfma_i32_16x16x64_i8 v[98:101], v[190:193], v[206:209], v[98:101]
	v_mfma_i32_16x16x64_i8 v[90:93], v[182:185], v[214:217], v[90:93]
	v_mfma_i32_16x16x64_i8 v[82:85], v[190:193], v[214:217], v[82:85]
	v_mfma_i32_16x16x64_i8 v[74:77], v[182:185], v[222:225], v[74:77]
	v_mfma_i32_16x16x64_i8 v[66:69], v[190:193], v[222:225], v[66:69]
	v_mfma_i32_16x16x64_i8 v[122:125], v[186:189], v[202:205], v[122:125]
	v_mfma_i32_16x16x64_i8 v[114:117], v[194:197], v[202:205], v[114:117]
	v_mfma_i32_16x16x64_i8 v[106:109], v[186:189], v[210:213], v[106:109]
	v_mfma_i32_16x16x64_i8 v[98:101], v[194:197], v[210:213], v[98:101]
	v_mfma_i32_16x16x64_i8 v[90:93], v[186:189], v[218:221], v[90:93]
	v_mfma_i32_16x16x64_i8 v[82:85], v[194:197], v[218:221], v[82:85]
	v_mfma_i32_16x16x64_i8 v[74:77], v[186:189], v[226:229], v[74:77]
	v_mfma_i32_16x16x64_i8 v[66:69], v[194:197], v[226:229], v[66:69]
	s_setprio 0
	s_barrier
	s_add_i32 s55, s43, s35
	v_lshl_add_u64 v[162:163], s[28:29], 0, v[134:135]
	s_mov_b32 m0, s55
	ds_read_b128 v[198:201], v179 offset:16384
	ds_read_b128 v[202:205], v179 offset:17408
	ds_read_b128 v[206:209], v179 offset:18432
	ds_read_b128 v[210:213], v179 offset:19456
	ds_read_b128 v[214:217], v179 offset:20480
	ds_read_b128 v[218:221], v179 offset:21504
	ds_read_b128 v[222:225], v179 offset:22528
	ds_read_b128 v[226:229], v179 offset:23552
	global_load_lds_dwordx4 v134, s[28:29]
	s_add_i32 m0, s55, 0x2000
	s_add_u32 s56, s28, 0x40000
	v_lshl_add_u64 v[230:231], s[28:29], 0, v[130:131]
	s_addc_u32 s57, s29, 0
	s_add_i32 s55, s44, s35
	global_load_lds_dwordx4 v130, s[28:29]
	s_mov_b32 m0, s55
	v_lshl_add_u64 v[234:235], s[30:31], 0, v[132:133]
	global_load_lds_dwordx4 v134, s[56:57]
	s_add_i32 m0, s55, 0x2000
	s_nop 0
	global_load_lds_dwordx4 v130, s[56:57]
	v_lshl_add_u64 v[232:233], s[30:31], 0, v[136:137]
	s_mov_b32 m0, s25
	s_nop 0
	global_load_lds_dwordx4 v136, s[30:31]
	s_mov_b32 m0, s37
	s_nop 0
	global_load_lds_dwordx4 v132, s[30:31]
	s_waitcnt vmcnt(8)
	s_waitcnt lgkmcnt(0)
	s_barrier
	s_setprio 1
	v_mfma_i32_16x16x64_i8 v[62:65], v[146:149], v[198:201], v[62:65]
	v_mfma_i32_16x16x64_i8 v[54:57], v[154:157], v[198:201], v[54:57]
	v_mfma_i32_16x16x64_i8 v[46:49], v[146:149], v[206:209], v[46:49]
	v_mfma_i32_16x16x64_i8 v[38:41], v[154:157], v[206:209], v[38:41]
	v_mfma_i32_16x16x64_i8 v[30:33], v[146:149], v[214:217], v[30:33]
	v_mfma_i32_16x16x64_i8 v[22:25], v[154:157], v[214:217], v[22:25]
	v_mfma_i32_16x16x64_i8 v[14:17], v[146:149], v[222:225], v[14:17]
	v_mfma_i32_16x16x64_i8 v[6:9], v[154:157], v[222:225], v[6:9]
	v_mfma_i32_16x16x64_i8 v[62:65], v[150:153], v[202:205], v[62:65]
	v_mfma_i32_16x16x64_i8 v[54:57], v[158:161], v[202:205], v[54:57]
	v_mfma_i32_16x16x64_i8 v[46:49], v[150:153], v[210:213], v[46:49]
	v_mfma_i32_16x16x64_i8 v[38:41], v[158:161], v[210:213], v[38:41]
	v_mfma_i32_16x16x64_i8 v[30:33], v[150:153], v[218:221], v[30:33]
	v_mfma_i32_16x16x64_i8 v[22:25], v[158:161], v[218:221], v[22:25]
	v_mfma_i32_16x16x64_i8 v[14:17], v[150:153], v[226:229], v[14:17]
	v_mfma_i32_16x16x64_i8 v[6:9], v[158:161], v[226:229], v[6:9]
	v_mfma_i32_16x16x64_i8 v[58:61], v[182:185], v[198:201], v[58:61]
	v_mfma_i32_16x16x64_i8 v[50:53], v[190:193], v[198:201], v[50:53]
	v_mfma_i32_16x16x64_i8 v[42:45], v[182:185], v[206:209], v[42:45]
	v_mfma_i32_16x16x64_i8 v[34:37], v[190:193], v[206:209], v[34:37]
	v_mfma_i32_16x16x64_i8 v[26:29], v[182:185], v[214:217], v[26:29]
	v_mfma_i32_16x16x64_i8 v[18:21], v[190:193], v[214:217], v[18:21]
	v_mfma_i32_16x16x64_i8 v[10:13], v[182:185], v[222:225], v[10:13]
	v_mfma_i32_16x16x64_i8 v[2:5], v[190:193], v[222:225], v[2:5]
	v_mfma_i32_16x16x64_i8 v[58:61], v[186:189], v[202:205], v[58:61]
	v_mfma_i32_16x16x64_i8 v[50:53], v[194:197], v[202:205], v[50:53]
	v_mfma_i32_16x16x64_i8 v[42:45], v[186:189], v[210:213], v[42:45]
	v_mfma_i32_16x16x64_i8 v[34:37], v[194:197], v[210:213], v[34:37]
	v_mfma_i32_16x16x64_i8 v[26:29], v[186:189], v[218:221], v[26:29]
	v_mfma_i32_16x16x64_i8 v[18:21], v[194:197], v[218:221], v[18:21]
	v_mfma_i32_16x16x64_i8 v[10:13], v[186:189], v[226:229], v[10:13]
	v_mfma_i32_16x16x64_i8 v[2:5], v[194:197], v[226:229], v[2:5]
	s_setprio 0
	s_barrier
	s_add_i32 s55, 0, 0x18000
	v_add_u32_e32 v158, s55, v168
	ds_read_b128 v[146:149], v158
	ds_read_b128 v[150:153], v158 offset:1024
	ds_read_b128 v[154:157], v158 offset:2048
	ds_read_b128 v[158:161], v158 offset:3072
	ds_read_b128 v[182:185], v180
	ds_read_b128 v[186:189], v180 offset:1024
	ds_read_b128 v[190:193], v180 offset:2048
	ds_read_b128 v[194:197], v180 offset:3072
	s_add_u32 s30, s30, 0x40000
	s_addc_u32 s31, s31, 0
	s_mov_b32 m0, s38
	ds_read_b128 v[198:201], v179 offset:32768
	ds_read_b128 v[202:205], v179 offset:33792
	ds_read_b128 v[206:209], v179 offset:34816
	ds_read_b128 v[210:213], v179 offset:35840
	ds_read_b128 v[214:217], v179 offset:36864
	ds_read_b128 v[218:221], v179 offset:37888
	ds_read_b128 v[222:225], v179 offset:38912
	ds_read_b128 v[226:229], v179 offset:39936
	global_load_lds_dwordx4 v136, s[30:31]
	s_mov_b32 m0, s39
	s_nop 0
	global_load_lds_dwordx4 v132, s[30:31]
	s_waitcnt vmcnt(8)
	s_waitcnt lgkmcnt(0)
	s_barrier
	s_setprio 1
	v_mfma_i32_16x16x64_i8 v[126:129], v[146:149], v[198:201], v[126:129]
	v_mfma_i32_16x16x64_i8 v[118:121], v[154:157], v[198:201], v[118:121]
	v_mfma_i32_16x16x64_i8 v[110:113], v[146:149], v[206:209], v[110:113]
	v_mfma_i32_16x16x64_i8 v[102:105], v[154:157], v[206:209], v[102:105]
	v_mfma_i32_16x16x64_i8 v[94:97], v[146:149], v[214:217], v[94:97]
	v_mfma_i32_16x16x64_i8 v[86:89], v[154:157], v[214:217], v[86:89]
	v_mfma_i32_16x16x64_i8 v[78:81], v[146:149], v[222:225], v[78:81]
	v_mfma_i32_16x16x64_i8 v[70:73], v[154:157], v[222:225], v[70:73]
	v_mfma_i32_16x16x64_i8 v[126:129], v[150:153], v[202:205], v[126:129]
	v_mfma_i32_16x16x64_i8 v[118:121], v[158:161], v[202:205], v[118:121]
	v_mfma_i32_16x16x64_i8 v[110:113], v[150:153], v[210:213], v[110:113]
	v_mfma_i32_16x16x64_i8 v[102:105], v[158:161], v[210:213], v[102:105]
	v_mfma_i32_16x16x64_i8 v[94:97], v[150:153], v[218:221], v[94:97]
	v_mfma_i32_16x16x64_i8 v[86:89], v[158:161], v[218:221], v[86:89]
	v_mfma_i32_16x16x64_i8 v[78:81], v[150:153], v[226:229], v[78:81]
	v_mfma_i32_16x16x64_i8 v[70:73], v[158:161], v[226:229], v[70:73]
	v_mfma_i32_16x16x64_i8 v[122:125], v[182:185], v[198:201], v[122:125]
	v_mfma_i32_16x16x64_i8 v[114:117], v[190:193], v[198:201], v[114:117]
	v_mfma_i32_16x16x64_i8 v[106:109], v[182:185], v[206:209], v[106:109]
	v_mfma_i32_16x16x64_i8 v[98:101], v[190:193], v[206:209], v[98:101]
	v_mfma_i32_16x16x64_i8 v[90:93], v[182:185], v[214:217], v[90:93]
	v_mfma_i32_16x16x64_i8 v[82:85], v[190:193], v[214:217], v[82:85]
	v_mfma_i32_16x16x64_i8 v[74:77], v[182:185], v[222:225], v[74:77]
	v_mfma_i32_16x16x64_i8 v[66:69], v[190:193], v[222:225], v[66:69]
	v_mfma_i32_16x16x64_i8 v[122:125], v[186:189], v[202:205], v[122:125]
	v_mfma_i32_16x16x64_i8 v[114:117], v[194:197], v[202:205], v[114:117]
	v_mfma_i32_16x16x64_i8 v[106:109], v[186:189], v[210:213], v[106:109]
	v_mfma_i32_16x16x64_i8 v[98:101], v[194:197], v[210:213], v[98:101]
	v_mfma_i32_16x16x64_i8 v[90:93], v[186:189], v[218:221], v[90:93]
	v_mfma_i32_16x16x64_i8 v[82:85], v[194:197], v[218:221], v[82:85]
	v_mfma_i32_16x16x64_i8 v[74:77], v[186:189], v[226:229], v[74:77]
	v_mfma_i32_16x16x64_i8 v[66:69], v[194:197], v[226:229], v[66:69]
	s_setprio 0
	s_barrier
	s_add_i32 s30, s55, s35
	v_lshl_add_u64 v[162:163], v[162:163], 0, s[8:9]
	s_mov_b32 m0, s30
	ds_read_b128 v[198:201], v179 offset:49152
	ds_read_b128 v[202:205], v179 offset:50176
	ds_read_b128 v[206:209], v179 offset:51200
	ds_read_b128 v[210:213], v179 offset:52224
	ds_read_b128 v[214:217], v179 offset:53248
	ds_read_b128 v[218:221], v179 offset:54272
	ds_read_b128 v[222:225], v179 offset:55296
	ds_read_b128 v[226:229], v179 offset:56320
	global_load_lds_dwordx4 v[162:163], off
	s_add_i32 m0, s30, 0x2000
	s_add_u32 s28, s28, 0x40080
	v_lshl_add_u64 v[162:163], v[230:231], 0, s[8:9]
	s_addc_u32 s29, s29, 0
	s_add_i32 s30, s45, s35
	global_load_lds_dwordx4 v[162:163], off
	s_mov_b32 m0, s30
	s_nop 0
	global_load_lds_dwordx4 v134, s[28:29]
	s_add_i32 m0, s30, 0x2000
	s_nop 0
	global_load_lds_dwordx4 v130, s[28:29]
	v_lshl_add_u64 v[162:163], v[232:233], 0, s[8:9]
	s_mov_b32 m0, s40
	s_nop 0
	global_load_lds_dwordx4 v[162:163], off
	v_lshl_add_u64 v[162:163], v[234:235], 0, s[8:9]
	s_mov_b32 m0, s41
	s_nop 0
	global_load_lds_dwordx4 v[162:163], off
	s_waitcnt vmcnt(8)
	s_waitcnt lgkmcnt(0)
	s_barrier
	s_setprio 1
	v_mfma_i32_16x16x64_i8 v[62:65], v[146:149], v[198:201], v[62:65]
	v_mfma_i32_16x16x64_i8 v[54:57], v[154:157], v[198:201], v[54:57]
	v_mfma_i32_16x16x64_i8 v[46:49], v[146:149], v[206:209], v[46:49]
	v_mfma_i32_16x16x64_i8 v[38:41], v[154:157], v[206:209], v[38:41]
	v_mfma_i32_16x16x64_i8 v[30:33], v[146:149], v[214:217], v[30:33]
	v_mfma_i32_16x16x64_i8 v[22:25], v[154:157], v[214:217], v[22:25]
	v_mfma_i32_16x16x64_i8 v[14:17], v[146:149], v[222:225], v[14:17]
	v_mfma_i32_16x16x64_i8 v[6:9], v[154:157], v[222:225], v[6:9]
	v_mfma_i32_16x16x64_i8 v[62:65], v[150:153], v[202:205], v[62:65]
	v_mfma_i32_16x16x64_i8 v[54:57], v[158:161], v[202:205], v[54:57]
	v_mfma_i32_16x16x64_i8 v[46:49], v[150:153], v[210:213], v[46:49]
	v_mfma_i32_16x16x64_i8 v[38:41], v[158:161], v[210:213], v[38:41]
	v_mfma_i32_16x16x64_i8 v[30:33], v[150:153], v[218:221], v[30:33]
	v_mfma_i32_16x16x64_i8 v[22:25], v[158:161], v[218:221], v[22:25]
	v_mfma_i32_16x16x64_i8 v[14:17], v[150:153], v[226:229], v[14:17]
	v_mfma_i32_16x16x64_i8 v[6:9], v[158:161], v[226:229], v[6:9]
	v_mfma_i32_16x16x64_i8 v[58:61], v[182:185], v[198:201], v[58:61]
	v_mfma_i32_16x16x64_i8 v[50:53], v[190:193], v[198:201], v[50:53]
	v_mfma_i32_16x16x64_i8 v[42:45], v[182:185], v[206:209], v[42:45]
	v_mfma_i32_16x16x64_i8 v[34:37], v[190:193], v[206:209], v[34:37]
	v_mfma_i32_16x16x64_i8 v[26:29], v[182:185], v[214:217], v[26:29]
	v_mfma_i32_16x16x64_i8 v[18:21], v[190:193], v[214:217], v[18:21]
	v_mfma_i32_16x16x64_i8 v[10:13], v[182:185], v[222:225], v[10:13]
	v_mfma_i32_16x16x64_i8 v[2:5], v[190:193], v[222:225], v[2:5]
	v_mfma_i32_16x16x64_i8 v[58:61], v[186:189], v[202:205], v[58:61]
	v_mfma_i32_16x16x64_i8 v[50:53], v[194:197], v[202:205], v[50:53]
	v_mfma_i32_16x16x64_i8 v[42:45], v[186:189], v[210:213], v[42:45]
	v_mfma_i32_16x16x64_i8 v[34:37], v[194:197], v[210:213], v[34:37]
	v_mfma_i32_16x16x64_i8 v[26:29], v[186:189], v[218:221], v[26:29]
	v_mfma_i32_16x16x64_i8 v[18:21], v[194:197], v[218:221], v[18:21]
	v_mfma_i32_16x16x64_i8 v[10:13], v[186:189], v[226:229], v[10:13]
	v_mfma_i32_16x16x64_i8 v[2:5], v[194:197], v[226:229], v[2:5]
	s_setprio 0
	s_barrier
	s_add_i32 s54, s54, 2
	s_add_u32 s26, s26, 0x100
	s_addc_u32 s27, s27, 0
	s_add_u32 s52, s52, 0x100
	s_addc_u32 s53, s53, 0
	s_cmp_gt_u32 s54, 13
	s_cbranch_scc0 .LBB0_3387
	s_and_b64 vcc, exec, s[12:13]
	s_cbranch_vccz .LBB0_3390
	s_barrier

.LBB0_3496:
	ds_read_b128 v[154:157], v149
	ds_read_b128 v[158:161], v149 offset:1024
	ds_read_b128 v[162:165], v149 offset:2048
	ds_read_b128 v[168:171], v149 offset:3072
	ds_read_b128 v[172:175], v150
	ds_read_b128 v[176:179], v150 offset:1024
	ds_read_b128 v[180:183], v150 offset:2048
	ds_read_b128 v[184:187], v150 offset:3072
	s_add_u32 s26, s24, 0xffea0080
	s_addc_u32 s27, s25, -1
	s_cmpk_eq_i32 s55, 0x54
	s_cselect_b32 s29, s5, s27
	s_cselect_b32 s28, s4, s26
	s_cselect_b32 s27, s23, s54
	s_cselect_b32 s26, s22, s53
	s_add_i32 m0, s31, 0xc000
	ds_read_b128 v[188:191], v151
	ds_read_b128 v[192:195], v151 offset:1024
	ds_read_b128 v[196:199], v151 offset:2048
	ds_read_b128 v[200:203], v151 offset:3072
	ds_read_b128 v[204:207], v151 offset:4096
	ds_read_b128 v[208:211], v151 offset:5120
	ds_read_b128 v[212:215], v151 offset:6144
	ds_read_b128 v[216:219], v151 offset:7168
	global_load_lds_dwordx4 v138, s[24:25]
	s_add_i32 m0, s31, 0xe000
	s_nop 0
	global_load_lds_dwordx4 v140, s[24:25]
	s_waitcnt vmcnt(8)
	s_waitcnt lgkmcnt(0)
	s_barrier
	s_setprio 1
	v_mfma_f32_16x16x32_bf16 v[126:129], v[154:157], v[188:191], v[126:129]
	v_mfma_f32_16x16x32_bf16 v[122:125], v[162:165], v[188:191], v[122:125]
	v_mfma_f32_16x16x32_bf16 v[118:121], v[154:157], v[196:199], v[118:121]
	v_mfma_f32_16x16x32_bf16 v[110:113], v[162:165], v[196:199], v[110:113]
	v_mfma_f32_16x16x32_bf16 v[102:105], v[154:157], v[204:207], v[102:105]
	v_mfma_f32_16x16x32_bf16 v[94:97], v[162:165], v[204:207], v[94:97]
	v_mfma_f32_16x16x32_bf16 v[86:89], v[154:157], v[212:215], v[86:89]
	v_mfma_f32_16x16x32_bf16 v[78:81], v[162:165], v[212:215], v[78:81]
	v_mfma_f32_16x16x32_bf16 v[126:129], v[158:161], v[192:195], v[126:129]
	v_mfma_f32_16x16x32_bf16 v[122:125], v[168:171], v[192:195], v[122:125]
	v_mfma_f32_16x16x32_bf16 v[118:121], v[158:161], v[200:203], v[118:121]
	v_mfma_f32_16x16x32_bf16 v[110:113], v[168:171], v[200:203], v[110:113]
	v_mfma_f32_16x16x32_bf16 v[102:105], v[158:161], v[208:211], v[102:105]
	v_mfma_f32_16x16x32_bf16 v[94:97], v[168:171], v[208:211], v[94:97]
	v_mfma_f32_16x16x32_bf16 v[86:89], v[158:161], v[216:219], v[86:89]
	v_mfma_f32_16x16x32_bf16 v[78:81], v[168:171], v[216:219], v[78:81]
	v_mfma_f32_16x16x32_bf16 v[114:117], v[172:175], v[188:191], v[114:117]
	v_mfma_f32_16x16x32_bf16 v[106:109], v[180:183], v[188:191], v[106:109]
	v_mfma_f32_16x16x32_bf16 v[98:101], v[172:175], v[196:199], v[98:101]
	v_mfma_f32_16x16x32_bf16 v[90:93], v[180:183], v[196:199], v[90:93]
	v_mfma_f32_16x16x32_bf16 v[82:85], v[172:175], v[204:207], v[82:85]
	v_mfma_f32_16x16x32_bf16 v[74:77], v[180:183], v[204:207], v[74:77]
	v_mfma_f32_16x16x32_bf16 v[70:73], v[172:175], v[212:215], v[70:73]
	v_mfma_f32_16x16x32_bf16 v[66:69], v[180:183], v[212:215], v[66:69]
	v_mfma_f32_16x16x32_bf16 v[114:117], v[176:179], v[192:195], v[114:117]
	v_mfma_f32_16x16x32_bf16 v[106:109], v[184:187], v[192:195], v[106:109]
	v_mfma_f32_16x16x32_bf16 v[98:101], v[176:179], v[200:203], v[98:101]
	v_mfma_f32_16x16x32_bf16 v[90:93], v[184:187], v[200:203], v[90:93]
	v_mfma_f32_16x16x32_bf16 v[82:85], v[176:179], v[208:211], v[82:85]
	v_mfma_f32_16x16x32_bf16 v[74:77], v[184:187], v[208:211], v[74:77]
	v_mfma_f32_16x16x32_bf16 v[70:73], v[176:179], v[216:219], v[70:73]
	v_mfma_f32_16x16x32_bf16 v[66:69], v[184:187], v[216:219], v[66:69]
	s_setprio 0
	s_barrier
	s_add_i32 s56, s41, s30
	v_lshl_add_u64 v[146:147], s[26:27], 0, v[132:133]
	s_mov_b32 m0, s56
	ds_read_b128 v[188:191], v151 offset:16384
	ds_read_b128 v[192:195], v151 offset:17408
	ds_read_b128 v[196:199], v151 offset:18432
	ds_read_b128 v[200:203], v151 offset:19456
	ds_read_b128 v[204:207], v151 offset:20480
	ds_read_b128 v[208:211], v151 offset:21504
	ds_read_b128 v[212:215], v151 offset:22528
	ds_read_b128 v[216:219], v151 offset:23552
	global_load_lds_dwordx4 v132, s[26:27]
	s_add_i32 m0, s56, 0x2000
	s_add_u32 s56, s26, 0x160000
	v_lshl_add_u64 v[220:221], s[26:27], 0, v[136:137]
	s_addc_u32 s57, s27, 0
	s_add_i32 s63, s42, s30
	global_load_lds_dwordx4 v136, s[26:27]
	s_mov_b32 m0, s63
	v_lshl_add_u64 v[224:225], s[28:29], 0, v[134:135]
	global_load_lds_dwordx4 v132, s[56:57]
	s_add_i32 m0, s63, 0x2000
	s_nop 0
	global_load_lds_dwordx4 v136, s[56:57]
	v_lshl_add_u64 v[222:223], s[28:29], 0, v[130:131]
	s_mov_b32 m0, s31
	s_nop 0
	global_load_lds_dwordx4 v130, s[28:29]
	s_mov_b32 m0, s34
	s_nop 0
	global_load_lds_dwordx4 v134, s[28:29]
	s_waitcnt vmcnt(8)
	s_waitcnt lgkmcnt(0)
	s_barrier
	s_setprio 1
	v_mfma_f32_16x16x32_bf16 v[62:65], v[154:157], v[188:191], v[62:65]
	v_mfma_f32_16x16x32_bf16 v[58:61], v[162:165], v[188:191], v[58:61]
	v_mfma_f32_16x16x32_bf16 v[54:57], v[154:157], v[196:199], v[54:57]
	v_mfma_f32_16x16x32_bf16 v[46:49], v[162:165], v[196:199], v[46:49]
	v_mfma_f32_16x16x32_bf16 v[38:41], v[154:157], v[204:207], v[38:41]
	v_mfma_f32_16x16x32_bf16 v[30:33], v[162:165], v[204:207], v[30:33]
	v_mfma_f32_16x16x32_bf16 v[22:25], v[154:157], v[212:215], v[22:25]
	v_mfma_f32_16x16x32_bf16 v[14:17], v[162:165], v[212:215], v[14:17]
	v_mfma_f32_16x16x32_bf16 v[62:65], v[158:161], v[192:195], v[62:65]
	v_mfma_f32_16x16x32_bf16 v[58:61], v[168:171], v[192:195], v[58:61]
	v_mfma_f32_16x16x32_bf16 v[54:57], v[158:161], v[200:203], v[54:57]
	v_mfma_f32_16x16x32_bf16 v[46:49], v[168:171], v[200:203], v[46:49]
	v_mfma_f32_16x16x32_bf16 v[38:41], v[158:161], v[208:211], v[38:41]
	v_mfma_f32_16x16x32_bf16 v[30:33], v[168:171], v[208:211], v[30:33]
	v_mfma_f32_16x16x32_bf16 v[22:25], v[158:161], v[216:219], v[22:25]
	v_mfma_f32_16x16x32_bf16 v[14:17], v[168:171], v[216:219], v[14:17]
	v_mfma_f32_16x16x32_bf16 v[50:53], v[172:175], v[188:191], v[50:53]
	v_mfma_f32_16x16x32_bf16 v[42:45], v[180:183], v[188:191], v[42:45]
	v_mfma_f32_16x16x32_bf16 v[34:37], v[172:175], v[196:199], v[34:37]
	v_mfma_f32_16x16x32_bf16 v[26:29], v[180:183], v[196:199], v[26:29]
	v_mfma_f32_16x16x32_bf16 v[18:21], v[172:175], v[204:207], v[18:21]
	v_mfma_f32_16x16x32_bf16 v[10:13], v[180:183], v[204:207], v[10:13]
	v_mfma_f32_16x16x32_bf16 v[6:9], v[172:175], v[212:215], v[6:9]
	v_mfma_f32_16x16x32_bf16 v[2:5], v[180:183], v[212:215], v[2:5]
	v_mfma_f32_16x16x32_bf16 v[50:53], v[176:179], v[192:195], v[50:53]
	v_mfma_f32_16x16x32_bf16 v[42:45], v[184:187], v[192:195], v[42:45]
	v_mfma_f32_16x16x32_bf16 v[34:37], v[176:179], v[200:203], v[34:37]
	v_mfma_f32_16x16x32_bf16 v[26:29], v[184:187], v[200:203], v[26:29]
	v_mfma_f32_16x16x32_bf16 v[18:21], v[176:179], v[208:211], v[18:21]
	v_mfma_f32_16x16x32_bf16 v[10:13], v[184:187], v[208:211], v[10:13]
	v_mfma_f32_16x16x32_bf16 v[6:9], v[176:179], v[216:219], v[6:9]
	v_mfma_f32_16x16x32_bf16 v[2:5], v[184:187], v[216:219], v[2:5]
	s_setprio 0
	s_barrier
	ds_read_b128 v[154:157], v152
	ds_read_b128 v[158:161], v152 offset:1024
	ds_read_b128 v[162:165], v152 offset:2048
	ds_read_b128 v[168:171], v152 offset:3072
	ds_read_b128 v[172:175], v153
	ds_read_b128 v[176:179], v153 offset:1024
	ds_read_b128 v[180:183], v153 offset:2048
	ds_read_b128 v[184:187], v153 offset:3072
	s_add_u32 s28, s28, 0x160000
	s_addc_u32 s29, s29, 0
	s_mov_b32 m0, s35
	ds_read_b128 v[188:191], v151 offset:32768
	ds_read_b128 v[192:195], v151 offset:33792
	ds_read_b128 v[196:199], v151 offset:34816
	ds_read_b128 v[200:203], v151 offset:35840
	ds_read_b128 v[204:207], v151 offset:36864
	ds_read_b128 v[208:211], v151 offset:37888
	ds_read_b128 v[212:215], v151 offset:38912
	ds_read_b128 v[216:219], v151 offset:39936
	global_load_lds_dwordx4 v130, s[28:29]
	s_mov_b32 m0, s36
	s_nop 0
	global_load_lds_dwordx4 v134, s[28:29]
	s_waitcnt vmcnt(8)
	s_waitcnt lgkmcnt(0)
	s_barrier
	s_setprio 1
	v_mfma_f32_16x16x32_bf16 v[126:129], v[154:157], v[188:191], v[126:129]
	v_mfma_f32_16x16x32_bf16 v[122:125], v[162:165], v[188:191], v[122:125]
	v_mfma_f32_16x16x32_bf16 v[118:121], v[154:157], v[196:199], v[118:121]
	v_mfma_f32_16x16x32_bf16 v[110:113], v[162:165], v[196:199], v[110:113]
	v_mfma_f32_16x16x32_bf16 v[102:105], v[154:157], v[204:207], v[102:105]
	v_mfma_f32_16x16x32_bf16 v[94:97], v[162:165], v[204:207], v[94:97]
	v_mfma_f32_16x16x32_bf16 v[86:89], v[154:157], v[212:215], v[86:89]
	v_mfma_f32_16x16x32_bf16 v[78:81], v[162:165], v[212:215], v[78:81]
	v_mfma_f32_16x16x32_bf16 v[126:129], v[158:161], v[192:195], v[126:129]
	v_mfma_f32_16x16x32_bf16 v[122:125], v[168:171], v[192:195], v[122:125]
	v_mfma_f32_16x16x32_bf16 v[118:121], v[158:161], v[200:203], v[118:121]
	v_mfma_f32_16x16x32_bf16 v[110:113], v[168:171], v[200:203], v[110:113]
	v_mfma_f32_16x16x32_bf16 v[102:105], v[158:161], v[208:211], v[102:105]
	v_mfma_f32_16x16x32_bf16 v[94:97], v[168:171], v[208:211], v[94:97]
	v_mfma_f32_16x16x32_bf16 v[86:89], v[158:161], v[216:219], v[86:89]
	v_mfma_f32_16x16x32_bf16 v[78:81], v[168:171], v[216:219], v[78:81]
	v_mfma_f32_16x16x32_bf16 v[114:117], v[172:175], v[188:191], v[114:117]
	v_mfma_f32_16x16x32_bf16 v[106:109], v[180:183], v[188:191], v[106:109]
	v_mfma_f32_16x16x32_bf16 v[98:101], v[172:175], v[196:199], v[98:101]
	v_mfma_f32_16x16x32_bf16 v[90:93], v[180:183], v[196:199], v[90:93]
	v_mfma_f32_16x16x32_bf16 v[82:85], v[172:175], v[204:207], v[82:85]
	v_mfma_f32_16x16x32_bf16 v[74:77], v[180:183], v[204:207], v[74:77]
	v_mfma_f32_16x16x32_bf16 v[70:73], v[172:175], v[212:215], v[70:73]
	v_mfma_f32_16x16x32_bf16 v[66:69], v[180:183], v[212:215], v[66:69]
	v_mfma_f32_16x16x32_bf16 v[114:117], v[176:179], v[192:195], v[114:117]
	v_mfma_f32_16x16x32_bf16 v[106:109], v[184:187], v[192:195], v[106:109]
	v_mfma_f32_16x16x32_bf16 v[98:101], v[176:179], v[200:203], v[98:101]
	v_mfma_f32_16x16x32_bf16 v[90:93], v[184:187], v[200:203], v[90:93]
	v_mfma_f32_16x16x32_bf16 v[82:85], v[176:179], v[208:211], v[82:85]
	v_mfma_f32_16x16x32_bf16 v[74:77], v[184:187], v[208:211], v[74:77]
	v_mfma_f32_16x16x32_bf16 v[70:73], v[176:179], v[216:219], v[70:73]
	v_mfma_f32_16x16x32_bf16 v[66:69], v[184:187], v[216:219], v[66:69]
	s_setprio 0
	s_barrier
	s_add_i32 s28, s43, s30
	v_lshl_add_u64 v[146:147], v[146:147], 0, s[6:7]
	s_mov_b32 m0, s28
	ds_read_b128 v[188:191], v151 offset:49152
	ds_read_b128 v[192:195], v151 offset:50176
	ds_read_b128 v[196:199], v151 offset:51200
	ds_read_b128 v[200:203], v151 offset:52224
	ds_read_b128 v[204:207], v151 offset:53248
	ds_read_b128 v[208:211], v151 offset:54272
	ds_read_b128 v[212:215], v151 offset:55296
	ds_read_b128 v[216:219], v151 offset:56320
	global_load_lds_dwordx4 v[146:147], off
	s_add_i32 m0, s28, 0x2000
	s_add_u32 s26, s26, 0x160080
	v_lshl_add_u64 v[146:147], v[220:221], 0, s[6:7]
	s_addc_u32 s27, s27, 0
	s_add_i32 s28, s44, s30
	global_load_lds_dwordx4 v[146:147], off
	s_mov_b32 m0, s28
	s_nop 0
	global_load_lds_dwordx4 v132, s[26:27]
	s_add_i32 m0, s28, 0x2000
	s_nop 0
	global_load_lds_dwordx4 v136, s[26:27]
	v_lshl_add_u64 v[146:147], v[222:223], 0, s[6:7]
	s_mov_b32 m0, s37
	s_nop 0
	global_load_lds_dwordx4 v[146:147], off
	v_lshl_add_u64 v[146:147], v[224:225], 0, s[6:7]
	s_mov_b32 m0, s38
	s_nop 0
	global_load_lds_dwordx4 v[146:147], off
	s_waitcnt vmcnt(8)
	s_waitcnt lgkmcnt(0)
	s_barrier
	s_setprio 1
	v_mfma_f32_16x16x32_bf16 v[62:65], v[154:157], v[188:191], v[62:65]
	v_mfma_f32_16x16x32_bf16 v[58:61], v[162:165], v[188:191], v[58:61]
	v_mfma_f32_16x16x32_bf16 v[54:57], v[154:157], v[196:199], v[54:57]
	v_mfma_f32_16x16x32_bf16 v[46:49], v[162:165], v[196:199], v[46:49]
	v_mfma_f32_16x16x32_bf16 v[38:41], v[154:157], v[204:207], v[38:41]
	v_mfma_f32_16x16x32_bf16 v[30:33], v[162:165], v[204:207], v[30:33]
	v_mfma_f32_16x16x32_bf16 v[22:25], v[154:157], v[212:215], v[22:25]
	v_mfma_f32_16x16x32_bf16 v[14:17], v[162:165], v[212:215], v[14:17]
	v_mfma_f32_16x16x32_bf16 v[62:65], v[158:161], v[192:195], v[62:65]
	v_mfma_f32_16x16x32_bf16 v[58:61], v[168:171], v[192:195], v[58:61]
	v_mfma_f32_16x16x32_bf16 v[54:57], v[158:161], v[200:203], v[54:57]
	v_mfma_f32_16x16x32_bf16 v[46:49], v[168:171], v[200:203], v[46:49]
	v_mfma_f32_16x16x32_bf16 v[38:41], v[158:161], v[208:211], v[38:41]
	v_mfma_f32_16x16x32_bf16 v[30:33], v[168:171], v[208:211], v[30:33]
	v_mfma_f32_16x16x32_bf16 v[22:25], v[158:161], v[216:219], v[22:25]
	v_mfma_f32_16x16x32_bf16 v[14:17], v[168:171], v[216:219], v[14:17]
	v_mfma_f32_16x16x32_bf16 v[50:53], v[172:175], v[188:191], v[50:53]
	v_mfma_f32_16x16x32_bf16 v[42:45], v[180:183], v[188:191], v[42:45]
	v_mfma_f32_16x16x32_bf16 v[34:37], v[172:175], v[196:199], v[34:37]
	v_mfma_f32_16x16x32_bf16 v[26:29], v[180:183], v[196:199], v[26:29]
	v_mfma_f32_16x16x32_bf16 v[18:21], v[172:175], v[204:207], v[18:21]
	v_mfma_f32_16x16x32_bf16 v[10:13], v[180:183], v[204:207], v[10:13]
	v_mfma_f32_16x16x32_bf16 v[6:9], v[172:175], v[212:215], v[6:9]
	v_mfma_f32_16x16x32_bf16 v[2:5], v[180:183], v[212:215], v[2:5]
	v_mfma_f32_16x16x32_bf16 v[50:53], v[176:179], v[192:195], v[50:53]
	v_mfma_f32_16x16x32_bf16 v[42:45], v[184:187], v[192:195], v[42:45]
	v_mfma_f32_16x16x32_bf16 v[34:37], v[176:179], v[200:203], v[34:37]
	v_mfma_f32_16x16x32_bf16 v[26:29], v[184:187], v[200:203], v[26:29]
	v_mfma_f32_16x16x32_bf16 v[18:21], v[176:179], v[208:211], v[18:21]
	v_mfma_f32_16x16x32_bf16 v[10:13], v[184:187], v[208:211], v[10:13]
	v_mfma_f32_16x16x32_bf16 v[6:9], v[176:179], v[216:219], v[6:9]
	v_mfma_f32_16x16x32_bf16 v[2:5], v[184:187], v[216:219], v[2:5]
	s_setprio 0
	s_barrier
	s_add_i32 s55, s55, 2
	s_add_u32 s24, s24, 0x100
	s_addc_u32 s25, s25, 0
	s_add_u32 s53, s53, 0x100
	s_addc_u32 s54, s54, 0
	s_cmpk_gt_u32 s55, 0x55
	s_cbranch_scc0 .LBB0_3496
	s_and_b64 vcc, exec, s[12:13]
	s_cbranch_vccz .LBB0_3499
	s_barrier
